# phase 6 rewritten by hand: B-shared dual-tile mainloops (both tiles of a block share the weight tile) + own epilogues (same arithmetic), stash for tile 1 in R3
# speedup vs baseline: 1.1090x; 1.0143x over previous
.Lp6_visit:
	s_cmp_lg_u64 s[20:21], 0
	s_cbranch_scc1 .Lp6_lin
	s_lshr_b32 s71, s81, 6
	s_and_b32 s72, s81, 63
	s_lshr_b32 s74, s72, 3
	s_and_b32 s72, s72, 7
	s_lshl_b32 s70, s71, 3
	s_add_u32 s70, s70, s79
	s_add_u32 s70, s70, s72
	s_branch .Lp6_dec
.Lp6_lin:
	s_and_b32 s70, s81, 0x7f
	s_lshr_b32 s74, s81, 7
.Lp6_dec:
	s_load_dwordx2 s[22:23], s[0:1], 0x60
	s_load_dwordx2 s[24:25], s[0:1], 0xe0
	s_load_dwordx2 s[26:27], s[0:1], 0xd8
	s_mov_b32 s3, 0x7fff
	v_mov_b32_e32 v242, 1
	v_lshlrev_b32_e32 v243, 4, v168
	v_bfe_u32 v249, v168, 6, 1
	v_bfe_u32 v250, v168, 4, 2
	v_lshlrev_b32_e32 v250, 4, v250
	v_lshl_or_b32 v244, v249, 8, v250
	s_lshl_b32 s71, s74, 9
	s_lshl_b32 s72, s2, 16
	s_waitcnt lgkmcnt(0)
	s_add_u32 s22, s22, s71
	s_addc_u32 s23, s23, 0
	s_add_u32 s24, s24, s72
	s_addc_u32 s25, s25, 0
	v_and_b32_e32 v236, 15, v168
	v_lshrrev_b32_e32 v237, 1, v236
	v_bfe_u32 v238, v168, 4, 2
	v_xor_b32_e32 v237, v237, v238
	v_lshlrev_b32_e32 v237, 4, v237
	v_lshl_or_b32 v236, v236, 7, v237
	v_xor_b32_e32 v237, 64, v236
	v_add_u32_e32 v236, 16, v236
	v_add_u32_e32 v237, 16, v237
	v_bfe_u32 v238, v168, 7, 1
	v_lshl_add_u32 v240, v238, 13, v237
	v_lshl_add_u32 v238, v238, 13, v236
	v_bfe_u32 v239, v168, 6, 1
	v_lshl_add_u32 v241, v239, 13, v237
	v_lshl_add_u32 v239, v239, 13, v236
	v_lshrrev_b32_e32 v236, 3, v168
	v_lshrrev_b32_e32 v237, 4, v168
	v_xor_b32_e32 v237, v237, v168
	v_and_b32_e32 v237, 7, v237
	v_lshlrev_b32_e32 v237, 4, v237
	v_lshl_or_b32 v232, v236, 11, v237
	v_add_u32_e32 v233, 0x10000, v232
	v_add_u32_e32 v234, 0x20000, v232
	v_add_u32_e32 v235, 0x30000, v232
	s_load_dwordx2 s[90:91], s[0:1], 0xa0
	s_load_dwordx2 s[92:93], s[0:1], 0xa8
	v_lshrrev_b32_e32 v237, 6, v168
	s_nop 1
	v_readfirstlane_b32 s97, v237
	s_nop 3
	s_lshl_b32 s96, s97, 10
	s_add_u32 s96, s96, 16
	s_add_u32 s94, s81, s80
	s_cmp_lt_i32 s94, s82
	s_cselect_b32 s95, 1, 0
	s_cmp_lg_u64 s[20:21], 0
	s_cselect_b32 s95, 0, s95
	s_cmp_ge_u32 s94, 0x40
	s_cselect_b32 s97, 1, 0
	s_mul_i32 s100, s97, 0x40
	s_sub_u32 s100, s94, s100
	s_lshr_b32 s101, s100, 3
	s_and_b32 s100, s100, 7
	s_lshl_b32 s97, s97, 3
	s_add_u32 s100, s100, s97
	s_add_u32 s100, s100, s79
	s_cmp_lg_u32 s101, s74
	s_cselect_b32 s95, 0, s95
	s_cmp_eq_u32 s95, 1
	s_cselect_b32 s101, s100, s70
	s_mov_b32 s97, s101
	s_waitcnt lgkmcnt(0)
	s_lshl_b32 s94, s74, 18
	s_add_u32 s94, s94, 0xc40000
	s_add_u32 s98, s92, s94
	s_addc_u32 s99, s93, 0
	s_lshl_b32 s101, s101, 18
	s_add_u32 s92, s90, s101
	s_addc_u32 s93, s91, 0
	s_lshl_b32 s94, s70, 18
	s_add_u32 s90, s90, s94
	s_addc_u32 s91, s91, 0
	s_waitcnt vmcnt(0)
	s_barrier
	s_add_u32 m0, s96, 0x0
	s_nop 0
	global_load_lds_dwordx4 v232, s[90:91]
	s_add_u32 m0, s96, 0x1000
	s_nop 0
	global_load_lds_dwordx4 v233, s[90:91]
	s_add_u32 m0, s96, 0x2000
	s_nop 0
	global_load_lds_dwordx4 v234, s[90:91]
	s_add_u32 m0, s96, 0x3000
	s_nop 0
	global_load_lds_dwordx4 v235, s[90:91]
	s_add_u32 m0, s96, 0x4000
	s_nop 0
	global_load_lds_dwordx4 v232, s[92:93]
	s_add_u32 m0, s96, 0x5000
	s_nop 0
	global_load_lds_dwordx4 v233, s[92:93]
	s_add_u32 m0, s96, 0x6000
	s_nop 0
	global_load_lds_dwordx4 v234, s[92:93]
	s_add_u32 m0, s96, 0x7000
	s_nop 0
	global_load_lds_dwordx4 v235, s[92:93]
	s_add_u32 m0, s96, 0x8000
	s_nop 0
	global_load_lds_dwordx4 v232, s[98:99]
	s_add_u32 m0, s96, 0x9000
	s_nop 0
	global_load_lds_dwordx4 v233, s[98:99]
	s_add_u32 m0, s96, 0xa000
	s_nop 0
	global_load_lds_dwordx4 v234, s[98:99]
	s_add_u32 m0, s96, 0xb000
	s_nop 0
	global_load_lds_dwordx4 v235, s[98:99]
	s_add_u32 s90, s90, 0x80
	s_addc_u32 s91, s91, 0
	s_add_u32 s92, s92, 0x80
	s_addc_u32 s93, s93, 0
	s_add_u32 s98, s98, 0x80
	s_addc_u32 s99, s99, 0
	v_mov_b32_e32 v0, 0
	v_mov_b32_e32 v1, v0
	v_mov_b32_e32 v2, v0
	v_mov_b32_e32 v3, v0
	v_mov_b32_e32 v4, v0
	v_mov_b32_e32 v5, v0
	v_mov_b32_e32 v6, v0
	v_mov_b32_e32 v7, v0
	v_mov_b32_e32 v8, v0
	v_mov_b32_e32 v9, v0
	v_mov_b32_e32 v10, v0
	v_mov_b32_e32 v11, v0
	v_mov_b32_e32 v12, v0
	v_mov_b32_e32 v13, v0
	v_mov_b32_e32 v14, v0
	v_mov_b32_e32 v15, v0
	v_mov_b32_e32 v16, v0
	v_mov_b32_e32 v17, v0
	v_mov_b32_e32 v18, v0
	v_mov_b32_e32 v19, v0
	v_mov_b32_e32 v20, v0
	v_mov_b32_e32 v21, v0
	v_mov_b32_e32 v22, v0
	v_mov_b32_e32 v23, v0
	v_mov_b32_e32 v24, v0
	v_mov_b32_e32 v25, v0
	v_mov_b32_e32 v26, v0
	v_mov_b32_e32 v27, v0
	v_mov_b32_e32 v28, v0
	v_mov_b32_e32 v29, v0
	v_mov_b32_e32 v30, v0
	v_mov_b32_e32 v31, v0
	v_mov_b32_e32 v32, v0
	v_mov_b32_e32 v33, v0
	v_mov_b32_e32 v34, v0
	v_mov_b32_e32 v35, v0
	v_mov_b32_e32 v36, v0
	v_mov_b32_e32 v37, v0
	v_mov_b32_e32 v38, v0
	v_mov_b32_e32 v39, v0
	v_mov_b32_e32 v40, v0
	v_mov_b32_e32 v41, v0
	v_mov_b32_e32 v42, v0
	v_mov_b32_e32 v43, v0
	v_mov_b32_e32 v44, v0
	v_mov_b32_e32 v45, v0
	v_mov_b32_e32 v46, v0
	v_mov_b32_e32 v47, v0
	v_mov_b32_e32 v48, v0
	v_mov_b32_e32 v49, v0
	v_mov_b32_e32 v50, v0
	v_mov_b32_e32 v51, v0
	v_mov_b32_e32 v52, v0
	v_mov_b32_e32 v53, v0
	v_mov_b32_e32 v54, v0
	v_mov_b32_e32 v55, v0
	v_mov_b32_e32 v56, v0
	v_mov_b32_e32 v57, v0
	v_mov_b32_e32 v58, v0
	v_mov_b32_e32 v59, v0
	v_mov_b32_e32 v60, v0
	v_mov_b32_e32 v61, v0
	v_mov_b32_e32 v62, v0
	v_mov_b32_e32 v63, v0
	v_mov_b32_e32 v64, v0
	v_mov_b32_e32 v65, v0
	v_mov_b32_e32 v66, v0
	v_mov_b32_e32 v67, v0
	v_mov_b32_e32 v68, v0
	v_mov_b32_e32 v69, v0
	v_mov_b32_e32 v70, v0
	v_mov_b32_e32 v71, v0
	v_mov_b32_e32 v72, v0
	v_mov_b32_e32 v73, v0
	v_mov_b32_e32 v74, v0
	v_mov_b32_e32 v75, v0
	v_mov_b32_e32 v76, v0
	v_mov_b32_e32 v77, v0
	v_mov_b32_e32 v78, v0
	v_mov_b32_e32 v79, v0
	v_mov_b32_e32 v80, v0
	v_mov_b32_e32 v81, v0
	v_mov_b32_e32 v82, v0
	v_mov_b32_e32 v83, v0
	v_mov_b32_e32 v84, v0
	v_mov_b32_e32 v85, v0
	v_mov_b32_e32 v86, v0
	v_mov_b32_e32 v87, v0
	v_mov_b32_e32 v88, v0
	v_mov_b32_e32 v89, v0
	v_mov_b32_e32 v90, v0
	v_mov_b32_e32 v91, v0
	v_mov_b32_e32 v92, v0
	v_mov_b32_e32 v93, v0
	v_mov_b32_e32 v94, v0
	v_mov_b32_e32 v95, v0
	v_mov_b32_e32 v96, v0
	v_mov_b32_e32 v97, v0
	v_mov_b32_e32 v98, v0
	v_mov_b32_e32 v99, v0
	v_mov_b32_e32 v100, v0
	v_mov_b32_e32 v101, v0
	v_mov_b32_e32 v102, v0
	v_mov_b32_e32 v103, v0
	v_mov_b32_e32 v104, v0
	v_mov_b32_e32 v105, v0
	v_mov_b32_e32 v106, v0
	v_mov_b32_e32 v107, v0
	v_mov_b32_e32 v108, v0
	v_mov_b32_e32 v109, v0
	v_mov_b32_e32 v110, v0
	v_mov_b32_e32 v111, v0
	v_mov_b32_e32 v112, v0
	v_mov_b32_e32 v113, v0
	v_mov_b32_e32 v114, v0
	v_mov_b32_e32 v115, v0
	v_mov_b32_e32 v116, v0
	v_mov_b32_e32 v117, v0
	v_mov_b32_e32 v118, v0
	v_mov_b32_e32 v119, v0
	v_mov_b32_e32 v120, v0
	v_mov_b32_e32 v121, v0
	v_mov_b32_e32 v122, v0
	v_mov_b32_e32 v123, v0
	v_mov_b32_e32 v124, v0
	v_mov_b32_e32 v125, v0
	v_mov_b32_e32 v126, v0
	v_mov_b32_e32 v127, v0
	s_mov_b32 s94, 0
.Lgp6a_loop:
	s_waitcnt vmcnt(0) lgkmcnt(0)
	s_barrier
	ds_read_b128 v[164:167], v238
	ds_read_b128 v[172:175], v238 offset:2048
	ds_read_b128 v[176:179], v238 offset:4096
	ds_read_b128 v[180:183], v238 offset:6144
	ds_read_b128 v[200:203], v238 offset:16384
	ds_read_b128 v[204:207], v238 offset:18432
	ds_read_b128 v[208:211], v238 offset:20480
	ds_read_b128 v[212:215], v238 offset:22528
	ds_read_b128 v[128:131], v239 offset:32768
	ds_read_b128 v[132:135], v239 offset:34816
	ds_read_b128 v[136:139], v239 offset:36864
	ds_read_b128 v[140:143], v239 offset:38912
	ds_read_b128 v[184:187], v240
	ds_read_b128 v[188:191], v240 offset:2048
	ds_read_b128 v[192:195], v240 offset:4096
	ds_read_b128 v[196:199], v240 offset:6144
	ds_read_b128 v[216:219], v240 offset:16384
	ds_read_b128 v[220:223], v240 offset:18432
	ds_read_b128 v[224:227], v240 offset:20480
	ds_read_b128 v[228:231], v240 offset:22528
	ds_read_b128 v[148:151], v241 offset:32768
	ds_read_b128 v[152:155], v241 offset:34816
	ds_read_b128 v[156:159], v241 offset:36864
	ds_read_b128 v[160:163], v241 offset:38912
	s_waitcnt lgkmcnt(0)
	s_barrier
	s_cmp_eq_u32 s94, 15
	s_cbranch_scc1 .Lgp6a_last
	s_add_u32 m0, s96, 0x0
	v_mfma_f32_16x16x32_bf16 v[0:3], v[128:131], v[164:167], v[0:3]
	global_load_lds_dwordx4 v232, s[90:91]
	v_mfma_f32_16x16x32_bf16 v[64:67], v[128:131], v[200:203], v[64:67]
	s_add_u32 m0, s96, 0x1000
	v_mfma_f32_16x16x32_bf16 v[4:7], v[132:135], v[164:167], v[4:7]
	global_load_lds_dwordx4 v233, s[90:91]
	v_mfma_f32_16x16x32_bf16 v[68:71], v[132:135], v[200:203], v[68:71]
	s_add_u32 m0, s96, 0x2000
	v_mfma_f32_16x16x32_bf16 v[8:11], v[136:139], v[164:167], v[8:11]
	global_load_lds_dwordx4 v234, s[90:91]
	v_mfma_f32_16x16x32_bf16 v[72:75], v[136:139], v[200:203], v[72:75]
	s_add_u32 m0, s96, 0x3000
	v_mfma_f32_16x16x32_bf16 v[12:15], v[140:143], v[164:167], v[12:15]
	global_load_lds_dwordx4 v235, s[90:91]
	v_mfma_f32_16x16x32_bf16 v[76:79], v[140:143], v[200:203], v[76:79]
	s_add_u32 m0, s96, 0x4000
	v_mfma_f32_16x16x32_bf16 v[16:19], v[128:131], v[172:175], v[16:19]
	global_load_lds_dwordx4 v232, s[92:93]
	v_mfma_f32_16x16x32_bf16 v[80:83], v[128:131], v[204:207], v[80:83]
	s_add_u32 m0, s96, 0x5000
	v_mfma_f32_16x16x32_bf16 v[20:23], v[132:135], v[172:175], v[20:23]
	global_load_lds_dwordx4 v233, s[92:93]
	v_mfma_f32_16x16x32_bf16 v[84:87], v[132:135], v[204:207], v[84:87]
	s_add_u32 m0, s96, 0x6000
	v_mfma_f32_16x16x32_bf16 v[24:27], v[136:139], v[172:175], v[24:27]
	global_load_lds_dwordx4 v234, s[92:93]
	v_mfma_f32_16x16x32_bf16 v[88:91], v[136:139], v[204:207], v[88:91]
	s_add_u32 m0, s96, 0x7000
	v_mfma_f32_16x16x32_bf16 v[28:31], v[140:143], v[172:175], v[28:31]
	global_load_lds_dwordx4 v235, s[92:93]
	v_mfma_f32_16x16x32_bf16 v[92:95], v[140:143], v[204:207], v[92:95]
	s_add_u32 m0, s96, 0x8000
	v_mfma_f32_16x16x32_bf16 v[32:35], v[128:131], v[176:179], v[32:35]
	global_load_lds_dwordx4 v232, s[98:99]
	v_mfma_f32_16x16x32_bf16 v[96:99], v[128:131], v[208:211], v[96:99]
	s_add_u32 m0, s96, 0x9000
	v_mfma_f32_16x16x32_bf16 v[36:39], v[132:135], v[176:179], v[36:39]
	global_load_lds_dwordx4 v233, s[98:99]
	v_mfma_f32_16x16x32_bf16 v[100:103], v[132:135], v[208:211], v[100:103]
	s_add_u32 m0, s96, 0xa000
	v_mfma_f32_16x16x32_bf16 v[40:43], v[136:139], v[176:179], v[40:43]
	global_load_lds_dwordx4 v234, s[98:99]
	v_mfma_f32_16x16x32_bf16 v[104:107], v[136:139], v[208:211], v[104:107]
	s_add_u32 m0, s96, 0xb000
	v_mfma_f32_16x16x32_bf16 v[44:47], v[140:143], v[176:179], v[44:47]
	global_load_lds_dwordx4 v235, s[98:99]
	s_add_u32 s90, s90, 0x80
	s_addc_u32 s91, s91, 0
	s_add_u32 s92, s92, 0x80
	s_addc_u32 s93, s93, 0
	s_add_u32 s98, s98, 0x80
	s_addc_u32 s99, s99, 0
	v_mfma_f32_16x16x32_bf16 v[108:111], v[140:143], v[208:211], v[108:111]
	v_mfma_f32_16x16x32_bf16 v[48:51], v[128:131], v[180:183], v[48:51]
	v_mfma_f32_16x16x32_bf16 v[112:115], v[128:131], v[212:215], v[112:115]
	v_mfma_f32_16x16x32_bf16 v[52:55], v[132:135], v[180:183], v[52:55]
	v_mfma_f32_16x16x32_bf16 v[116:119], v[132:135], v[212:215], v[116:119]
	v_mfma_f32_16x16x32_bf16 v[56:59], v[136:139], v[180:183], v[56:59]
	v_mfma_f32_16x16x32_bf16 v[120:123], v[136:139], v[212:215], v[120:123]
	v_mfma_f32_16x16x32_bf16 v[60:63], v[140:143], v[180:183], v[60:63]
	v_mfma_f32_16x16x32_bf16 v[124:127], v[140:143], v[212:215], v[124:127]
	v_mfma_f32_16x16x32_bf16 v[0:3], v[148:151], v[184:187], v[0:3]
	v_mfma_f32_16x16x32_bf16 v[64:67], v[148:151], v[216:219], v[64:67]
	v_mfma_f32_16x16x32_bf16 v[4:7], v[152:155], v[184:187], v[4:7]
	v_mfma_f32_16x16x32_bf16 v[68:71], v[152:155], v[216:219], v[68:71]
	v_mfma_f32_16x16x32_bf16 v[8:11], v[156:159], v[184:187], v[8:11]
	v_mfma_f32_16x16x32_bf16 v[72:75], v[156:159], v[216:219], v[72:75]
	v_mfma_f32_16x16x32_bf16 v[12:15], v[160:163], v[184:187], v[12:15]
	v_mfma_f32_16x16x32_bf16 v[76:79], v[160:163], v[216:219], v[76:79]
	v_mfma_f32_16x16x32_bf16 v[16:19], v[148:151], v[188:191], v[16:19]
	v_mfma_f32_16x16x32_bf16 v[80:83], v[148:151], v[220:223], v[80:83]
	v_mfma_f32_16x16x32_bf16 v[20:23], v[152:155], v[188:191], v[20:23]
	v_mfma_f32_16x16x32_bf16 v[84:87], v[152:155], v[220:223], v[84:87]
	v_mfma_f32_16x16x32_bf16 v[24:27], v[156:159], v[188:191], v[24:27]
	v_mfma_f32_16x16x32_bf16 v[88:91], v[156:159], v[220:223], v[88:91]
	v_mfma_f32_16x16x32_bf16 v[28:31], v[160:163], v[188:191], v[28:31]
	v_mfma_f32_16x16x32_bf16 v[92:95], v[160:163], v[220:223], v[92:95]
	v_mfma_f32_16x16x32_bf16 v[32:35], v[148:151], v[192:195], v[32:35]
	v_mfma_f32_16x16x32_bf16 v[96:99], v[148:151], v[224:227], v[96:99]
	v_mfma_f32_16x16x32_bf16 v[36:39], v[152:155], v[192:195], v[36:39]
	v_mfma_f32_16x16x32_bf16 v[100:103], v[152:155], v[224:227], v[100:103]
	v_mfma_f32_16x16x32_bf16 v[40:43], v[156:159], v[192:195], v[40:43]
	v_mfma_f32_16x16x32_bf16 v[104:107], v[156:159], v[224:227], v[104:107]
	v_mfma_f32_16x16x32_bf16 v[44:47], v[160:163], v[192:195], v[44:47]
	v_mfma_f32_16x16x32_bf16 v[108:111], v[160:163], v[224:227], v[108:111]
	v_mfma_f32_16x16x32_bf16 v[48:51], v[148:151], v[196:199], v[48:51]
	v_mfma_f32_16x16x32_bf16 v[112:115], v[148:151], v[228:231], v[112:115]
	v_mfma_f32_16x16x32_bf16 v[52:55], v[152:155], v[196:199], v[52:55]
	v_mfma_f32_16x16x32_bf16 v[116:119], v[152:155], v[228:231], v[116:119]
	v_mfma_f32_16x16x32_bf16 v[56:59], v[156:159], v[196:199], v[56:59]
	v_mfma_f32_16x16x32_bf16 v[120:123], v[156:159], v[228:231], v[120:123]
	v_mfma_f32_16x16x32_bf16 v[60:63], v[160:163], v[196:199], v[60:63]
	v_mfma_f32_16x16x32_bf16 v[124:127], v[160:163], v[228:231], v[124:127]
	s_add_u32 s94, s94, 1
	s_branch .Lgp6a_loop
.Lgp6a_last:
	v_mfma_f32_16x16x32_bf16 v[0:3], v[128:131], v[164:167], v[0:3]
	v_mfma_f32_16x16x32_bf16 v[64:67], v[128:131], v[200:203], v[64:67]
	v_mfma_f32_16x16x32_bf16 v[4:7], v[132:135], v[164:167], v[4:7]
	v_mfma_f32_16x16x32_bf16 v[68:71], v[132:135], v[200:203], v[68:71]
	v_mfma_f32_16x16x32_bf16 v[8:11], v[136:139], v[164:167], v[8:11]
	v_mfma_f32_16x16x32_bf16 v[72:75], v[136:139], v[200:203], v[72:75]
	v_mfma_f32_16x16x32_bf16 v[12:15], v[140:143], v[164:167], v[12:15]
	v_mfma_f32_16x16x32_bf16 v[76:79], v[140:143], v[200:203], v[76:79]
	v_mfma_f32_16x16x32_bf16 v[16:19], v[128:131], v[172:175], v[16:19]
	v_mfma_f32_16x16x32_bf16 v[80:83], v[128:131], v[204:207], v[80:83]
	v_mfma_f32_16x16x32_bf16 v[20:23], v[132:135], v[172:175], v[20:23]
	v_mfma_f32_16x16x32_bf16 v[84:87], v[132:135], v[204:207], v[84:87]
	v_mfma_f32_16x16x32_bf16 v[24:27], v[136:139], v[172:175], v[24:27]
	v_mfma_f32_16x16x32_bf16 v[88:91], v[136:139], v[204:207], v[88:91]
	v_mfma_f32_16x16x32_bf16 v[28:31], v[140:143], v[172:175], v[28:31]
	v_mfma_f32_16x16x32_bf16 v[92:95], v[140:143], v[204:207], v[92:95]
	v_mfma_f32_16x16x32_bf16 v[32:35], v[128:131], v[176:179], v[32:35]
	v_mfma_f32_16x16x32_bf16 v[96:99], v[128:131], v[208:211], v[96:99]
	v_mfma_f32_16x16x32_bf16 v[36:39], v[132:135], v[176:179], v[36:39]
	v_mfma_f32_16x16x32_bf16 v[100:103], v[132:135], v[208:211], v[100:103]
	v_mfma_f32_16x16x32_bf16 v[40:43], v[136:139], v[176:179], v[40:43]
	v_mfma_f32_16x16x32_bf16 v[104:107], v[136:139], v[208:211], v[104:107]
	v_mfma_f32_16x16x32_bf16 v[44:47], v[140:143], v[176:179], v[44:47]
	v_mfma_f32_16x16x32_bf16 v[108:111], v[140:143], v[208:211], v[108:111]
	v_mfma_f32_16x16x32_bf16 v[48:51], v[128:131], v[180:183], v[48:51]
	v_mfma_f32_16x16x32_bf16 v[112:115], v[128:131], v[212:215], v[112:115]
	v_mfma_f32_16x16x32_bf16 v[52:55], v[132:135], v[180:183], v[52:55]
	v_mfma_f32_16x16x32_bf16 v[116:119], v[132:135], v[212:215], v[116:119]
	v_mfma_f32_16x16x32_bf16 v[56:59], v[136:139], v[180:183], v[56:59]
	v_mfma_f32_16x16x32_bf16 v[120:123], v[136:139], v[212:215], v[120:123]
	v_mfma_f32_16x16x32_bf16 v[60:63], v[140:143], v[180:183], v[60:63]
	v_mfma_f32_16x16x32_bf16 v[124:127], v[140:143], v[212:215], v[124:127]
	v_mfma_f32_16x16x32_bf16 v[0:3], v[148:151], v[184:187], v[0:3]
	v_mfma_f32_16x16x32_bf16 v[64:67], v[148:151], v[216:219], v[64:67]
	v_mfma_f32_16x16x32_bf16 v[4:7], v[152:155], v[184:187], v[4:7]
	v_mfma_f32_16x16x32_bf16 v[68:71], v[152:155], v[216:219], v[68:71]
	v_mfma_f32_16x16x32_bf16 v[8:11], v[156:159], v[184:187], v[8:11]
	v_mfma_f32_16x16x32_bf16 v[72:75], v[156:159], v[216:219], v[72:75]
	v_mfma_f32_16x16x32_bf16 v[12:15], v[160:163], v[184:187], v[12:15]
	v_mfma_f32_16x16x32_bf16 v[76:79], v[160:163], v[216:219], v[76:79]
	v_mfma_f32_16x16x32_bf16 v[16:19], v[148:151], v[188:191], v[16:19]
	v_mfma_f32_16x16x32_bf16 v[80:83], v[148:151], v[220:223], v[80:83]
	v_mfma_f32_16x16x32_bf16 v[20:23], v[152:155], v[188:191], v[20:23]
	v_mfma_f32_16x16x32_bf16 v[84:87], v[152:155], v[220:223], v[84:87]
	v_mfma_f32_16x16x32_bf16 v[24:27], v[156:159], v[188:191], v[24:27]
	v_mfma_f32_16x16x32_bf16 v[88:91], v[156:159], v[220:223], v[88:91]
	v_mfma_f32_16x16x32_bf16 v[28:31], v[160:163], v[188:191], v[28:31]
	v_mfma_f32_16x16x32_bf16 v[92:95], v[160:163], v[220:223], v[92:95]
	v_mfma_f32_16x16x32_bf16 v[32:35], v[148:151], v[192:195], v[32:35]
	v_mfma_f32_16x16x32_bf16 v[96:99], v[148:151], v[224:227], v[96:99]
	v_mfma_f32_16x16x32_bf16 v[36:39], v[152:155], v[192:195], v[36:39]
	v_mfma_f32_16x16x32_bf16 v[100:103], v[152:155], v[224:227], v[100:103]
	v_mfma_f32_16x16x32_bf16 v[40:43], v[156:159], v[192:195], v[40:43]
	v_mfma_f32_16x16x32_bf16 v[104:107], v[156:159], v[224:227], v[104:107]
	v_mfma_f32_16x16x32_bf16 v[44:47], v[160:163], v[192:195], v[44:47]
	v_mfma_f32_16x16x32_bf16 v[108:111], v[160:163], v[224:227], v[108:111]
	v_mfma_f32_16x16x32_bf16 v[48:51], v[148:151], v[196:199], v[48:51]
	v_mfma_f32_16x16x32_bf16 v[112:115], v[148:151], v[228:231], v[112:115]
	v_mfma_f32_16x16x32_bf16 v[52:55], v[152:155], v[196:199], v[52:55]
	v_mfma_f32_16x16x32_bf16 v[116:119], v[152:155], v[228:231], v[116:119]
	v_mfma_f32_16x16x32_bf16 v[56:59], v[156:159], v[196:199], v[56:59]
	v_mfma_f32_16x16x32_bf16 v[120:123], v[156:159], v[228:231], v[120:123]
	v_mfma_f32_16x16x32_bf16 v[60:63], v[160:163], v[196:199], v[60:63]
	v_mfma_f32_16x16x32_bf16 v[124:127], v[160:163], v[228:231], v[124:127]
	s_nop 7
	s_nop 3
	s_mov_b32 s83, 0
.Lp6a_ep:
	global_load_dwordx4 v[128:131], v244, s[22:23]
	global_load_dwordx4 v[132:135], v244, s[22:23] offset:64
	global_load_dwordx4 v[136:139], v244, s[22:23] offset:128
	global_load_dwordx4 v[140:143], v244, s[22:23] offset:192
	s_lshl_b32 s71, s83, 25
	s_add_u32 s84, s24, s71
	s_addc_u32 s85, s25, 0
	s_waitcnt vmcnt(0)
	v_add_f32_e32 v148, v0, v128
	v_add_f32_e32 v149, v1, v129
	v_add_f32_e32 v150, v2, v130
	v_add_f32_e32 v151, v3, v131
	v_add_f32_e32 v152, v4, v132
	v_add_f32_e32 v153, v5, v133
	v_add_f32_e32 v154, v6, v134
	v_add_f32_e32 v155, v7, v135
	v_mul_f32_e32 v148, 0xbfb8aa3b, v148
	v_mul_f32_e32 v149, 0xbfb8aa3b, v149
	v_mul_f32_e32 v150, 0xbfb8aa3b, v150
	v_mul_f32_e32 v151, 0xbfb8aa3b, v151
	v_mul_f32_e32 v152, 0xbfb8aa3b, v152
	v_mul_f32_e32 v153, 0xbfb8aa3b, v153
	v_mul_f32_e32 v154, 0xbfb8aa3b, v154
	v_mul_f32_e32 v155, 0xbfb8aa3b, v155
	v_exp_f32_e32 v156, v148
	v_exp_f32_e32 v157, v149
	v_exp_f32_e32 v158, v150
	v_exp_f32_e32 v159, v151
	v_exp_f32_e32 v160, v152
	v_exp_f32_e32 v161, v153
	v_exp_f32_e32 v162, v154
	v_exp_f32_e32 v163, v155
	v_add_f32_e32 v156, 1.0, v156
	v_add_f32_e32 v157, 1.0, v157
	v_add_f32_e32 v158, 1.0, v158
	v_add_f32_e32 v159, 1.0, v159
	v_add_f32_e32 v160, 1.0, v160
	v_add_f32_e32 v161, 1.0, v161
	v_add_f32_e32 v162, 1.0, v162
	v_add_f32_e32 v163, 1.0, v163
	v_div_scale_f32 v164, s[76:77], v156, v156, 1.0
	v_div_scale_f32 v165, s[76:77], v157, v157, 1.0
	v_div_scale_f32 v166, s[76:77], v158, v158, 1.0
	v_div_scale_f32 v167, s[76:77], v159, v159, 1.0
	v_div_scale_f32 v172, s[76:77], v160, v160, 1.0
	v_div_scale_f32 v173, s[76:77], v161, v161, 1.0
	v_div_scale_f32 v174, s[76:77], v162, v162, 1.0
	v_div_scale_f32 v175, s[76:77], v163, v163, 1.0
	v_rcp_f32_e32 v176, v164
	v_rcp_f32_e32 v177, v165
	v_rcp_f32_e32 v178, v166
	v_rcp_f32_e32 v179, v167
	v_rcp_f32_e32 v180, v172
	v_rcp_f32_e32 v181, v173
	v_rcp_f32_e32 v182, v174
	v_rcp_f32_e32 v183, v175
	v_fma_f32 v148, -v164, v176, 1.0
	v_fma_f32 v149, -v165, v177, 1.0
	v_fma_f32 v150, -v166, v178, 1.0
	v_fma_f32 v151, -v167, v179, 1.0
	v_fma_f32 v152, -v172, v180, 1.0
	v_fma_f32 v153, -v173, v181, 1.0
	v_fma_f32 v154, -v174, v182, 1.0
	v_fma_f32 v155, -v175, v183, 1.0
	v_fmac_f32_e32 v176, v148, v176
	v_fmac_f32_e32 v177, v149, v177
	v_fmac_f32_e32 v178, v150, v178
	v_fmac_f32_e32 v179, v151, v179
	v_fmac_f32_e32 v180, v152, v180
	v_fmac_f32_e32 v181, v153, v181
	v_fmac_f32_e32 v182, v154, v182
	v_fmac_f32_e32 v183, v155, v183
	v_div_scale_f32 v184, vcc, 1.0, v156, 1.0
	v_mul_f32_e32 v192, v184, v176
	v_fma_f32 v148, -v164, v192, v184
	v_fmac_f32_e32 v192, v148, v176
	v_fma_f32 v184, -v164, v192, v184
	v_div_fmas_f32 v184, v184, v176, v192
	v_div_fixup_f32 v148, v184, v156, 1.0
	v_div_scale_f32 v185, vcc, 1.0, v157, 1.0
	v_mul_f32_e32 v193, v185, v177
	v_fma_f32 v149, -v165, v193, v185
	v_fmac_f32_e32 v193, v149, v177
	v_fma_f32 v185, -v165, v193, v185
	v_div_fmas_f32 v185, v185, v177, v193
	v_div_fixup_f32 v149, v185, v157, 1.0
	v_div_scale_f32 v186, vcc, 1.0, v158, 1.0
	v_mul_f32_e32 v194, v186, v178
	v_fma_f32 v150, -v166, v194, v186
	v_fmac_f32_e32 v194, v150, v178
	v_fma_f32 v186, -v166, v194, v186
	v_div_fmas_f32 v186, v186, v178, v194
	v_div_fixup_f32 v150, v186, v158, 1.0
	v_div_scale_f32 v187, vcc, 1.0, v159, 1.0
	v_mul_f32_e32 v195, v187, v179
	v_fma_f32 v151, -v167, v195, v187
	v_fmac_f32_e32 v195, v151, v179
	v_fma_f32 v187, -v167, v195, v187
	v_div_fmas_f32 v187, v187, v179, v195
	v_div_fixup_f32 v151, v187, v159, 1.0
	v_div_scale_f32 v188, vcc, 1.0, v160, 1.0
	v_mul_f32_e32 v196, v188, v180
	v_fma_f32 v152, -v172, v196, v188
	v_fmac_f32_e32 v196, v152, v180
	v_fma_f32 v188, -v172, v196, v188
	v_div_fmas_f32 v188, v188, v180, v196
	v_div_fixup_f32 v152, v188, v160, 1.0
	v_div_scale_f32 v189, vcc, 1.0, v161, 1.0
	v_mul_f32_e32 v197, v189, v181
	v_fma_f32 v153, -v173, v197, v189
	v_fmac_f32_e32 v197, v153, v181
	v_fma_f32 v189, -v173, v197, v189
	v_div_fmas_f32 v189, v189, v181, v197
	v_div_fixup_f32 v153, v189, v161, 1.0
	v_div_scale_f32 v190, vcc, 1.0, v162, 1.0
	v_mul_f32_e32 v198, v190, v182
	v_fma_f32 v154, -v174, v198, v190
	v_fmac_f32_e32 v198, v154, v182
	v_fma_f32 v190, -v174, v198, v190
	v_div_fmas_f32 v190, v190, v182, v198
	v_div_fixup_f32 v154, v190, v162, 1.0
	v_div_scale_f32 v191, vcc, 1.0, v163, 1.0
	v_mul_f32_e32 v199, v191, v183
	v_fma_f32 v155, -v175, v199, v191
	v_fmac_f32_e32 v199, v155, v183
	v_fma_f32 v191, -v175, v199, v191
	v_div_fmas_f32 v191, v191, v183, v199
	v_div_fixup_f32 v155, v191, v163, 1.0
	v_and_b32_sdwa v208, v148, v242 dst_sel:DWORD dst_unused:UNUSED_PAD src0_sel:WORD_1 src1_sel:DWORD
	v_and_b32_sdwa v209, v149, v242 dst_sel:DWORD dst_unused:UNUSED_PAD src0_sel:WORD_1 src1_sel:DWORD
	v_and_b32_sdwa v210, v150, v242 dst_sel:DWORD dst_unused:UNUSED_PAD src0_sel:WORD_1 src1_sel:DWORD
	v_and_b32_sdwa v211, v151, v242 dst_sel:DWORD dst_unused:UNUSED_PAD src0_sel:WORD_1 src1_sel:DWORD
	v_and_b32_sdwa v212, v152, v242 dst_sel:DWORD dst_unused:UNUSED_PAD src0_sel:WORD_1 src1_sel:DWORD
	v_and_b32_sdwa v213, v153, v242 dst_sel:DWORD dst_unused:UNUSED_PAD src0_sel:WORD_1 src1_sel:DWORD
	v_and_b32_sdwa v214, v154, v242 dst_sel:DWORD dst_unused:UNUSED_PAD src0_sel:WORD_1 src1_sel:DWORD
	v_and_b32_sdwa v215, v155, v242 dst_sel:DWORD dst_unused:UNUSED_PAD src0_sel:WORD_1 src1_sel:DWORD
	v_add3_u32 v148, v148, v208, s3
	v_add3_u32 v149, v149, v209, s3
	v_add3_u32 v150, v150, v210, s3
	v_add3_u32 v151, v151, v211, s3
	v_add3_u32 v152, v152, v212, s3
	v_add3_u32 v153, v153, v213, s3
	v_add3_u32 v154, v154, v214, s3
	v_add3_u32 v155, v155, v215, s3
	v_and_b32_e32 v149, 0xffff0000, v149
	v_and_b32_e32 v151, 0xffff0000, v151
	v_and_b32_e32 v153, 0xffff0000, v153
	v_and_b32_e32 v155, 0xffff0000, v155
	v_or_b32_sdwa v200, v149, v148 dst_sel:DWORD dst_unused:UNUSED_PAD src0_sel:DWORD src1_sel:WORD_1
	v_or_b32_sdwa v201, v151, v150 dst_sel:DWORD dst_unused:UNUSED_PAD src0_sel:DWORD src1_sel:WORD_1
	v_or_b32_sdwa v202, v153, v152 dst_sel:DWORD dst_unused:UNUSED_PAD src0_sel:DWORD src1_sel:WORD_1
	v_or_b32_sdwa v203, v155, v154 dst_sel:DWORD dst_unused:UNUSED_PAD src0_sel:DWORD src1_sel:WORD_1
	global_store_dwordx4 v243, v[200:203], s[84:85]
	s_add_u32 s84, s84, 0x1000
	s_addc_u32 s85, s85, 0
	v_add_f32_e32 v148, v8, v136
	v_add_f32_e32 v149, v9, v137
	v_add_f32_e32 v150, v10, v138
	v_add_f32_e32 v151, v11, v139
	v_add_f32_e32 v152, v12, v140
	v_add_f32_e32 v153, v13, v141
	v_add_f32_e32 v154, v14, v142
	v_add_f32_e32 v155, v15, v143
	v_mul_f32_e32 v148, 0xbfb8aa3b, v148
	v_mul_f32_e32 v149, 0xbfb8aa3b, v149
	v_mul_f32_e32 v150, 0xbfb8aa3b, v150
	v_mul_f32_e32 v151, 0xbfb8aa3b, v151
	v_mul_f32_e32 v152, 0xbfb8aa3b, v152
	v_mul_f32_e32 v153, 0xbfb8aa3b, v153
	v_mul_f32_e32 v154, 0xbfb8aa3b, v154
	v_mul_f32_e32 v155, 0xbfb8aa3b, v155
	v_exp_f32_e32 v156, v148
	v_exp_f32_e32 v157, v149
	v_exp_f32_e32 v158, v150
	v_exp_f32_e32 v159, v151
	v_exp_f32_e32 v160, v152
	v_exp_f32_e32 v161, v153
	v_exp_f32_e32 v162, v154
	v_exp_f32_e32 v163, v155
	v_add_f32_e32 v156, 1.0, v156
	v_add_f32_e32 v157, 1.0, v157
	v_add_f32_e32 v158, 1.0, v158
	v_add_f32_e32 v159, 1.0, v159
	v_add_f32_e32 v160, 1.0, v160
	v_add_f32_e32 v161, 1.0, v161
	v_add_f32_e32 v162, 1.0, v162
	v_add_f32_e32 v163, 1.0, v163
	v_div_scale_f32 v164, s[76:77], v156, v156, 1.0
	v_div_scale_f32 v165, s[76:77], v157, v157, 1.0
	v_div_scale_f32 v166, s[76:77], v158, v158, 1.0
	v_div_scale_f32 v167, s[76:77], v159, v159, 1.0
	v_div_scale_f32 v172, s[76:77], v160, v160, 1.0
	v_div_scale_f32 v173, s[76:77], v161, v161, 1.0
	v_div_scale_f32 v174, s[76:77], v162, v162, 1.0
	v_div_scale_f32 v175, s[76:77], v163, v163, 1.0
	v_rcp_f32_e32 v176, v164
	v_rcp_f32_e32 v177, v165
	v_rcp_f32_e32 v178, v166
	v_rcp_f32_e32 v179, v167
	v_rcp_f32_e32 v180, v172
	v_rcp_f32_e32 v181, v173
	v_rcp_f32_e32 v182, v174
	v_rcp_f32_e32 v183, v175
	v_fma_f32 v148, -v164, v176, 1.0
	v_fma_f32 v149, -v165, v177, 1.0
	v_fma_f32 v150, -v166, v178, 1.0
	v_fma_f32 v151, -v167, v179, 1.0
	v_fma_f32 v152, -v172, v180, 1.0
	v_fma_f32 v153, -v173, v181, 1.0
	v_fma_f32 v154, -v174, v182, 1.0
	v_fma_f32 v155, -v175, v183, 1.0
	v_fmac_f32_e32 v176, v148, v176
	v_fmac_f32_e32 v177, v149, v177
	v_fmac_f32_e32 v178, v150, v178
	v_fmac_f32_e32 v179, v151, v179
	v_fmac_f32_e32 v180, v152, v180
	v_fmac_f32_e32 v181, v153, v181
	v_fmac_f32_e32 v182, v154, v182
	v_fmac_f32_e32 v183, v155, v183
	v_div_scale_f32 v184, vcc, 1.0, v156, 1.0
	v_mul_f32_e32 v192, v184, v176
	v_fma_f32 v148, -v164, v192, v184
	v_fmac_f32_e32 v192, v148, v176
	v_fma_f32 v184, -v164, v192, v184
	v_div_fmas_f32 v184, v184, v176, v192
	v_div_fixup_f32 v148, v184, v156, 1.0
	v_div_scale_f32 v185, vcc, 1.0, v157, 1.0
	v_mul_f32_e32 v193, v185, v177
	v_fma_f32 v149, -v165, v193, v185
	v_fmac_f32_e32 v193, v149, v177
	v_fma_f32 v185, -v165, v193, v185
	v_div_fmas_f32 v185, v185, v177, v193
	v_div_fixup_f32 v149, v185, v157, 1.0
	v_div_scale_f32 v186, vcc, 1.0, v158, 1.0
	v_mul_f32_e32 v194, v186, v178
	v_fma_f32 v150, -v166, v194, v186
	v_fmac_f32_e32 v194, v150, v178
	v_fma_f32 v186, -v166, v194, v186
	v_div_fmas_f32 v186, v186, v178, v194
	v_div_fixup_f32 v150, v186, v158, 1.0
	v_div_scale_f32 v187, vcc, 1.0, v159, 1.0
	v_mul_f32_e32 v195, v187, v179
	v_fma_f32 v151, -v167, v195, v187
	v_fmac_f32_e32 v195, v151, v179
	v_fma_f32 v187, -v167, v195, v187
	v_div_fmas_f32 v187, v187, v179, v195
	v_div_fixup_f32 v151, v187, v159, 1.0
	v_div_scale_f32 v188, vcc, 1.0, v160, 1.0
	v_mul_f32_e32 v196, v188, v180
	v_fma_f32 v152, -v172, v196, v188
	v_fmac_f32_e32 v196, v152, v180
	v_fma_f32 v188, -v172, v196, v188
	v_div_fmas_f32 v188, v188, v180, v196
	v_div_fixup_f32 v152, v188, v160, 1.0
	v_div_scale_f32 v189, vcc, 1.0, v161, 1.0
	v_mul_f32_e32 v197, v189, v181
	v_fma_f32 v153, -v173, v197, v189
	v_fmac_f32_e32 v197, v153, v181
	v_fma_f32 v189, -v173, v197, v189
	v_div_fmas_f32 v189, v189, v181, v197
	v_div_fixup_f32 v153, v189, v161, 1.0
	v_div_scale_f32 v190, vcc, 1.0, v162, 1.0
	v_mul_f32_e32 v198, v190, v182
	v_fma_f32 v154, -v174, v198, v190
	v_fmac_f32_e32 v198, v154, v182
	v_fma_f32 v190, -v174, v198, v190
	v_div_fmas_f32 v190, v190, v182, v198
	v_div_fixup_f32 v154, v190, v162, 1.0
	v_div_scale_f32 v191, vcc, 1.0, v163, 1.0
	v_mul_f32_e32 v199, v191, v183
	v_fma_f32 v155, -v175, v199, v191
	v_fmac_f32_e32 v199, v155, v183
	v_fma_f32 v191, -v175, v199, v191
	v_div_fmas_f32 v191, v191, v183, v199
	v_div_fixup_f32 v155, v191, v163, 1.0
	v_and_b32_sdwa v208, v148, v242 dst_sel:DWORD dst_unused:UNUSED_PAD src0_sel:WORD_1 src1_sel:DWORD
	v_and_b32_sdwa v209, v149, v242 dst_sel:DWORD dst_unused:UNUSED_PAD src0_sel:WORD_1 src1_sel:DWORD
	v_and_b32_sdwa v210, v150, v242 dst_sel:DWORD dst_unused:UNUSED_PAD src0_sel:WORD_1 src1_sel:DWORD
	v_and_b32_sdwa v211, v151, v242 dst_sel:DWORD dst_unused:UNUSED_PAD src0_sel:WORD_1 src1_sel:DWORD
	v_and_b32_sdwa v212, v152, v242 dst_sel:DWORD dst_unused:UNUSED_PAD src0_sel:WORD_1 src1_sel:DWORD
	v_and_b32_sdwa v213, v153, v242 dst_sel:DWORD dst_unused:UNUSED_PAD src0_sel:WORD_1 src1_sel:DWORD
	v_and_b32_sdwa v214, v154, v242 dst_sel:DWORD dst_unused:UNUSED_PAD src0_sel:WORD_1 src1_sel:DWORD
	v_and_b32_sdwa v215, v155, v242 dst_sel:DWORD dst_unused:UNUSED_PAD src0_sel:WORD_1 src1_sel:DWORD
	v_add3_u32 v148, v148, v208, s3
	v_add3_u32 v149, v149, v209, s3
	v_add3_u32 v150, v150, v210, s3
	v_add3_u32 v151, v151, v211, s3
	v_add3_u32 v152, v152, v212, s3
	v_add3_u32 v153, v153, v213, s3
	v_add3_u32 v154, v154, v214, s3
	v_add3_u32 v155, v155, v215, s3
	v_and_b32_e32 v149, 0xffff0000, v149
	v_and_b32_e32 v151, 0xffff0000, v151
	v_and_b32_e32 v153, 0xffff0000, v153
	v_and_b32_e32 v155, 0xffff0000, v155
	v_or_b32_sdwa v204, v149, v148 dst_sel:DWORD dst_unused:UNUSED_PAD src0_sel:DWORD src1_sel:WORD_1
	v_or_b32_sdwa v205, v151, v150 dst_sel:DWORD dst_unused:UNUSED_PAD src0_sel:DWORD src1_sel:WORD_1
	v_or_b32_sdwa v206, v153, v152 dst_sel:DWORD dst_unused:UNUSED_PAD src0_sel:DWORD src1_sel:WORD_1
	v_or_b32_sdwa v207, v155, v154 dst_sel:DWORD dst_unused:UNUSED_PAD src0_sel:DWORD src1_sel:WORD_1
	global_store_dwordx4 v243, v[204:207], s[84:85]
	s_add_u32 s84, s84, 0x1000
	s_addc_u32 s85, s85, 0
	v_add_f32_e32 v148, v16, v128
	v_add_f32_e32 v149, v17, v129
	v_add_f32_e32 v150, v18, v130
	v_add_f32_e32 v151, v19, v131
	v_add_f32_e32 v152, v20, v132
	v_add_f32_e32 v153, v21, v133
	v_add_f32_e32 v154, v22, v134
	v_add_f32_e32 v155, v23, v135
	v_mul_f32_e32 v148, 0xbfb8aa3b, v148
	v_mul_f32_e32 v149, 0xbfb8aa3b, v149
	v_mul_f32_e32 v150, 0xbfb8aa3b, v150
	v_mul_f32_e32 v151, 0xbfb8aa3b, v151
	v_mul_f32_e32 v152, 0xbfb8aa3b, v152
	v_mul_f32_e32 v153, 0xbfb8aa3b, v153
	v_mul_f32_e32 v154, 0xbfb8aa3b, v154
	v_mul_f32_e32 v155, 0xbfb8aa3b, v155
	v_exp_f32_e32 v156, v148
	v_exp_f32_e32 v157, v149
	v_exp_f32_e32 v158, v150
	v_exp_f32_e32 v159, v151
	v_exp_f32_e32 v160, v152
	v_exp_f32_e32 v161, v153
	v_exp_f32_e32 v162, v154
	v_exp_f32_e32 v163, v155
	v_add_f32_e32 v156, 1.0, v156
	v_add_f32_e32 v157, 1.0, v157
	v_add_f32_e32 v158, 1.0, v158
	v_add_f32_e32 v159, 1.0, v159
	v_add_f32_e32 v160, 1.0, v160
	v_add_f32_e32 v161, 1.0, v161
	v_add_f32_e32 v162, 1.0, v162
	v_add_f32_e32 v163, 1.0, v163
	v_div_scale_f32 v164, s[76:77], v156, v156, 1.0
	v_div_scale_f32 v165, s[76:77], v157, v157, 1.0
	v_div_scale_f32 v166, s[76:77], v158, v158, 1.0
	v_div_scale_f32 v167, s[76:77], v159, v159, 1.0
	v_div_scale_f32 v172, s[76:77], v160, v160, 1.0
	v_div_scale_f32 v173, s[76:77], v161, v161, 1.0
	v_div_scale_f32 v174, s[76:77], v162, v162, 1.0
	v_div_scale_f32 v175, s[76:77], v163, v163, 1.0
	v_rcp_f32_e32 v176, v164
	v_rcp_f32_e32 v177, v165
	v_rcp_f32_e32 v178, v166
	v_rcp_f32_e32 v179, v167
	v_rcp_f32_e32 v180, v172
	v_rcp_f32_e32 v181, v173
	v_rcp_f32_e32 v182, v174
	v_rcp_f32_e32 v183, v175
	v_fma_f32 v148, -v164, v176, 1.0
	v_fma_f32 v149, -v165, v177, 1.0
	v_fma_f32 v150, -v166, v178, 1.0
	v_fma_f32 v151, -v167, v179, 1.0
	v_fma_f32 v152, -v172, v180, 1.0
	v_fma_f32 v153, -v173, v181, 1.0
	v_fma_f32 v154, -v174, v182, 1.0
	v_fma_f32 v155, -v175, v183, 1.0
	v_fmac_f32_e32 v176, v148, v176
	v_fmac_f32_e32 v177, v149, v177
	v_fmac_f32_e32 v178, v150, v178
	v_fmac_f32_e32 v179, v151, v179
	v_fmac_f32_e32 v180, v152, v180
	v_fmac_f32_e32 v181, v153, v181
	v_fmac_f32_e32 v182, v154, v182
	v_fmac_f32_e32 v183, v155, v183
	v_div_scale_f32 v184, vcc, 1.0, v156, 1.0
	v_mul_f32_e32 v192, v184, v176
	v_fma_f32 v148, -v164, v192, v184
	v_fmac_f32_e32 v192, v148, v176
	v_fma_f32 v184, -v164, v192, v184
	v_div_fmas_f32 v184, v184, v176, v192
	v_div_fixup_f32 v148, v184, v156, 1.0
	v_div_scale_f32 v185, vcc, 1.0, v157, 1.0
	v_mul_f32_e32 v193, v185, v177
	v_fma_f32 v149, -v165, v193, v185
	v_fmac_f32_e32 v193, v149, v177
	v_fma_f32 v185, -v165, v193, v185
	v_div_fmas_f32 v185, v185, v177, v193
	v_div_fixup_f32 v149, v185, v157, 1.0
	v_div_scale_f32 v186, vcc, 1.0, v158, 1.0
	v_mul_f32_e32 v194, v186, v178
	v_fma_f32 v150, -v166, v194, v186
	v_fmac_f32_e32 v194, v150, v178
	v_fma_f32 v186, -v166, v194, v186
	v_div_fmas_f32 v186, v186, v178, v194
	v_div_fixup_f32 v150, v186, v158, 1.0
	v_div_scale_f32 v187, vcc, 1.0, v159, 1.0
	v_mul_f32_e32 v195, v187, v179
	v_fma_f32 v151, -v167, v195, v187
	v_fmac_f32_e32 v195, v151, v179
	v_fma_f32 v187, -v167, v195, v187
	v_div_fmas_f32 v187, v187, v179, v195
	v_div_fixup_f32 v151, v187, v159, 1.0
	v_div_scale_f32 v188, vcc, 1.0, v160, 1.0
	v_mul_f32_e32 v196, v188, v180
	v_fma_f32 v152, -v172, v196, v188
	v_fmac_f32_e32 v196, v152, v180
	v_fma_f32 v188, -v172, v196, v188
	v_div_fmas_f32 v188, v188, v180, v196
	v_div_fixup_f32 v152, v188, v160, 1.0
	v_div_scale_f32 v189, vcc, 1.0, v161, 1.0
	v_mul_f32_e32 v197, v189, v181
	v_fma_f32 v153, -v173, v197, v189
	v_fmac_f32_e32 v197, v153, v181
	v_fma_f32 v189, -v173, v197, v189
	v_div_fmas_f32 v189, v189, v181, v197
	v_div_fixup_f32 v153, v189, v161, 1.0
	v_div_scale_f32 v190, vcc, 1.0, v162, 1.0
	v_mul_f32_e32 v198, v190, v182
	v_fma_f32 v154, -v174, v198, v190
	v_fmac_f32_e32 v198, v154, v182
	v_fma_f32 v190, -v174, v198, v190
	v_div_fmas_f32 v190, v190, v182, v198
	v_div_fixup_f32 v154, v190, v162, 1.0
	v_div_scale_f32 v191, vcc, 1.0, v163, 1.0
	v_mul_f32_e32 v199, v191, v183
	v_fma_f32 v155, -v175, v199, v191
	v_fmac_f32_e32 v199, v155, v183
	v_fma_f32 v191, -v175, v199, v191
	v_div_fmas_f32 v191, v191, v183, v199
	v_div_fixup_f32 v155, v191, v163, 1.0
	v_and_b32_sdwa v208, v148, v242 dst_sel:DWORD dst_unused:UNUSED_PAD src0_sel:WORD_1 src1_sel:DWORD
	v_and_b32_sdwa v209, v149, v242 dst_sel:DWORD dst_unused:UNUSED_PAD src0_sel:WORD_1 src1_sel:DWORD
	v_and_b32_sdwa v210, v150, v242 dst_sel:DWORD dst_unused:UNUSED_PAD src0_sel:WORD_1 src1_sel:DWORD
	v_and_b32_sdwa v211, v151, v242 dst_sel:DWORD dst_unused:UNUSED_PAD src0_sel:WORD_1 src1_sel:DWORD
	v_and_b32_sdwa v212, v152, v242 dst_sel:DWORD dst_unused:UNUSED_PAD src0_sel:WORD_1 src1_sel:DWORD
	v_and_b32_sdwa v213, v153, v242 dst_sel:DWORD dst_unused:UNUSED_PAD src0_sel:WORD_1 src1_sel:DWORD
	v_and_b32_sdwa v214, v154, v242 dst_sel:DWORD dst_unused:UNUSED_PAD src0_sel:WORD_1 src1_sel:DWORD
	v_and_b32_sdwa v215, v155, v242 dst_sel:DWORD dst_unused:UNUSED_PAD src0_sel:WORD_1 src1_sel:DWORD
	v_add3_u32 v148, v148, v208, s3
	v_add3_u32 v149, v149, v209, s3
	v_add3_u32 v150, v150, v210, s3
	v_add3_u32 v151, v151, v211, s3
	v_add3_u32 v152, v152, v212, s3
	v_add3_u32 v153, v153, v213, s3
	v_add3_u32 v154, v154, v214, s3
	v_add3_u32 v155, v155, v215, s3
	v_and_b32_e32 v149, 0xffff0000, v149
	v_and_b32_e32 v151, 0xffff0000, v151
	v_and_b32_e32 v153, 0xffff0000, v153
	v_and_b32_e32 v155, 0xffff0000, v155
	v_or_b32_sdwa v200, v149, v148 dst_sel:DWORD dst_unused:UNUSED_PAD src0_sel:DWORD src1_sel:WORD_1
	v_or_b32_sdwa v201, v151, v150 dst_sel:DWORD dst_unused:UNUSED_PAD src0_sel:DWORD src1_sel:WORD_1
	v_or_b32_sdwa v202, v153, v152 dst_sel:DWORD dst_unused:UNUSED_PAD src0_sel:DWORD src1_sel:WORD_1
	v_or_b32_sdwa v203, v155, v154 dst_sel:DWORD dst_unused:UNUSED_PAD src0_sel:DWORD src1_sel:WORD_1
	global_store_dwordx4 v243, v[200:203], s[84:85]
	s_add_u32 s84, s84, 0x1000
	s_addc_u32 s85, s85, 0
	v_add_f32_e32 v148, v24, v136
	v_add_f32_e32 v149, v25, v137
	v_add_f32_e32 v150, v26, v138
	v_add_f32_e32 v151, v27, v139
	v_add_f32_e32 v152, v28, v140
	v_add_f32_e32 v153, v29, v141
	v_add_f32_e32 v154, v30, v142
	v_add_f32_e32 v155, v31, v143
	v_mul_f32_e32 v148, 0xbfb8aa3b, v148
	v_mul_f32_e32 v149, 0xbfb8aa3b, v149
	v_mul_f32_e32 v150, 0xbfb8aa3b, v150
	v_mul_f32_e32 v151, 0xbfb8aa3b, v151
	v_mul_f32_e32 v152, 0xbfb8aa3b, v152
	v_mul_f32_e32 v153, 0xbfb8aa3b, v153
	v_mul_f32_e32 v154, 0xbfb8aa3b, v154
	v_mul_f32_e32 v155, 0xbfb8aa3b, v155
	v_exp_f32_e32 v156, v148
	v_exp_f32_e32 v157, v149
	v_exp_f32_e32 v158, v150
	v_exp_f32_e32 v159, v151
	v_exp_f32_e32 v160, v152
	v_exp_f32_e32 v161, v153
	v_exp_f32_e32 v162, v154
	v_exp_f32_e32 v163, v155
	v_add_f32_e32 v156, 1.0, v156
	v_add_f32_e32 v157, 1.0, v157
	v_add_f32_e32 v158, 1.0, v158
	v_add_f32_e32 v159, 1.0, v159
	v_add_f32_e32 v160, 1.0, v160
	v_add_f32_e32 v161, 1.0, v161
	v_add_f32_e32 v162, 1.0, v162
	v_add_f32_e32 v163, 1.0, v163
	v_div_scale_f32 v164, s[76:77], v156, v156, 1.0
	v_div_scale_f32 v165, s[76:77], v157, v157, 1.0
	v_div_scale_f32 v166, s[76:77], v158, v158, 1.0
	v_div_scale_f32 v167, s[76:77], v159, v159, 1.0
	v_div_scale_f32 v172, s[76:77], v160, v160, 1.0
	v_div_scale_f32 v173, s[76:77], v161, v161, 1.0
	v_div_scale_f32 v174, s[76:77], v162, v162, 1.0
	v_div_scale_f32 v175, s[76:77], v163, v163, 1.0
	v_rcp_f32_e32 v176, v164
	v_rcp_f32_e32 v177, v165
	v_rcp_f32_e32 v178, v166
	v_rcp_f32_e32 v179, v167
	v_rcp_f32_e32 v180, v172
	v_rcp_f32_e32 v181, v173
	v_rcp_f32_e32 v182, v174
	v_rcp_f32_e32 v183, v175
	v_fma_f32 v148, -v164, v176, 1.0
	v_fma_f32 v149, -v165, v177, 1.0
	v_fma_f32 v150, -v166, v178, 1.0
	v_fma_f32 v151, -v167, v179, 1.0
	v_fma_f32 v152, -v172, v180, 1.0
	v_fma_f32 v153, -v173, v181, 1.0
	v_fma_f32 v154, -v174, v182, 1.0
	v_fma_f32 v155, -v175, v183, 1.0
	v_fmac_f32_e32 v176, v148, v176
	v_fmac_f32_e32 v177, v149, v177
	v_fmac_f32_e32 v178, v150, v178
	v_fmac_f32_e32 v179, v151, v179
	v_fmac_f32_e32 v180, v152, v180
	v_fmac_f32_e32 v181, v153, v181
	v_fmac_f32_e32 v182, v154, v182
	v_fmac_f32_e32 v183, v155, v183
	v_div_scale_f32 v184, vcc, 1.0, v156, 1.0
	v_mul_f32_e32 v192, v184, v176
	v_fma_f32 v148, -v164, v192, v184
	v_fmac_f32_e32 v192, v148, v176
	v_fma_f32 v184, -v164, v192, v184
	v_div_fmas_f32 v184, v184, v176, v192
	v_div_fixup_f32 v148, v184, v156, 1.0
	v_div_scale_f32 v185, vcc, 1.0, v157, 1.0
	v_mul_f32_e32 v193, v185, v177
	v_fma_f32 v149, -v165, v193, v185
	v_fmac_f32_e32 v193, v149, v177
	v_fma_f32 v185, -v165, v193, v185
	v_div_fmas_f32 v185, v185, v177, v193
	v_div_fixup_f32 v149, v185, v157, 1.0
	v_div_scale_f32 v186, vcc, 1.0, v158, 1.0
	v_mul_f32_e32 v194, v186, v178
	v_fma_f32 v150, -v166, v194, v186
	v_fmac_f32_e32 v194, v150, v178
	v_fma_f32 v186, -v166, v194, v186
	v_div_fmas_f32 v186, v186, v178, v194
	v_div_fixup_f32 v150, v186, v158, 1.0
	v_div_scale_f32 v187, vcc, 1.0, v159, 1.0
	v_mul_f32_e32 v195, v187, v179
	v_fma_f32 v151, -v167, v195, v187
	v_fmac_f32_e32 v195, v151, v179
	v_fma_f32 v187, -v167, v195, v187
	v_div_fmas_f32 v187, v187, v179, v195
	v_div_fixup_f32 v151, v187, v159, 1.0
	v_div_scale_f32 v188, vcc, 1.0, v160, 1.0
	v_mul_f32_e32 v196, v188, v180
	v_fma_f32 v152, -v172, v196, v188
	v_fmac_f32_e32 v196, v152, v180
	v_fma_f32 v188, -v172, v196, v188
	v_div_fmas_f32 v188, v188, v180, v196
	v_div_fixup_f32 v152, v188, v160, 1.0
	v_div_scale_f32 v189, vcc, 1.0, v161, 1.0
	v_mul_f32_e32 v197, v189, v181
	v_fma_f32 v153, -v173, v197, v189
	v_fmac_f32_e32 v197, v153, v181
	v_fma_f32 v189, -v173, v197, v189
	v_div_fmas_f32 v189, v189, v181, v197
	v_div_fixup_f32 v153, v189, v161, 1.0
	v_div_scale_f32 v190, vcc, 1.0, v162, 1.0
	v_mul_f32_e32 v198, v190, v182
	v_fma_f32 v154, -v174, v198, v190
	v_fmac_f32_e32 v198, v154, v182
	v_fma_f32 v190, -v174, v198, v190
	v_div_fmas_f32 v190, v190, v182, v198
	v_div_fixup_f32 v154, v190, v162, 1.0
	v_div_scale_f32 v191, vcc, 1.0, v163, 1.0
	v_mul_f32_e32 v199, v191, v183
	v_fma_f32 v155, -v175, v199, v191
	v_fmac_f32_e32 v199, v155, v183
	v_fma_f32 v191, -v175, v199, v191
	v_div_fmas_f32 v191, v191, v183, v199
	v_div_fixup_f32 v155, v191, v163, 1.0
	v_and_b32_sdwa v208, v148, v242 dst_sel:DWORD dst_unused:UNUSED_PAD src0_sel:WORD_1 src1_sel:DWORD
	v_and_b32_sdwa v209, v149, v242 dst_sel:DWORD dst_unused:UNUSED_PAD src0_sel:WORD_1 src1_sel:DWORD
	v_and_b32_sdwa v210, v150, v242 dst_sel:DWORD dst_unused:UNUSED_PAD src0_sel:WORD_1 src1_sel:DWORD
	v_and_b32_sdwa v211, v151, v242 dst_sel:DWORD dst_unused:UNUSED_PAD src0_sel:WORD_1 src1_sel:DWORD
	v_and_b32_sdwa v212, v152, v242 dst_sel:DWORD dst_unused:UNUSED_PAD src0_sel:WORD_1 src1_sel:DWORD
	v_and_b32_sdwa v213, v153, v242 dst_sel:DWORD dst_unused:UNUSED_PAD src0_sel:WORD_1 src1_sel:DWORD
	v_and_b32_sdwa v214, v154, v242 dst_sel:DWORD dst_unused:UNUSED_PAD src0_sel:WORD_1 src1_sel:DWORD
	v_and_b32_sdwa v215, v155, v242 dst_sel:DWORD dst_unused:UNUSED_PAD src0_sel:WORD_1 src1_sel:DWORD
	v_add3_u32 v148, v148, v208, s3
	v_add3_u32 v149, v149, v209, s3
	v_add3_u32 v150, v150, v210, s3
	v_add3_u32 v151, v151, v211, s3
	v_add3_u32 v152, v152, v212, s3
	v_add3_u32 v153, v153, v213, s3
	v_add3_u32 v154, v154, v214, s3
	v_add3_u32 v155, v155, v215, s3
	v_and_b32_e32 v149, 0xffff0000, v149
	v_and_b32_e32 v151, 0xffff0000, v151
	v_and_b32_e32 v153, 0xffff0000, v153
	v_and_b32_e32 v155, 0xffff0000, v155
	v_or_b32_sdwa v204, v149, v148 dst_sel:DWORD dst_unused:UNUSED_PAD src0_sel:DWORD src1_sel:WORD_1
	v_or_b32_sdwa v205, v151, v150 dst_sel:DWORD dst_unused:UNUSED_PAD src0_sel:DWORD src1_sel:WORD_1
	v_or_b32_sdwa v206, v153, v152 dst_sel:DWORD dst_unused:UNUSED_PAD src0_sel:DWORD src1_sel:WORD_1
	v_or_b32_sdwa v207, v155, v154 dst_sel:DWORD dst_unused:UNUSED_PAD src0_sel:DWORD src1_sel:WORD_1
	global_store_dwordx4 v243, v[204:207], s[84:85]
	s_add_u32 s84, s84, 0x1000
	s_addc_u32 s85, s85, 0
	v_add_f32_e32 v148, v32, v128
	v_add_f32_e32 v149, v33, v129
	v_add_f32_e32 v150, v34, v130
	v_add_f32_e32 v151, v35, v131
	v_add_f32_e32 v152, v36, v132
	v_add_f32_e32 v153, v37, v133
	v_add_f32_e32 v154, v38, v134
	v_add_f32_e32 v155, v39, v135
	v_mul_f32_e32 v148, 0xbfb8aa3b, v148
	v_mul_f32_e32 v149, 0xbfb8aa3b, v149
	v_mul_f32_e32 v150, 0xbfb8aa3b, v150
	v_mul_f32_e32 v151, 0xbfb8aa3b, v151
	v_mul_f32_e32 v152, 0xbfb8aa3b, v152
	v_mul_f32_e32 v153, 0xbfb8aa3b, v153
	v_mul_f32_e32 v154, 0xbfb8aa3b, v154
	v_mul_f32_e32 v155, 0xbfb8aa3b, v155
	v_exp_f32_e32 v156, v148
	v_exp_f32_e32 v157, v149
	v_exp_f32_e32 v158, v150
	v_exp_f32_e32 v159, v151
	v_exp_f32_e32 v160, v152
	v_exp_f32_e32 v161, v153
	v_exp_f32_e32 v162, v154
	v_exp_f32_e32 v163, v155
	v_add_f32_e32 v156, 1.0, v156
	v_add_f32_e32 v157, 1.0, v157
	v_add_f32_e32 v158, 1.0, v158
	v_add_f32_e32 v159, 1.0, v159
	v_add_f32_e32 v160, 1.0, v160
	v_add_f32_e32 v161, 1.0, v161
	v_add_f32_e32 v162, 1.0, v162
	v_add_f32_e32 v163, 1.0, v163
	v_div_scale_f32 v164, s[76:77], v156, v156, 1.0
	v_div_scale_f32 v165, s[76:77], v157, v157, 1.0
	v_div_scale_f32 v166, s[76:77], v158, v158, 1.0
	v_div_scale_f32 v167, s[76:77], v159, v159, 1.0
	v_div_scale_f32 v172, s[76:77], v160, v160, 1.0
	v_div_scale_f32 v173, s[76:77], v161, v161, 1.0
	v_div_scale_f32 v174, s[76:77], v162, v162, 1.0
	v_div_scale_f32 v175, s[76:77], v163, v163, 1.0
	v_rcp_f32_e32 v176, v164
	v_rcp_f32_e32 v177, v165
	v_rcp_f32_e32 v178, v166
	v_rcp_f32_e32 v179, v167
	v_rcp_f32_e32 v180, v172
	v_rcp_f32_e32 v181, v173
	v_rcp_f32_e32 v182, v174
	v_rcp_f32_e32 v183, v175
	v_fma_f32 v148, -v164, v176, 1.0
	v_fma_f32 v149, -v165, v177, 1.0
	v_fma_f32 v150, -v166, v178, 1.0
	v_fma_f32 v151, -v167, v179, 1.0
	v_fma_f32 v152, -v172, v180, 1.0
	v_fma_f32 v153, -v173, v181, 1.0
	v_fma_f32 v154, -v174, v182, 1.0
	v_fma_f32 v155, -v175, v183, 1.0
	v_fmac_f32_e32 v176, v148, v176
	v_fmac_f32_e32 v177, v149, v177
	v_fmac_f32_e32 v178, v150, v178
	v_fmac_f32_e32 v179, v151, v179
	v_fmac_f32_e32 v180, v152, v180
	v_fmac_f32_e32 v181, v153, v181
	v_fmac_f32_e32 v182, v154, v182
	v_fmac_f32_e32 v183, v155, v183
	v_div_scale_f32 v184, vcc, 1.0, v156, 1.0
	v_mul_f32_e32 v192, v184, v176
	v_fma_f32 v148, -v164, v192, v184
	v_fmac_f32_e32 v192, v148, v176
	v_fma_f32 v184, -v164, v192, v184
	v_div_fmas_f32 v184, v184, v176, v192
	v_div_fixup_f32 v148, v184, v156, 1.0
	v_div_scale_f32 v185, vcc, 1.0, v157, 1.0
	v_mul_f32_e32 v193, v185, v177
	v_fma_f32 v149, -v165, v193, v185
	v_fmac_f32_e32 v193, v149, v177
	v_fma_f32 v185, -v165, v193, v185
	v_div_fmas_f32 v185, v185, v177, v193
	v_div_fixup_f32 v149, v185, v157, 1.0
	v_div_scale_f32 v186, vcc, 1.0, v158, 1.0
	v_mul_f32_e32 v194, v186, v178
	v_fma_f32 v150, -v166, v194, v186
	v_fmac_f32_e32 v194, v150, v178
	v_fma_f32 v186, -v166, v194, v186
	v_div_fmas_f32 v186, v186, v178, v194
	v_div_fixup_f32 v150, v186, v158, 1.0
	v_div_scale_f32 v187, vcc, 1.0, v159, 1.0
	v_mul_f32_e32 v195, v187, v179
	v_fma_f32 v151, -v167, v195, v187
	v_fmac_f32_e32 v195, v151, v179
	v_fma_f32 v187, -v167, v195, v187
	v_div_fmas_f32 v187, v187, v179, v195
	v_div_fixup_f32 v151, v187, v159, 1.0
	v_div_scale_f32 v188, vcc, 1.0, v160, 1.0
	v_mul_f32_e32 v196, v188, v180
	v_fma_f32 v152, -v172, v196, v188
	v_fmac_f32_e32 v196, v152, v180
	v_fma_f32 v188, -v172, v196, v188
	v_div_fmas_f32 v188, v188, v180, v196
	v_div_fixup_f32 v152, v188, v160, 1.0
	v_div_scale_f32 v189, vcc, 1.0, v161, 1.0
	v_mul_f32_e32 v197, v189, v181
	v_fma_f32 v153, -v173, v197, v189
	v_fmac_f32_e32 v197, v153, v181
	v_fma_f32 v189, -v173, v197, v189
	v_div_fmas_f32 v189, v189, v181, v197
	v_div_fixup_f32 v153, v189, v161, 1.0
	v_div_scale_f32 v190, vcc, 1.0, v162, 1.0
	v_mul_f32_e32 v198, v190, v182
	v_fma_f32 v154, -v174, v198, v190
	v_fmac_f32_e32 v198, v154, v182
	v_fma_f32 v190, -v174, v198, v190
	v_div_fmas_f32 v190, v190, v182, v198
	v_div_fixup_f32 v154, v190, v162, 1.0
	v_div_scale_f32 v191, vcc, 1.0, v163, 1.0
	v_mul_f32_e32 v199, v191, v183
	v_fma_f32 v155, -v175, v199, v191
	v_fmac_f32_e32 v199, v155, v183
	v_fma_f32 v191, -v175, v199, v191
	v_div_fmas_f32 v191, v191, v183, v199
	v_div_fixup_f32 v155, v191, v163, 1.0
	v_and_b32_sdwa v208, v148, v242 dst_sel:DWORD dst_unused:UNUSED_PAD src0_sel:WORD_1 src1_sel:DWORD
	v_and_b32_sdwa v209, v149, v242 dst_sel:DWORD dst_unused:UNUSED_PAD src0_sel:WORD_1 src1_sel:DWORD
	v_and_b32_sdwa v210, v150, v242 dst_sel:DWORD dst_unused:UNUSED_PAD src0_sel:WORD_1 src1_sel:DWORD
	v_and_b32_sdwa v211, v151, v242 dst_sel:DWORD dst_unused:UNUSED_PAD src0_sel:WORD_1 src1_sel:DWORD
	v_and_b32_sdwa v212, v152, v242 dst_sel:DWORD dst_unused:UNUSED_PAD src0_sel:WORD_1 src1_sel:DWORD
	v_and_b32_sdwa v213, v153, v242 dst_sel:DWORD dst_unused:UNUSED_PAD src0_sel:WORD_1 src1_sel:DWORD
	v_and_b32_sdwa v214, v154, v242 dst_sel:DWORD dst_unused:UNUSED_PAD src0_sel:WORD_1 src1_sel:DWORD
	v_and_b32_sdwa v215, v155, v242 dst_sel:DWORD dst_unused:UNUSED_PAD src0_sel:WORD_1 src1_sel:DWORD
	v_add3_u32 v148, v148, v208, s3
	v_add3_u32 v149, v149, v209, s3
	v_add3_u32 v150, v150, v210, s3
	v_add3_u32 v151, v151, v211, s3
	v_add3_u32 v152, v152, v212, s3
	v_add3_u32 v153, v153, v213, s3
	v_add3_u32 v154, v154, v214, s3
	v_add3_u32 v155, v155, v215, s3
	v_and_b32_e32 v149, 0xffff0000, v149
	v_and_b32_e32 v151, 0xffff0000, v151
	v_and_b32_e32 v153, 0xffff0000, v153
	v_and_b32_e32 v155, 0xffff0000, v155
	v_or_b32_sdwa v200, v149, v148 dst_sel:DWORD dst_unused:UNUSED_PAD src0_sel:DWORD src1_sel:WORD_1
	v_or_b32_sdwa v201, v151, v150 dst_sel:DWORD dst_unused:UNUSED_PAD src0_sel:DWORD src1_sel:WORD_1
	v_or_b32_sdwa v202, v153, v152 dst_sel:DWORD dst_unused:UNUSED_PAD src0_sel:DWORD src1_sel:WORD_1
	v_or_b32_sdwa v203, v155, v154 dst_sel:DWORD dst_unused:UNUSED_PAD src0_sel:DWORD src1_sel:WORD_1
	global_store_dwordx4 v243, v[200:203], s[84:85]
	s_add_u32 s84, s84, 0x1000
	s_addc_u32 s85, s85, 0
	v_add_f32_e32 v148, v40, v136
	v_add_f32_e32 v149, v41, v137
	v_add_f32_e32 v150, v42, v138
	v_add_f32_e32 v151, v43, v139
	v_add_f32_e32 v152, v44, v140
	v_add_f32_e32 v153, v45, v141
	v_add_f32_e32 v154, v46, v142
	v_add_f32_e32 v155, v47, v143
	v_mul_f32_e32 v148, 0xbfb8aa3b, v148
	v_mul_f32_e32 v149, 0xbfb8aa3b, v149
	v_mul_f32_e32 v150, 0xbfb8aa3b, v150
	v_mul_f32_e32 v151, 0xbfb8aa3b, v151
	v_mul_f32_e32 v152, 0xbfb8aa3b, v152
	v_mul_f32_e32 v153, 0xbfb8aa3b, v153
	v_mul_f32_e32 v154, 0xbfb8aa3b, v154
	v_mul_f32_e32 v155, 0xbfb8aa3b, v155
	v_exp_f32_e32 v156, v148
	v_exp_f32_e32 v157, v149
	v_exp_f32_e32 v158, v150
	v_exp_f32_e32 v159, v151
	v_exp_f32_e32 v160, v152
	v_exp_f32_e32 v161, v153
	v_exp_f32_e32 v162, v154
	v_exp_f32_e32 v163, v155
	v_add_f32_e32 v156, 1.0, v156
	v_add_f32_e32 v157, 1.0, v157
	v_add_f32_e32 v158, 1.0, v158
	v_add_f32_e32 v159, 1.0, v159
	v_add_f32_e32 v160, 1.0, v160
	v_add_f32_e32 v161, 1.0, v161
	v_add_f32_e32 v162, 1.0, v162
	v_add_f32_e32 v163, 1.0, v163
	v_div_scale_f32 v164, s[76:77], v156, v156, 1.0
	v_div_scale_f32 v165, s[76:77], v157, v157, 1.0
	v_div_scale_f32 v166, s[76:77], v158, v158, 1.0
	v_div_scale_f32 v167, s[76:77], v159, v159, 1.0
	v_div_scale_f32 v172, s[76:77], v160, v160, 1.0
	v_div_scale_f32 v173, s[76:77], v161, v161, 1.0
	v_div_scale_f32 v174, s[76:77], v162, v162, 1.0
	v_div_scale_f32 v175, s[76:77], v163, v163, 1.0
	v_rcp_f32_e32 v176, v164
	v_rcp_f32_e32 v177, v165
	v_rcp_f32_e32 v178, v166
	v_rcp_f32_e32 v179, v167
	v_rcp_f32_e32 v180, v172
	v_rcp_f32_e32 v181, v173
	v_rcp_f32_e32 v182, v174
	v_rcp_f32_e32 v183, v175
	v_fma_f32 v148, -v164, v176, 1.0
	v_fma_f32 v149, -v165, v177, 1.0
	v_fma_f32 v150, -v166, v178, 1.0
	v_fma_f32 v151, -v167, v179, 1.0
	v_fma_f32 v152, -v172, v180, 1.0
	v_fma_f32 v153, -v173, v181, 1.0
	v_fma_f32 v154, -v174, v182, 1.0
	v_fma_f32 v155, -v175, v183, 1.0
	v_fmac_f32_e32 v176, v148, v176
	v_fmac_f32_e32 v177, v149, v177
	v_fmac_f32_e32 v178, v150, v178
	v_fmac_f32_e32 v179, v151, v179
	v_fmac_f32_e32 v180, v152, v180
	v_fmac_f32_e32 v181, v153, v181
	v_fmac_f32_e32 v182, v154, v182
	v_fmac_f32_e32 v183, v155, v183
	v_div_scale_f32 v184, vcc, 1.0, v156, 1.0
	v_mul_f32_e32 v192, v184, v176
	v_fma_f32 v148, -v164, v192, v184
	v_fmac_f32_e32 v192, v148, v176
	v_fma_f32 v184, -v164, v192, v184
	v_div_fmas_f32 v184, v184, v176, v192
	v_div_fixup_f32 v148, v184, v156, 1.0
	v_div_scale_f32 v185, vcc, 1.0, v157, 1.0
	v_mul_f32_e32 v193, v185, v177
	v_fma_f32 v149, -v165, v193, v185
	v_fmac_f32_e32 v193, v149, v177
	v_fma_f32 v185, -v165, v193, v185
	v_div_fmas_f32 v185, v185, v177, v193
	v_div_fixup_f32 v149, v185, v157, 1.0
	v_div_scale_f32 v186, vcc, 1.0, v158, 1.0
	v_mul_f32_e32 v194, v186, v178
	v_fma_f32 v150, -v166, v194, v186
	v_fmac_f32_e32 v194, v150, v178
	v_fma_f32 v186, -v166, v194, v186
	v_div_fmas_f32 v186, v186, v178, v194
	v_div_fixup_f32 v150, v186, v158, 1.0
	v_div_scale_f32 v187, vcc, 1.0, v159, 1.0
	v_mul_f32_e32 v195, v187, v179
	v_fma_f32 v151, -v167, v195, v187
	v_fmac_f32_e32 v195, v151, v179
	v_fma_f32 v187, -v167, v195, v187
	v_div_fmas_f32 v187, v187, v179, v195
	v_div_fixup_f32 v151, v187, v159, 1.0
	v_div_scale_f32 v188, vcc, 1.0, v160, 1.0
	v_mul_f32_e32 v196, v188, v180
	v_fma_f32 v152, -v172, v196, v188
	v_fmac_f32_e32 v196, v152, v180
	v_fma_f32 v188, -v172, v196, v188
	v_div_fmas_f32 v188, v188, v180, v196
	v_div_fixup_f32 v152, v188, v160, 1.0
	v_div_scale_f32 v189, vcc, 1.0, v161, 1.0
	v_mul_f32_e32 v197, v189, v181
	v_fma_f32 v153, -v173, v197, v189
	v_fmac_f32_e32 v197, v153, v181
	v_fma_f32 v189, -v173, v197, v189
	v_div_fmas_f32 v189, v189, v181, v197
	v_div_fixup_f32 v153, v189, v161, 1.0
	v_div_scale_f32 v190, vcc, 1.0, v162, 1.0
	v_mul_f32_e32 v198, v190, v182
	v_fma_f32 v154, -v174, v198, v190
	v_fmac_f32_e32 v198, v154, v182
	v_fma_f32 v190, -v174, v198, v190
	v_div_fmas_f32 v190, v190, v182, v198
	v_div_fixup_f32 v154, v190, v162, 1.0
	v_div_scale_f32 v191, vcc, 1.0, v163, 1.0
	v_mul_f32_e32 v199, v191, v183
	v_fma_f32 v155, -v175, v199, v191
	v_fmac_f32_e32 v199, v155, v183
	v_fma_f32 v191, -v175, v199, v191
	v_div_fmas_f32 v191, v191, v183, v199
	v_div_fixup_f32 v155, v191, v163, 1.0
	v_and_b32_sdwa v208, v148, v242 dst_sel:DWORD dst_unused:UNUSED_PAD src0_sel:WORD_1 src1_sel:DWORD
	v_and_b32_sdwa v209, v149, v242 dst_sel:DWORD dst_unused:UNUSED_PAD src0_sel:WORD_1 src1_sel:DWORD
	v_and_b32_sdwa v210, v150, v242 dst_sel:DWORD dst_unused:UNUSED_PAD src0_sel:WORD_1 src1_sel:DWORD
	v_and_b32_sdwa v211, v151, v242 dst_sel:DWORD dst_unused:UNUSED_PAD src0_sel:WORD_1 src1_sel:DWORD
	v_and_b32_sdwa v212, v152, v242 dst_sel:DWORD dst_unused:UNUSED_PAD src0_sel:WORD_1 src1_sel:DWORD
	v_and_b32_sdwa v213, v153, v242 dst_sel:DWORD dst_unused:UNUSED_PAD src0_sel:WORD_1 src1_sel:DWORD
	v_and_b32_sdwa v214, v154, v242 dst_sel:DWORD dst_unused:UNUSED_PAD src0_sel:WORD_1 src1_sel:DWORD
	v_and_b32_sdwa v215, v155, v242 dst_sel:DWORD dst_unused:UNUSED_PAD src0_sel:WORD_1 src1_sel:DWORD
	v_add3_u32 v148, v148, v208, s3
	v_add3_u32 v149, v149, v209, s3
	v_add3_u32 v150, v150, v210, s3
	v_add3_u32 v151, v151, v211, s3
	v_add3_u32 v152, v152, v212, s3
	v_add3_u32 v153, v153, v213, s3
	v_add3_u32 v154, v154, v214, s3
	v_add3_u32 v155, v155, v215, s3
	v_and_b32_e32 v149, 0xffff0000, v149
	v_and_b32_e32 v151, 0xffff0000, v151
	v_and_b32_e32 v153, 0xffff0000, v153
	v_and_b32_e32 v155, 0xffff0000, v155
	v_or_b32_sdwa v204, v149, v148 dst_sel:DWORD dst_unused:UNUSED_PAD src0_sel:DWORD src1_sel:WORD_1
	v_or_b32_sdwa v205, v151, v150 dst_sel:DWORD dst_unused:UNUSED_PAD src0_sel:DWORD src1_sel:WORD_1
	v_or_b32_sdwa v206, v153, v152 dst_sel:DWORD dst_unused:UNUSED_PAD src0_sel:DWORD src1_sel:WORD_1
	v_or_b32_sdwa v207, v155, v154 dst_sel:DWORD dst_unused:UNUSED_PAD src0_sel:DWORD src1_sel:WORD_1
	global_store_dwordx4 v243, v[204:207], s[84:85]
	s_add_u32 s84, s84, 0x1000
	s_addc_u32 s85, s85, 0
	v_add_f32_e32 v148, v48, v128
	v_add_f32_e32 v149, v49, v129
	v_add_f32_e32 v150, v50, v130
	v_add_f32_e32 v151, v51, v131
	v_add_f32_e32 v152, v52, v132
	v_add_f32_e32 v153, v53, v133
	v_add_f32_e32 v154, v54, v134
	v_add_f32_e32 v155, v55, v135
	v_mul_f32_e32 v148, 0xbfb8aa3b, v148
	v_mul_f32_e32 v149, 0xbfb8aa3b, v149
	v_mul_f32_e32 v150, 0xbfb8aa3b, v150
	v_mul_f32_e32 v151, 0xbfb8aa3b, v151
	v_mul_f32_e32 v152, 0xbfb8aa3b, v152
	v_mul_f32_e32 v153, 0xbfb8aa3b, v153
	v_mul_f32_e32 v154, 0xbfb8aa3b, v154
	v_mul_f32_e32 v155, 0xbfb8aa3b, v155
	v_exp_f32_e32 v156, v148
	v_exp_f32_e32 v157, v149
	v_exp_f32_e32 v158, v150
	v_exp_f32_e32 v159, v151
	v_exp_f32_e32 v160, v152
	v_exp_f32_e32 v161, v153
	v_exp_f32_e32 v162, v154
	v_exp_f32_e32 v163, v155
	v_add_f32_e32 v156, 1.0, v156
	v_add_f32_e32 v157, 1.0, v157
	v_add_f32_e32 v158, 1.0, v158
	v_add_f32_e32 v159, 1.0, v159
	v_add_f32_e32 v160, 1.0, v160
	v_add_f32_e32 v161, 1.0, v161
	v_add_f32_e32 v162, 1.0, v162
	v_add_f32_e32 v163, 1.0, v163
	v_div_scale_f32 v164, s[76:77], v156, v156, 1.0
	v_div_scale_f32 v165, s[76:77], v157, v157, 1.0
	v_div_scale_f32 v166, s[76:77], v158, v158, 1.0
	v_div_scale_f32 v167, s[76:77], v159, v159, 1.0
	v_div_scale_f32 v172, s[76:77], v160, v160, 1.0
	v_div_scale_f32 v173, s[76:77], v161, v161, 1.0
	v_div_scale_f32 v174, s[76:77], v162, v162, 1.0
	v_div_scale_f32 v175, s[76:77], v163, v163, 1.0
	v_rcp_f32_e32 v176, v164
	v_rcp_f32_e32 v177, v165
	v_rcp_f32_e32 v178, v166
	v_rcp_f32_e32 v179, v167
	v_rcp_f32_e32 v180, v172
	v_rcp_f32_e32 v181, v173
	v_rcp_f32_e32 v182, v174
	v_rcp_f32_e32 v183, v175
	v_fma_f32 v148, -v164, v176, 1.0
	v_fma_f32 v149, -v165, v177, 1.0
	v_fma_f32 v150, -v166, v178, 1.0
	v_fma_f32 v151, -v167, v179, 1.0
	v_fma_f32 v152, -v172, v180, 1.0
	v_fma_f32 v153, -v173, v181, 1.0
	v_fma_f32 v154, -v174, v182, 1.0
	v_fma_f32 v155, -v175, v183, 1.0
	v_fmac_f32_e32 v176, v148, v176
	v_fmac_f32_e32 v177, v149, v177
	v_fmac_f32_e32 v178, v150, v178
	v_fmac_f32_e32 v179, v151, v179
	v_fmac_f32_e32 v180, v152, v180
	v_fmac_f32_e32 v181, v153, v181
	v_fmac_f32_e32 v182, v154, v182
	v_fmac_f32_e32 v183, v155, v183
	v_div_scale_f32 v184, vcc, 1.0, v156, 1.0
	v_mul_f32_e32 v192, v184, v176
	v_fma_f32 v148, -v164, v192, v184
	v_fmac_f32_e32 v192, v148, v176
	v_fma_f32 v184, -v164, v192, v184
	v_div_fmas_f32 v184, v184, v176, v192
	v_div_fixup_f32 v148, v184, v156, 1.0
	v_div_scale_f32 v185, vcc, 1.0, v157, 1.0
	v_mul_f32_e32 v193, v185, v177
	v_fma_f32 v149, -v165, v193, v185
	v_fmac_f32_e32 v193, v149, v177
	v_fma_f32 v185, -v165, v193, v185
	v_div_fmas_f32 v185, v185, v177, v193
	v_div_fixup_f32 v149, v185, v157, 1.0
	v_div_scale_f32 v186, vcc, 1.0, v158, 1.0
	v_mul_f32_e32 v194, v186, v178
	v_fma_f32 v150, -v166, v194, v186
	v_fmac_f32_e32 v194, v150, v178
	v_fma_f32 v186, -v166, v194, v186
	v_div_fmas_f32 v186, v186, v178, v194
	v_div_fixup_f32 v150, v186, v158, 1.0
	v_div_scale_f32 v187, vcc, 1.0, v159, 1.0
	v_mul_f32_e32 v195, v187, v179
	v_fma_f32 v151, -v167, v195, v187
	v_fmac_f32_e32 v195, v151, v179
	v_fma_f32 v187, -v167, v195, v187
	v_div_fmas_f32 v187, v187, v179, v195
	v_div_fixup_f32 v151, v187, v159, 1.0
	v_div_scale_f32 v188, vcc, 1.0, v160, 1.0
	v_mul_f32_e32 v196, v188, v180
	v_fma_f32 v152, -v172, v196, v188
	v_fmac_f32_e32 v196, v152, v180
	v_fma_f32 v188, -v172, v196, v188
	v_div_fmas_f32 v188, v188, v180, v196
	v_div_fixup_f32 v152, v188, v160, 1.0
	v_div_scale_f32 v189, vcc, 1.0, v161, 1.0
	v_mul_f32_e32 v197, v189, v181
	v_fma_f32 v153, -v173, v197, v189
	v_fmac_f32_e32 v197, v153, v181
	v_fma_f32 v189, -v173, v197, v189
	v_div_fmas_f32 v189, v189, v181, v197
	v_div_fixup_f32 v153, v189, v161, 1.0
	v_div_scale_f32 v190, vcc, 1.0, v162, 1.0
	v_mul_f32_e32 v198, v190, v182
	v_fma_f32 v154, -v174, v198, v190
	v_fmac_f32_e32 v198, v154, v182
	v_fma_f32 v190, -v174, v198, v190
	v_div_fmas_f32 v190, v190, v182, v198
	v_div_fixup_f32 v154, v190, v162, 1.0
	v_div_scale_f32 v191, vcc, 1.0, v163, 1.0
	v_mul_f32_e32 v199, v191, v183
	v_fma_f32 v155, -v175, v199, v191
	v_fmac_f32_e32 v199, v155, v183
	v_fma_f32 v191, -v175, v199, v191
	v_div_fmas_f32 v191, v191, v183, v199
	v_div_fixup_f32 v155, v191, v163, 1.0
	v_and_b32_sdwa v208, v148, v242 dst_sel:DWORD dst_unused:UNUSED_PAD src0_sel:WORD_1 src1_sel:DWORD
	v_and_b32_sdwa v209, v149, v242 dst_sel:DWORD dst_unused:UNUSED_PAD src0_sel:WORD_1 src1_sel:DWORD
	v_and_b32_sdwa v210, v150, v242 dst_sel:DWORD dst_unused:UNUSED_PAD src0_sel:WORD_1 src1_sel:DWORD
	v_and_b32_sdwa v211, v151, v242 dst_sel:DWORD dst_unused:UNUSED_PAD src0_sel:WORD_1 src1_sel:DWORD
	v_and_b32_sdwa v212, v152, v242 dst_sel:DWORD dst_unused:UNUSED_PAD src0_sel:WORD_1 src1_sel:DWORD
	v_and_b32_sdwa v213, v153, v242 dst_sel:DWORD dst_unused:UNUSED_PAD src0_sel:WORD_1 src1_sel:DWORD
	v_and_b32_sdwa v214, v154, v242 dst_sel:DWORD dst_unused:UNUSED_PAD src0_sel:WORD_1 src1_sel:DWORD
	v_and_b32_sdwa v215, v155, v242 dst_sel:DWORD dst_unused:UNUSED_PAD src0_sel:WORD_1 src1_sel:DWORD
	v_add3_u32 v148, v148, v208, s3
	v_add3_u32 v149, v149, v209, s3
	v_add3_u32 v150, v150, v210, s3
	v_add3_u32 v151, v151, v211, s3
	v_add3_u32 v152, v152, v212, s3
	v_add3_u32 v153, v153, v213, s3
	v_add3_u32 v154, v154, v214, s3
	v_add3_u32 v155, v155, v215, s3
	v_and_b32_e32 v149, 0xffff0000, v149
	v_and_b32_e32 v151, 0xffff0000, v151
	v_and_b32_e32 v153, 0xffff0000, v153
	v_and_b32_e32 v155, 0xffff0000, v155
	v_or_b32_sdwa v200, v149, v148 dst_sel:DWORD dst_unused:UNUSED_PAD src0_sel:DWORD src1_sel:WORD_1
	v_or_b32_sdwa v201, v151, v150 dst_sel:DWORD dst_unused:UNUSED_PAD src0_sel:DWORD src1_sel:WORD_1
	v_or_b32_sdwa v202, v153, v152 dst_sel:DWORD dst_unused:UNUSED_PAD src0_sel:DWORD src1_sel:WORD_1
	v_or_b32_sdwa v203, v155, v154 dst_sel:DWORD dst_unused:UNUSED_PAD src0_sel:DWORD src1_sel:WORD_1
	global_store_dwordx4 v243, v[200:203], s[84:85]
	s_add_u32 s84, s84, 0x1000
	s_addc_u32 s85, s85, 0
	v_add_f32_e32 v148, v56, v136
	v_add_f32_e32 v149, v57, v137
	v_add_f32_e32 v150, v58, v138
	v_add_f32_e32 v151, v59, v139
	v_add_f32_e32 v152, v60, v140
	v_add_f32_e32 v153, v61, v141
	v_add_f32_e32 v154, v62, v142
	v_add_f32_e32 v155, v63, v143
	v_mul_f32_e32 v148, 0xbfb8aa3b, v148
	v_mul_f32_e32 v149, 0xbfb8aa3b, v149
	v_mul_f32_e32 v150, 0xbfb8aa3b, v150
	v_mul_f32_e32 v151, 0xbfb8aa3b, v151
	v_mul_f32_e32 v152, 0xbfb8aa3b, v152
	v_mul_f32_e32 v153, 0xbfb8aa3b, v153
	v_mul_f32_e32 v154, 0xbfb8aa3b, v154
	v_mul_f32_e32 v155, 0xbfb8aa3b, v155
	v_exp_f32_e32 v156, v148
	v_exp_f32_e32 v157, v149
	v_exp_f32_e32 v158, v150
	v_exp_f32_e32 v159, v151
	v_exp_f32_e32 v160, v152
	v_exp_f32_e32 v161, v153
	v_exp_f32_e32 v162, v154
	v_exp_f32_e32 v163, v155
	v_add_f32_e32 v156, 1.0, v156
	v_add_f32_e32 v157, 1.0, v157
	v_add_f32_e32 v158, 1.0, v158
	v_add_f32_e32 v159, 1.0, v159
	v_add_f32_e32 v160, 1.0, v160
	v_add_f32_e32 v161, 1.0, v161
	v_add_f32_e32 v162, 1.0, v162
	v_add_f32_e32 v163, 1.0, v163
	v_div_scale_f32 v164, s[76:77], v156, v156, 1.0
	v_div_scale_f32 v165, s[76:77], v157, v157, 1.0
	v_div_scale_f32 v166, s[76:77], v158, v158, 1.0
	v_div_scale_f32 v167, s[76:77], v159, v159, 1.0
	v_div_scale_f32 v172, s[76:77], v160, v160, 1.0
	v_div_scale_f32 v173, s[76:77], v161, v161, 1.0
	v_div_scale_f32 v174, s[76:77], v162, v162, 1.0
	v_div_scale_f32 v175, s[76:77], v163, v163, 1.0
	v_rcp_f32_e32 v176, v164
	v_rcp_f32_e32 v177, v165
	v_rcp_f32_e32 v178, v166
	v_rcp_f32_e32 v179, v167
	v_rcp_f32_e32 v180, v172
	v_rcp_f32_e32 v181, v173
	v_rcp_f32_e32 v182, v174
	v_rcp_f32_e32 v183, v175
	v_fma_f32 v148, -v164, v176, 1.0
	v_fma_f32 v149, -v165, v177, 1.0
	v_fma_f32 v150, -v166, v178, 1.0
	v_fma_f32 v151, -v167, v179, 1.0
	v_fma_f32 v152, -v172, v180, 1.0
	v_fma_f32 v153, -v173, v181, 1.0
	v_fma_f32 v154, -v174, v182, 1.0
	v_fma_f32 v155, -v175, v183, 1.0
	v_fmac_f32_e32 v176, v148, v176
	v_fmac_f32_e32 v177, v149, v177
	v_fmac_f32_e32 v178, v150, v178
	v_fmac_f32_e32 v179, v151, v179
	v_fmac_f32_e32 v180, v152, v180
	v_fmac_f32_e32 v181, v153, v181
	v_fmac_f32_e32 v182, v154, v182
	v_fmac_f32_e32 v183, v155, v183
	v_div_scale_f32 v184, vcc, 1.0, v156, 1.0
	v_mul_f32_e32 v192, v184, v176
	v_fma_f32 v148, -v164, v192, v184
	v_fmac_f32_e32 v192, v148, v176
	v_fma_f32 v184, -v164, v192, v184
	v_div_fmas_f32 v184, v184, v176, v192
	v_div_fixup_f32 v148, v184, v156, 1.0
	v_div_scale_f32 v185, vcc, 1.0, v157, 1.0
	v_mul_f32_e32 v193, v185, v177
	v_fma_f32 v149, -v165, v193, v185
	v_fmac_f32_e32 v193, v149, v177
	v_fma_f32 v185, -v165, v193, v185
	v_div_fmas_f32 v185, v185, v177, v193
	v_div_fixup_f32 v149, v185, v157, 1.0
	v_div_scale_f32 v186, vcc, 1.0, v158, 1.0
	v_mul_f32_e32 v194, v186, v178
	v_fma_f32 v150, -v166, v194, v186
	v_fmac_f32_e32 v194, v150, v178
	v_fma_f32 v186, -v166, v194, v186
	v_div_fmas_f32 v186, v186, v178, v194
	v_div_fixup_f32 v150, v186, v158, 1.0
	v_div_scale_f32 v187, vcc, 1.0, v159, 1.0
	v_mul_f32_e32 v195, v187, v179
	v_fma_f32 v151, -v167, v195, v187
	v_fmac_f32_e32 v195, v151, v179
	v_fma_f32 v187, -v167, v195, v187
	v_div_fmas_f32 v187, v187, v179, v195
	v_div_fixup_f32 v151, v187, v159, 1.0
	v_div_scale_f32 v188, vcc, 1.0, v160, 1.0
	v_mul_f32_e32 v196, v188, v180
	v_fma_f32 v152, -v172, v196, v188
	v_fmac_f32_e32 v196, v152, v180
	v_fma_f32 v188, -v172, v196, v188
	v_div_fmas_f32 v188, v188, v180, v196
	v_div_fixup_f32 v152, v188, v160, 1.0
	v_div_scale_f32 v189, vcc, 1.0, v161, 1.0
	v_mul_f32_e32 v197, v189, v181
	v_fma_f32 v153, -v173, v197, v189
	v_fmac_f32_e32 v197, v153, v181
	v_fma_f32 v189, -v173, v197, v189
	v_div_fmas_f32 v189, v189, v181, v197
	v_div_fixup_f32 v153, v189, v161, 1.0
	v_div_scale_f32 v190, vcc, 1.0, v162, 1.0
	v_mul_f32_e32 v198, v190, v182
	v_fma_f32 v154, -v174, v198, v190
	v_fmac_f32_e32 v198, v154, v182
	v_fma_f32 v190, -v174, v198, v190
	v_div_fmas_f32 v190, v190, v182, v198
	v_div_fixup_f32 v154, v190, v162, 1.0
	v_div_scale_f32 v191, vcc, 1.0, v163, 1.0
	v_mul_f32_e32 v199, v191, v183
	v_fma_f32 v155, -v175, v199, v191
	v_fmac_f32_e32 v199, v155, v183
	v_fma_f32 v191, -v175, v199, v191
	v_div_fmas_f32 v191, v191, v183, v199
	v_div_fixup_f32 v155, v191, v163, 1.0
	v_and_b32_sdwa v208, v148, v242 dst_sel:DWORD dst_unused:UNUSED_PAD src0_sel:WORD_1 src1_sel:DWORD
	v_and_b32_sdwa v209, v149, v242 dst_sel:DWORD dst_unused:UNUSED_PAD src0_sel:WORD_1 src1_sel:DWORD
	v_and_b32_sdwa v210, v150, v242 dst_sel:DWORD dst_unused:UNUSED_PAD src0_sel:WORD_1 src1_sel:DWORD
	v_and_b32_sdwa v211, v151, v242 dst_sel:DWORD dst_unused:UNUSED_PAD src0_sel:WORD_1 src1_sel:DWORD
	v_and_b32_sdwa v212, v152, v242 dst_sel:DWORD dst_unused:UNUSED_PAD src0_sel:WORD_1 src1_sel:DWORD
	v_and_b32_sdwa v213, v153, v242 dst_sel:DWORD dst_unused:UNUSED_PAD src0_sel:WORD_1 src1_sel:DWORD
	v_and_b32_sdwa v214, v154, v242 dst_sel:DWORD dst_unused:UNUSED_PAD src0_sel:WORD_1 src1_sel:DWORD
	v_and_b32_sdwa v215, v155, v242 dst_sel:DWORD dst_unused:UNUSED_PAD src0_sel:WORD_1 src1_sel:DWORD
	v_add3_u32 v148, v148, v208, s3
	v_add3_u32 v149, v149, v209, s3
	v_add3_u32 v150, v150, v210, s3
	v_add3_u32 v151, v151, v211, s3
	v_add3_u32 v152, v152, v212, s3
	v_add3_u32 v153, v153, v213, s3
	v_add3_u32 v154, v154, v214, s3
	v_add3_u32 v155, v155, v215, s3
	v_and_b32_e32 v149, 0xffff0000, v149
	v_and_b32_e32 v151, 0xffff0000, v151
	v_and_b32_e32 v153, 0xffff0000, v153
	v_and_b32_e32 v155, 0xffff0000, v155
	v_or_b32_sdwa v204, v149, v148 dst_sel:DWORD dst_unused:UNUSED_PAD src0_sel:DWORD src1_sel:WORD_1
	v_or_b32_sdwa v205, v151, v150 dst_sel:DWORD dst_unused:UNUSED_PAD src0_sel:DWORD src1_sel:WORD_1
	v_or_b32_sdwa v206, v153, v152 dst_sel:DWORD dst_unused:UNUSED_PAD src0_sel:DWORD src1_sel:WORD_1
	v_or_b32_sdwa v207, v155, v154 dst_sel:DWORD dst_unused:UNUSED_PAD src0_sel:DWORD src1_sel:WORD_1
	global_store_dwordx4 v243, v[204:207], s[84:85]
	s_add_u32 s84, s84, 0x1000
	s_addc_u32 s85, s85, 0
	s_cmp_eq_u32 s83, 1
	s_cbranch_scc1 .Lp6a_epdone
	s_cmp_eq_u32 s95, 1
	s_cbranch_scc0 .Lp6a_epdone
	v_mov_b32_e32 v0, v64
	v_mov_b32_e32 v1, v65
	v_mov_b32_e32 v2, v66
	v_mov_b32_e32 v3, v67
	v_mov_b32_e32 v4, v68
	v_mov_b32_e32 v5, v69
	v_mov_b32_e32 v6, v70
	v_mov_b32_e32 v7, v71
	v_mov_b32_e32 v8, v72
	v_mov_b32_e32 v9, v73
	v_mov_b32_e32 v10, v74
	v_mov_b32_e32 v11, v75
	v_mov_b32_e32 v12, v76
	v_mov_b32_e32 v13, v77
	v_mov_b32_e32 v14, v78
	v_mov_b32_e32 v15, v79
	v_mov_b32_e32 v16, v80
	v_mov_b32_e32 v17, v81
	v_mov_b32_e32 v18, v82
	v_mov_b32_e32 v19, v83
	v_mov_b32_e32 v20, v84
	v_mov_b32_e32 v21, v85
	v_mov_b32_e32 v22, v86
	v_mov_b32_e32 v23, v87
	v_mov_b32_e32 v24, v88
	v_mov_b32_e32 v25, v89
	v_mov_b32_e32 v26, v90
	v_mov_b32_e32 v27, v91
	v_mov_b32_e32 v28, v92
	v_mov_b32_e32 v29, v93
	v_mov_b32_e32 v30, v94
	v_mov_b32_e32 v31, v95
	v_mov_b32_e32 v32, v96
	v_mov_b32_e32 v33, v97
	v_mov_b32_e32 v34, v98
	v_mov_b32_e32 v35, v99
	v_mov_b32_e32 v36, v100
	v_mov_b32_e32 v37, v101
	v_mov_b32_e32 v38, v102
	v_mov_b32_e32 v39, v103
	v_mov_b32_e32 v40, v104
	v_mov_b32_e32 v41, v105
	v_mov_b32_e32 v42, v106
	v_mov_b32_e32 v43, v107
	v_mov_b32_e32 v44, v108
	v_mov_b32_e32 v45, v109
	v_mov_b32_e32 v46, v110
	v_mov_b32_e32 v47, v111
	v_mov_b32_e32 v48, v112
	v_mov_b32_e32 v49, v113
	v_mov_b32_e32 v50, v114
	v_mov_b32_e32 v51, v115
	v_mov_b32_e32 v52, v116
	v_mov_b32_e32 v53, v117
	v_mov_b32_e32 v54, v118
	v_mov_b32_e32 v55, v119
	v_mov_b32_e32 v56, v120
	v_mov_b32_e32 v57, v121
	v_mov_b32_e32 v58, v122
	v_mov_b32_e32 v59, v123
	v_mov_b32_e32 v60, v124
	v_mov_b32_e32 v61, v125
	v_mov_b32_e32 v62, v126
	v_mov_b32_e32 v63, v127
	s_mov_b32 s83, 1
	s_branch .Lp6a_ep
.Lp6a_epdone:
	v_lshrrev_b32_e32 v236, 3, v168
	v_lshrrev_b32_e32 v237, 4, v168
	v_xor_b32_e32 v237, v237, v168
	v_and_b32_e32 v237, 7, v237
	v_lshlrev_b32_e32 v237, 4, v237
	v_lshl_or_b32 v232, v236, 11, v237
	v_add_u32_e32 v233, 0x10000, v232
	v_add_u32_e32 v234, 0x20000, v232
	v_add_u32_e32 v235, 0x30000, v232
	s_load_dwordx2 s[90:91], s[0:1], 0xa0
	s_load_dwordx2 s[92:93], s[0:1], 0xb0
	v_lshrrev_b32_e32 v237, 6, v168
	s_nop 1
	v_readfirstlane_b32 s97, v237
	s_nop 3
	s_lshl_b32 s96, s97, 10
	s_add_u32 s96, s96, 16
	s_add_u32 s94, s81, s80
	s_cmp_lt_i32 s94, s82
	s_cselect_b32 s95, 1, 0
	s_cmp_lg_u64 s[20:21], 0
	s_cselect_b32 s95, 0, s95
	s_cmp_ge_u32 s94, 0x40
	s_cselect_b32 s97, 1, 0
	s_mul_i32 s100, s97, 0x40
	s_sub_u32 s100, s94, s100
	s_lshr_b32 s101, s100, 3
	s_and_b32 s100, s100, 7
	s_lshl_b32 s97, s97, 3
	s_add_u32 s100, s100, s97
	s_add_u32 s100, s100, s79
	s_cmp_lg_u32 s101, s74
	s_cselect_b32 s95, 0, s95
	s_cmp_eq_u32 s95, 1
	s_cselect_b32 s101, s100, s70
	s_mov_b32 s97, s101
	s_waitcnt lgkmcnt(0)
	s_lshl_b32 s94, s74, 18
	s_add_u32 s98, s92, s94
	s_addc_u32 s99, s93, 0
	s_lshl_b32 s101, s101, 18
	s_add_u32 s101, s101, 0x2000000
	s_add_u32 s92, s90, s101
	s_addc_u32 s93, s91, 0
	s_lshl_b32 s94, s70, 18
	s_add_u32 s94, s94, 0x2000000
	s_add_u32 s90, s90, s94
	s_addc_u32 s91, s91, 0
	s_waitcnt vmcnt(0)
	s_barrier
	s_add_u32 m0, s96, 0x0
	s_nop 0
	global_load_lds_dwordx4 v232, s[90:91]
	s_add_u32 m0, s96, 0x1000
	s_nop 0
	global_load_lds_dwordx4 v233, s[90:91]
	s_add_u32 m0, s96, 0x2000
	s_nop 0
	global_load_lds_dwordx4 v234, s[90:91]
	s_add_u32 m0, s96, 0x3000
	s_nop 0
	global_load_lds_dwordx4 v235, s[90:91]
	s_add_u32 m0, s96, 0x4000
	s_nop 0
	global_load_lds_dwordx4 v232, s[92:93]
	s_add_u32 m0, s96, 0x5000
	s_nop 0
	global_load_lds_dwordx4 v233, s[92:93]
	s_add_u32 m0, s96, 0x6000
	s_nop 0
	global_load_lds_dwordx4 v234, s[92:93]
	s_add_u32 m0, s96, 0x7000
	s_nop 0
	global_load_lds_dwordx4 v235, s[92:93]
	s_add_u32 m0, s96, 0x8000
	s_nop 0
	global_load_lds_dwordx4 v232, s[98:99]
	s_add_u32 m0, s96, 0x9000
	s_nop 0
	global_load_lds_dwordx4 v233, s[98:99]
	s_add_u32 m0, s96, 0xa000
	s_nop 0
	global_load_lds_dwordx4 v234, s[98:99]
	s_add_u32 m0, s96, 0xb000
	s_nop 0
	global_load_lds_dwordx4 v235, s[98:99]
	s_add_u32 s90, s90, 0x80
	s_addc_u32 s91, s91, 0
	s_add_u32 s92, s92, 0x80
	s_addc_u32 s93, s93, 0
	s_add_u32 s98, s98, 0x80
	s_addc_u32 s99, s99, 0
	v_mov_b32_e32 v0, 0
	v_mov_b32_e32 v1, v0
	v_mov_b32_e32 v2, v0
	v_mov_b32_e32 v3, v0
	v_mov_b32_e32 v4, v0
	v_mov_b32_e32 v5, v0
	v_mov_b32_e32 v6, v0
	v_mov_b32_e32 v7, v0
	v_mov_b32_e32 v8, v0
	v_mov_b32_e32 v9, v0
	v_mov_b32_e32 v10, v0
	v_mov_b32_e32 v11, v0
	v_mov_b32_e32 v12, v0
	v_mov_b32_e32 v13, v0
	v_mov_b32_e32 v14, v0
	v_mov_b32_e32 v15, v0
	v_mov_b32_e32 v16, v0
	v_mov_b32_e32 v17, v0
	v_mov_b32_e32 v18, v0
	v_mov_b32_e32 v19, v0
	v_mov_b32_e32 v20, v0
	v_mov_b32_e32 v21, v0
	v_mov_b32_e32 v22, v0
	v_mov_b32_e32 v23, v0
	v_mov_b32_e32 v24, v0
	v_mov_b32_e32 v25, v0
	v_mov_b32_e32 v26, v0
	v_mov_b32_e32 v27, v0
	v_mov_b32_e32 v28, v0
	v_mov_b32_e32 v29, v0
	v_mov_b32_e32 v30, v0
	v_mov_b32_e32 v31, v0
	v_mov_b32_e32 v32, v0
	v_mov_b32_e32 v33, v0
	v_mov_b32_e32 v34, v0
	v_mov_b32_e32 v35, v0
	v_mov_b32_e32 v36, v0
	v_mov_b32_e32 v37, v0
	v_mov_b32_e32 v38, v0
	v_mov_b32_e32 v39, v0
	v_mov_b32_e32 v40, v0
	v_mov_b32_e32 v41, v0
	v_mov_b32_e32 v42, v0
	v_mov_b32_e32 v43, v0
	v_mov_b32_e32 v44, v0
	v_mov_b32_e32 v45, v0
	v_mov_b32_e32 v46, v0
	v_mov_b32_e32 v47, v0
	v_mov_b32_e32 v48, v0
	v_mov_b32_e32 v49, v0
	v_mov_b32_e32 v50, v0
	v_mov_b32_e32 v51, v0
	v_mov_b32_e32 v52, v0
	v_mov_b32_e32 v53, v0
	v_mov_b32_e32 v54, v0
	v_mov_b32_e32 v55, v0
	v_mov_b32_e32 v56, v0
	v_mov_b32_e32 v57, v0
	v_mov_b32_e32 v58, v0
	v_mov_b32_e32 v59, v0
	v_mov_b32_e32 v60, v0
	v_mov_b32_e32 v61, v0
	v_mov_b32_e32 v62, v0
	v_mov_b32_e32 v63, v0
	v_mov_b32_e32 v64, v0
	v_mov_b32_e32 v65, v0
	v_mov_b32_e32 v66, v0
	v_mov_b32_e32 v67, v0
	v_mov_b32_e32 v68, v0
	v_mov_b32_e32 v69, v0
	v_mov_b32_e32 v70, v0
	v_mov_b32_e32 v71, v0
	v_mov_b32_e32 v72, v0
	v_mov_b32_e32 v73, v0
	v_mov_b32_e32 v74, v0
	v_mov_b32_e32 v75, v0
	v_mov_b32_e32 v76, v0
	v_mov_b32_e32 v77, v0
	v_mov_b32_e32 v78, v0
	v_mov_b32_e32 v79, v0
	v_mov_b32_e32 v80, v0
	v_mov_b32_e32 v81, v0
	v_mov_b32_e32 v82, v0
	v_mov_b32_e32 v83, v0
	v_mov_b32_e32 v84, v0
	v_mov_b32_e32 v85, v0
	v_mov_b32_e32 v86, v0
	v_mov_b32_e32 v87, v0
	v_mov_b32_e32 v88, v0
	v_mov_b32_e32 v89, v0
	v_mov_b32_e32 v90, v0
	v_mov_b32_e32 v91, v0
	v_mov_b32_e32 v92, v0
	v_mov_b32_e32 v93, v0
	v_mov_b32_e32 v94, v0
	v_mov_b32_e32 v95, v0
	v_mov_b32_e32 v96, v0
	v_mov_b32_e32 v97, v0
	v_mov_b32_e32 v98, v0
	v_mov_b32_e32 v99, v0
	v_mov_b32_e32 v100, v0
	v_mov_b32_e32 v101, v0
	v_mov_b32_e32 v102, v0
	v_mov_b32_e32 v103, v0
	v_mov_b32_e32 v104, v0
	v_mov_b32_e32 v105, v0
	v_mov_b32_e32 v106, v0
	v_mov_b32_e32 v107, v0
	v_mov_b32_e32 v108, v0
	v_mov_b32_e32 v109, v0
	v_mov_b32_e32 v110, v0
	v_mov_b32_e32 v111, v0
	v_mov_b32_e32 v112, v0
	v_mov_b32_e32 v113, v0
	v_mov_b32_e32 v114, v0
	v_mov_b32_e32 v115, v0
	v_mov_b32_e32 v116, v0
	v_mov_b32_e32 v117, v0
	v_mov_b32_e32 v118, v0
	v_mov_b32_e32 v119, v0
	v_mov_b32_e32 v120, v0
	v_mov_b32_e32 v121, v0
	v_mov_b32_e32 v122, v0
	v_mov_b32_e32 v123, v0
	v_mov_b32_e32 v124, v0
	v_mov_b32_e32 v125, v0
	v_mov_b32_e32 v126, v0
	v_mov_b32_e32 v127, v0
	s_mov_b32 s94, 0

.Lp6b_ep:
	s_lshl_b32 s71, s83, 25
	s_add_u32 s86, s24, s71
	s_addc_u32 s87, s25, 0
	s_lshl_b32 s71, s83, 25
	s_add_u32 s84, s24, s71
	s_addc_u32 s85, s25, 0
	global_load_dwordx4 v[128:131], v243, s[86:87]
	s_add_u32 s86, s86, 0x1000
	s_addc_u32 s87, s87, 0
	global_load_dwordx4 v[132:135], v243, s[86:87]
	s_add_u32 s86, s86, 0x1000
	s_addc_u32 s87, s87, 0
	global_load_dwordx4 v[136:139], v243, s[86:87]
	s_add_u32 s86, s86, 0x1000
	s_addc_u32 s87, s87, 0
	global_load_dwordx4 v[140:143], v243, s[86:87]
	s_add_u32 s86, s86, 0x1000
	s_addc_u32 s87, s87, 0
	global_load_dwordx4 v[148:151], v243, s[86:87]
	s_add_u32 s86, s86, 0x1000
	s_addc_u32 s87, s87, 0
	global_load_dwordx4 v[152:155], v243, s[86:87]
	s_add_u32 s86, s86, 0x1000
	s_addc_u32 s87, s87, 0
	global_load_dwordx4 v[156:159], v243, s[86:87]
	s_add_u32 s86, s86, 0x1000
	s_addc_u32 s87, s87, 0
	global_load_dwordx4 v[160:163], v243, s[86:87]
	s_add_u32 s86, s86, 0x1000
	s_addc_u32 s87, s87, 0
	s_waitcnt vmcnt(7)
	v_lshlrev_b32_e32 v164, 16, v128
	v_and_b32_e32 v165, 0xffff0000, v128
	v_lshlrev_b32_e32 v166, 16, v129
	v_and_b32_e32 v167, 0xffff0000, v129
	v_lshlrev_b32_e32 v172, 16, v130
	v_and_b32_e32 v173, 0xffff0000, v130
	v_lshlrev_b32_e32 v174, 16, v131
	v_and_b32_e32 v175, 0xffff0000, v131
	v_mul_f32_e32 v164, v0, v164
	v_mul_f32_e32 v165, v1, v165
	v_mul_f32_e32 v166, v2, v166
	v_mul_f32_e32 v167, v3, v167
	v_mul_f32_e32 v172, v4, v172
	v_mul_f32_e32 v173, v5, v173
	v_mul_f32_e32 v174, v6, v174
	v_mul_f32_e32 v175, v7, v175
	v_and_b32_sdwa v176, v164, v242 dst_sel:DWORD dst_unused:UNUSED_PAD src0_sel:WORD_1 src1_sel:DWORD
	v_and_b32_sdwa v177, v165, v242 dst_sel:DWORD dst_unused:UNUSED_PAD src0_sel:WORD_1 src1_sel:DWORD
	v_and_b32_sdwa v178, v166, v242 dst_sel:DWORD dst_unused:UNUSED_PAD src0_sel:WORD_1 src1_sel:DWORD
	v_and_b32_sdwa v179, v167, v242 dst_sel:DWORD dst_unused:UNUSED_PAD src0_sel:WORD_1 src1_sel:DWORD
	v_and_b32_sdwa v180, v172, v242 dst_sel:DWORD dst_unused:UNUSED_PAD src0_sel:WORD_1 src1_sel:DWORD
	v_and_b32_sdwa v181, v173, v242 dst_sel:DWORD dst_unused:UNUSED_PAD src0_sel:WORD_1 src1_sel:DWORD
	v_and_b32_sdwa v182, v174, v242 dst_sel:DWORD dst_unused:UNUSED_PAD src0_sel:WORD_1 src1_sel:DWORD
	v_and_b32_sdwa v183, v175, v242 dst_sel:DWORD dst_unused:UNUSED_PAD src0_sel:WORD_1 src1_sel:DWORD
	v_add3_u32 v164, v164, v176, s3
	v_add3_u32 v165, v165, v177, s3
	v_add3_u32 v166, v166, v178, s3
	v_add3_u32 v167, v167, v179, s3
	v_add3_u32 v172, v172, v180, s3
	v_add3_u32 v173, v173, v181, s3
	v_add3_u32 v174, v174, v182, s3
	v_add3_u32 v175, v175, v183, s3
	v_and_b32_e32 v165, 0xffff0000, v165
	v_and_b32_e32 v167, 0xffff0000, v167
	v_and_b32_e32 v173, 0xffff0000, v173
	v_and_b32_e32 v175, 0xffff0000, v175
	v_or_b32_sdwa v184, v165, v164 dst_sel:DWORD dst_unused:UNUSED_PAD src0_sel:DWORD src1_sel:WORD_1
	v_or_b32_sdwa v185, v167, v166 dst_sel:DWORD dst_unused:UNUSED_PAD src0_sel:DWORD src1_sel:WORD_1
	v_or_b32_sdwa v186, v173, v172 dst_sel:DWORD dst_unused:UNUSED_PAD src0_sel:DWORD src1_sel:WORD_1
	v_or_b32_sdwa v187, v175, v174 dst_sel:DWORD dst_unused:UNUSED_PAD src0_sel:DWORD src1_sel:WORD_1
	global_store_dwordx4 v243, v[184:187], s[84:85]
	s_add_u32 s84, s84, 0x1000
	s_addc_u32 s85, s85, 0
	s_waitcnt vmcnt(7)
	v_lshlrev_b32_e32 v164, 16, v132
	v_and_b32_e32 v165, 0xffff0000, v132
	v_lshlrev_b32_e32 v166, 16, v133
	v_and_b32_e32 v167, 0xffff0000, v133
	v_lshlrev_b32_e32 v172, 16, v134
	v_and_b32_e32 v173, 0xffff0000, v134
	v_lshlrev_b32_e32 v174, 16, v135
	v_and_b32_e32 v175, 0xffff0000, v135
	v_mul_f32_e32 v164, v8, v164
	v_mul_f32_e32 v165, v9, v165
	v_mul_f32_e32 v166, v10, v166
	v_mul_f32_e32 v167, v11, v167
	v_mul_f32_e32 v172, v12, v172
	v_mul_f32_e32 v173, v13, v173
	v_mul_f32_e32 v174, v14, v174
	v_mul_f32_e32 v175, v15, v175
	v_and_b32_sdwa v176, v164, v242 dst_sel:DWORD dst_unused:UNUSED_PAD src0_sel:WORD_1 src1_sel:DWORD
	v_and_b32_sdwa v177, v165, v242 dst_sel:DWORD dst_unused:UNUSED_PAD src0_sel:WORD_1 src1_sel:DWORD
	v_and_b32_sdwa v178, v166, v242 dst_sel:DWORD dst_unused:UNUSED_PAD src0_sel:WORD_1 src1_sel:DWORD
	v_and_b32_sdwa v179, v167, v242 dst_sel:DWORD dst_unused:UNUSED_PAD src0_sel:WORD_1 src1_sel:DWORD
	v_and_b32_sdwa v180, v172, v242 dst_sel:DWORD dst_unused:UNUSED_PAD src0_sel:WORD_1 src1_sel:DWORD
	v_and_b32_sdwa v181, v173, v242 dst_sel:DWORD dst_unused:UNUSED_PAD src0_sel:WORD_1 src1_sel:DWORD
	v_and_b32_sdwa v182, v174, v242 dst_sel:DWORD dst_unused:UNUSED_PAD src0_sel:WORD_1 src1_sel:DWORD
	v_and_b32_sdwa v183, v175, v242 dst_sel:DWORD dst_unused:UNUSED_PAD src0_sel:WORD_1 src1_sel:DWORD
	v_add3_u32 v164, v164, v176, s3
	v_add3_u32 v165, v165, v177, s3
	v_add3_u32 v166, v166, v178, s3
	v_add3_u32 v167, v167, v179, s3
	v_add3_u32 v172, v172, v180, s3
	v_add3_u32 v173, v173, v181, s3
	v_add3_u32 v174, v174, v182, s3
	v_add3_u32 v175, v175, v183, s3
	v_and_b32_e32 v165, 0xffff0000, v165
	v_and_b32_e32 v167, 0xffff0000, v167
	v_and_b32_e32 v173, 0xffff0000, v173
	v_and_b32_e32 v175, 0xffff0000, v175
	v_or_b32_sdwa v188, v165, v164 dst_sel:DWORD dst_unused:UNUSED_PAD src0_sel:DWORD src1_sel:WORD_1
	v_or_b32_sdwa v189, v167, v166 dst_sel:DWORD dst_unused:UNUSED_PAD src0_sel:DWORD src1_sel:WORD_1
	v_or_b32_sdwa v190, v173, v172 dst_sel:DWORD dst_unused:UNUSED_PAD src0_sel:DWORD src1_sel:WORD_1
	v_or_b32_sdwa v191, v175, v174 dst_sel:DWORD dst_unused:UNUSED_PAD src0_sel:DWORD src1_sel:WORD_1
	global_store_dwordx4 v243, v[188:191], s[84:85]
	s_add_u32 s84, s84, 0x1000
	s_addc_u32 s85, s85, 0
	s_waitcnt vmcnt(7)
	v_lshlrev_b32_e32 v164, 16, v136
	v_and_b32_e32 v165, 0xffff0000, v136
	v_lshlrev_b32_e32 v166, 16, v137
	v_and_b32_e32 v167, 0xffff0000, v137
	v_lshlrev_b32_e32 v172, 16, v138
	v_and_b32_e32 v173, 0xffff0000, v138
	v_lshlrev_b32_e32 v174, 16, v139
	v_and_b32_e32 v175, 0xffff0000, v139
	v_mul_f32_e32 v164, v16, v164
	v_mul_f32_e32 v165, v17, v165
	v_mul_f32_e32 v166, v18, v166
	v_mul_f32_e32 v167, v19, v167
	v_mul_f32_e32 v172, v20, v172
	v_mul_f32_e32 v173, v21, v173
	v_mul_f32_e32 v174, v22, v174
	v_mul_f32_e32 v175, v23, v175
	v_and_b32_sdwa v176, v164, v242 dst_sel:DWORD dst_unused:UNUSED_PAD src0_sel:WORD_1 src1_sel:DWORD
	v_and_b32_sdwa v177, v165, v242 dst_sel:DWORD dst_unused:UNUSED_PAD src0_sel:WORD_1 src1_sel:DWORD
	v_and_b32_sdwa v178, v166, v242 dst_sel:DWORD dst_unused:UNUSED_PAD src0_sel:WORD_1 src1_sel:DWORD
	v_and_b32_sdwa v179, v167, v242 dst_sel:DWORD dst_unused:UNUSED_PAD src0_sel:WORD_1 src1_sel:DWORD
	v_and_b32_sdwa v180, v172, v242 dst_sel:DWORD dst_unused:UNUSED_PAD src0_sel:WORD_1 src1_sel:DWORD
	v_and_b32_sdwa v181, v173, v242 dst_sel:DWORD dst_unused:UNUSED_PAD src0_sel:WORD_1 src1_sel:DWORD
	v_and_b32_sdwa v182, v174, v242 dst_sel:DWORD dst_unused:UNUSED_PAD src0_sel:WORD_1 src1_sel:DWORD
	v_and_b32_sdwa v183, v175, v242 dst_sel:DWORD dst_unused:UNUSED_PAD src0_sel:WORD_1 src1_sel:DWORD
	v_add3_u32 v164, v164, v176, s3
	v_add3_u32 v165, v165, v177, s3
	v_add3_u32 v166, v166, v178, s3
	v_add3_u32 v167, v167, v179, s3
	v_add3_u32 v172, v172, v180, s3
	v_add3_u32 v173, v173, v181, s3
	v_add3_u32 v174, v174, v182, s3
	v_add3_u32 v175, v175, v183, s3
	v_and_b32_e32 v165, 0xffff0000, v165
	v_and_b32_e32 v167, 0xffff0000, v167
	v_and_b32_e32 v173, 0xffff0000, v173
	v_and_b32_e32 v175, 0xffff0000, v175
	v_or_b32_sdwa v184, v165, v164 dst_sel:DWORD dst_unused:UNUSED_PAD src0_sel:DWORD src1_sel:WORD_1
	v_or_b32_sdwa v185, v167, v166 dst_sel:DWORD dst_unused:UNUSED_PAD src0_sel:DWORD src1_sel:WORD_1
	v_or_b32_sdwa v186, v173, v172 dst_sel:DWORD dst_unused:UNUSED_PAD src0_sel:DWORD src1_sel:WORD_1
	v_or_b32_sdwa v187, v175, v174 dst_sel:DWORD dst_unused:UNUSED_PAD src0_sel:DWORD src1_sel:WORD_1
	global_store_dwordx4 v243, v[184:187], s[84:85]
	s_add_u32 s84, s84, 0x1000
	s_addc_u32 s85, s85, 0
	s_waitcnt vmcnt(7)
	v_lshlrev_b32_e32 v164, 16, v140
	v_and_b32_e32 v165, 0xffff0000, v140
	v_lshlrev_b32_e32 v166, 16, v141
	v_and_b32_e32 v167, 0xffff0000, v141
	v_lshlrev_b32_e32 v172, 16, v142
	v_and_b32_e32 v173, 0xffff0000, v142
	v_lshlrev_b32_e32 v174, 16, v143
	v_and_b32_e32 v175, 0xffff0000, v143
	v_mul_f32_e32 v164, v24, v164
	v_mul_f32_e32 v165, v25, v165
	v_mul_f32_e32 v166, v26, v166
	v_mul_f32_e32 v167, v27, v167
	v_mul_f32_e32 v172, v28, v172
	v_mul_f32_e32 v173, v29, v173
	v_mul_f32_e32 v174, v30, v174
	v_mul_f32_e32 v175, v31, v175
	v_and_b32_sdwa v176, v164, v242 dst_sel:DWORD dst_unused:UNUSED_PAD src0_sel:WORD_1 src1_sel:DWORD
	v_and_b32_sdwa v177, v165, v242 dst_sel:DWORD dst_unused:UNUSED_PAD src0_sel:WORD_1 src1_sel:DWORD
	v_and_b32_sdwa v178, v166, v242 dst_sel:DWORD dst_unused:UNUSED_PAD src0_sel:WORD_1 src1_sel:DWORD
	v_and_b32_sdwa v179, v167, v242 dst_sel:DWORD dst_unused:UNUSED_PAD src0_sel:WORD_1 src1_sel:DWORD
	v_and_b32_sdwa v180, v172, v242 dst_sel:DWORD dst_unused:UNUSED_PAD src0_sel:WORD_1 src1_sel:DWORD
	v_and_b32_sdwa v181, v173, v242 dst_sel:DWORD dst_unused:UNUSED_PAD src0_sel:WORD_1 src1_sel:DWORD
	v_and_b32_sdwa v182, v174, v242 dst_sel:DWORD dst_unused:UNUSED_PAD src0_sel:WORD_1 src1_sel:DWORD
	v_and_b32_sdwa v183, v175, v242 dst_sel:DWORD dst_unused:UNUSED_PAD src0_sel:WORD_1 src1_sel:DWORD
	v_add3_u32 v164, v164, v176, s3
	v_add3_u32 v165, v165, v177, s3
	v_add3_u32 v166, v166, v178, s3
	v_add3_u32 v167, v167, v179, s3
	v_add3_u32 v172, v172, v180, s3
	v_add3_u32 v173, v173, v181, s3
	v_add3_u32 v174, v174, v182, s3
	v_add3_u32 v175, v175, v183, s3
	v_and_b32_e32 v165, 0xffff0000, v165
	v_and_b32_e32 v167, 0xffff0000, v167
	v_and_b32_e32 v173, 0xffff0000, v173
	v_and_b32_e32 v175, 0xffff0000, v175
	v_or_b32_sdwa v188, v165, v164 dst_sel:DWORD dst_unused:UNUSED_PAD src0_sel:DWORD src1_sel:WORD_1
	v_or_b32_sdwa v189, v167, v166 dst_sel:DWORD dst_unused:UNUSED_PAD src0_sel:DWORD src1_sel:WORD_1
	v_or_b32_sdwa v190, v173, v172 dst_sel:DWORD dst_unused:UNUSED_PAD src0_sel:DWORD src1_sel:WORD_1
	v_or_b32_sdwa v191, v175, v174 dst_sel:DWORD dst_unused:UNUSED_PAD src0_sel:DWORD src1_sel:WORD_1
	global_store_dwordx4 v243, v[188:191], s[84:85]
	s_add_u32 s84, s84, 0x1000
	s_addc_u32 s85, s85, 0
	s_waitcnt vmcnt(7)
	v_lshlrev_b32_e32 v164, 16, v148
	v_and_b32_e32 v165, 0xffff0000, v148
	v_lshlrev_b32_e32 v166, 16, v149
	v_and_b32_e32 v167, 0xffff0000, v149
	v_lshlrev_b32_e32 v172, 16, v150
	v_and_b32_e32 v173, 0xffff0000, v150
	v_lshlrev_b32_e32 v174, 16, v151
	v_and_b32_e32 v175, 0xffff0000, v151
	v_mul_f32_e32 v164, v32, v164
	v_mul_f32_e32 v165, v33, v165
	v_mul_f32_e32 v166, v34, v166
	v_mul_f32_e32 v167, v35, v167
	v_mul_f32_e32 v172, v36, v172
	v_mul_f32_e32 v173, v37, v173
	v_mul_f32_e32 v174, v38, v174
	v_mul_f32_e32 v175, v39, v175
	v_and_b32_sdwa v176, v164, v242 dst_sel:DWORD dst_unused:UNUSED_PAD src0_sel:WORD_1 src1_sel:DWORD
	v_and_b32_sdwa v177, v165, v242 dst_sel:DWORD dst_unused:UNUSED_PAD src0_sel:WORD_1 src1_sel:DWORD
	v_and_b32_sdwa v178, v166, v242 dst_sel:DWORD dst_unused:UNUSED_PAD src0_sel:WORD_1 src1_sel:DWORD
	v_and_b32_sdwa v179, v167, v242 dst_sel:DWORD dst_unused:UNUSED_PAD src0_sel:WORD_1 src1_sel:DWORD
	v_and_b32_sdwa v180, v172, v242 dst_sel:DWORD dst_unused:UNUSED_PAD src0_sel:WORD_1 src1_sel:DWORD
	v_and_b32_sdwa v181, v173, v242 dst_sel:DWORD dst_unused:UNUSED_PAD src0_sel:WORD_1 src1_sel:DWORD
	v_and_b32_sdwa v182, v174, v242 dst_sel:DWORD dst_unused:UNUSED_PAD src0_sel:WORD_1 src1_sel:DWORD
	v_and_b32_sdwa v183, v175, v242 dst_sel:DWORD dst_unused:UNUSED_PAD src0_sel:WORD_1 src1_sel:DWORD
	v_add3_u32 v164, v164, v176, s3
	v_add3_u32 v165, v165, v177, s3
	v_add3_u32 v166, v166, v178, s3
	v_add3_u32 v167, v167, v179, s3
	v_add3_u32 v172, v172, v180, s3
	v_add3_u32 v173, v173, v181, s3
	v_add3_u32 v174, v174, v182, s3
	v_add3_u32 v175, v175, v183, s3
	v_and_b32_e32 v165, 0xffff0000, v165
	v_and_b32_e32 v167, 0xffff0000, v167
	v_and_b32_e32 v173, 0xffff0000, v173
	v_and_b32_e32 v175, 0xffff0000, v175
	v_or_b32_sdwa v184, v165, v164 dst_sel:DWORD dst_unused:UNUSED_PAD src0_sel:DWORD src1_sel:WORD_1
	v_or_b32_sdwa v185, v167, v166 dst_sel:DWORD dst_unused:UNUSED_PAD src0_sel:DWORD src1_sel:WORD_1
	v_or_b32_sdwa v186, v173, v172 dst_sel:DWORD dst_unused:UNUSED_PAD src0_sel:DWORD src1_sel:WORD_1
	v_or_b32_sdwa v187, v175, v174 dst_sel:DWORD dst_unused:UNUSED_PAD src0_sel:DWORD src1_sel:WORD_1
	global_store_dwordx4 v243, v[184:187], s[84:85]
	s_add_u32 s84, s84, 0x1000
	s_addc_u32 s85, s85, 0
	s_waitcnt vmcnt(7)
	v_lshlrev_b32_e32 v164, 16, v152
	v_and_b32_e32 v165, 0xffff0000, v152
	v_lshlrev_b32_e32 v166, 16, v153
	v_and_b32_e32 v167, 0xffff0000, v153
	v_lshlrev_b32_e32 v172, 16, v154
	v_and_b32_e32 v173, 0xffff0000, v154
	v_lshlrev_b32_e32 v174, 16, v155
	v_and_b32_e32 v175, 0xffff0000, v155
	v_mul_f32_e32 v164, v40, v164
	v_mul_f32_e32 v165, v41, v165
	v_mul_f32_e32 v166, v42, v166
	v_mul_f32_e32 v167, v43, v167
	v_mul_f32_e32 v172, v44, v172
	v_mul_f32_e32 v173, v45, v173
	v_mul_f32_e32 v174, v46, v174
	v_mul_f32_e32 v175, v47, v175
	v_and_b32_sdwa v176, v164, v242 dst_sel:DWORD dst_unused:UNUSED_PAD src0_sel:WORD_1 src1_sel:DWORD
	v_and_b32_sdwa v177, v165, v242 dst_sel:DWORD dst_unused:UNUSED_PAD src0_sel:WORD_1 src1_sel:DWORD
	v_and_b32_sdwa v178, v166, v242 dst_sel:DWORD dst_unused:UNUSED_PAD src0_sel:WORD_1 src1_sel:DWORD
	v_and_b32_sdwa v179, v167, v242 dst_sel:DWORD dst_unused:UNUSED_PAD src0_sel:WORD_1 src1_sel:DWORD
	v_and_b32_sdwa v180, v172, v242 dst_sel:DWORD dst_unused:UNUSED_PAD src0_sel:WORD_1 src1_sel:DWORD
	v_and_b32_sdwa v181, v173, v242 dst_sel:DWORD dst_unused:UNUSED_PAD src0_sel:WORD_1 src1_sel:DWORD
	v_and_b32_sdwa v182, v174, v242 dst_sel:DWORD dst_unused:UNUSED_PAD src0_sel:WORD_1 src1_sel:DWORD
	v_and_b32_sdwa v183, v175, v242 dst_sel:DWORD dst_unused:UNUSED_PAD src0_sel:WORD_1 src1_sel:DWORD
	v_add3_u32 v164, v164, v176, s3
	v_add3_u32 v165, v165, v177, s3
	v_add3_u32 v166, v166, v178, s3
	v_add3_u32 v167, v167, v179, s3
	v_add3_u32 v172, v172, v180, s3
	v_add3_u32 v173, v173, v181, s3
	v_add3_u32 v174, v174, v182, s3
	v_add3_u32 v175, v175, v183, s3
	v_and_b32_e32 v165, 0xffff0000, v165
	v_and_b32_e32 v167, 0xffff0000, v167
	v_and_b32_e32 v173, 0xffff0000, v173
	v_and_b32_e32 v175, 0xffff0000, v175
	v_or_b32_sdwa v188, v165, v164 dst_sel:DWORD dst_unused:UNUSED_PAD src0_sel:DWORD src1_sel:WORD_1
	v_or_b32_sdwa v189, v167, v166 dst_sel:DWORD dst_unused:UNUSED_PAD src0_sel:DWORD src1_sel:WORD_1
	v_or_b32_sdwa v190, v173, v172 dst_sel:DWORD dst_unused:UNUSED_PAD src0_sel:DWORD src1_sel:WORD_1
	v_or_b32_sdwa v191, v175, v174 dst_sel:DWORD dst_unused:UNUSED_PAD src0_sel:DWORD src1_sel:WORD_1
	global_store_dwordx4 v243, v[188:191], s[84:85]
	s_add_u32 s84, s84, 0x1000
	s_addc_u32 s85, s85, 0
	s_waitcnt vmcnt(7)
	v_lshlrev_b32_e32 v164, 16, v156
	v_and_b32_e32 v165, 0xffff0000, v156
	v_lshlrev_b32_e32 v166, 16, v157
	v_and_b32_e32 v167, 0xffff0000, v157
	v_lshlrev_b32_e32 v172, 16, v158
	v_and_b32_e32 v173, 0xffff0000, v158
	v_lshlrev_b32_e32 v174, 16, v159
	v_and_b32_e32 v175, 0xffff0000, v159
	v_mul_f32_e32 v164, v48, v164
	v_mul_f32_e32 v165, v49, v165
	v_mul_f32_e32 v166, v50, v166
	v_mul_f32_e32 v167, v51, v167
	v_mul_f32_e32 v172, v52, v172
	v_mul_f32_e32 v173, v53, v173
	v_mul_f32_e32 v174, v54, v174
	v_mul_f32_e32 v175, v55, v175
	v_and_b32_sdwa v176, v164, v242 dst_sel:DWORD dst_unused:UNUSED_PAD src0_sel:WORD_1 src1_sel:DWORD
	v_and_b32_sdwa v177, v165, v242 dst_sel:DWORD dst_unused:UNUSED_PAD src0_sel:WORD_1 src1_sel:DWORD
	v_and_b32_sdwa v178, v166, v242 dst_sel:DWORD dst_unused:UNUSED_PAD src0_sel:WORD_1 src1_sel:DWORD
	v_and_b32_sdwa v179, v167, v242 dst_sel:DWORD dst_unused:UNUSED_PAD src0_sel:WORD_1 src1_sel:DWORD
	v_and_b32_sdwa v180, v172, v242 dst_sel:DWORD dst_unused:UNUSED_PAD src0_sel:WORD_1 src1_sel:DWORD
	v_and_b32_sdwa v181, v173, v242 dst_sel:DWORD dst_unused:UNUSED_PAD src0_sel:WORD_1 src1_sel:DWORD
	v_and_b32_sdwa v182, v174, v242 dst_sel:DWORD dst_unused:UNUSED_PAD src0_sel:WORD_1 src1_sel:DWORD
	v_and_b32_sdwa v183, v175, v242 dst_sel:DWORD dst_unused:UNUSED_PAD src0_sel:WORD_1 src1_sel:DWORD
	v_add3_u32 v164, v164, v176, s3
	v_add3_u32 v165, v165, v177, s3
	v_add3_u32 v166, v166, v178, s3
	v_add3_u32 v167, v167, v179, s3
	v_add3_u32 v172, v172, v180, s3
	v_add3_u32 v173, v173, v181, s3
	v_add3_u32 v174, v174, v182, s3
	v_add3_u32 v175, v175, v183, s3
	v_and_b32_e32 v165, 0xffff0000, v165
	v_and_b32_e32 v167, 0xffff0000, v167
	v_and_b32_e32 v173, 0xffff0000, v173
	v_and_b32_e32 v175, 0xffff0000, v175
	v_or_b32_sdwa v184, v165, v164 dst_sel:DWORD dst_unused:UNUSED_PAD src0_sel:DWORD src1_sel:WORD_1
	v_or_b32_sdwa v185, v167, v166 dst_sel:DWORD dst_unused:UNUSED_PAD src0_sel:DWORD src1_sel:WORD_1
	v_or_b32_sdwa v186, v173, v172 dst_sel:DWORD dst_unused:UNUSED_PAD src0_sel:DWORD src1_sel:WORD_1
	v_or_b32_sdwa v187, v175, v174 dst_sel:DWORD dst_unused:UNUSED_PAD src0_sel:DWORD src1_sel:WORD_1
	global_store_dwordx4 v243, v[184:187], s[84:85]
	s_add_u32 s84, s84, 0x1000
	s_addc_u32 s85, s85, 0
	s_waitcnt vmcnt(7)
	v_lshlrev_b32_e32 v164, 16, v160
	v_and_b32_e32 v165, 0xffff0000, v160
	v_lshlrev_b32_e32 v166, 16, v161
	v_and_b32_e32 v167, 0xffff0000, v161
	v_lshlrev_b32_e32 v172, 16, v162
	v_and_b32_e32 v173, 0xffff0000, v162
	v_lshlrev_b32_e32 v174, 16, v163
	v_and_b32_e32 v175, 0xffff0000, v163
	v_mul_f32_e32 v164, v56, v164
	v_mul_f32_e32 v165, v57, v165
	v_mul_f32_e32 v166, v58, v166
	v_mul_f32_e32 v167, v59, v167
	v_mul_f32_e32 v172, v60, v172
	v_mul_f32_e32 v173, v61, v173
	v_mul_f32_e32 v174, v62, v174
	v_mul_f32_e32 v175, v63, v175
	v_and_b32_sdwa v176, v164, v242 dst_sel:DWORD dst_unused:UNUSED_PAD src0_sel:WORD_1 src1_sel:DWORD
	v_and_b32_sdwa v177, v165, v242 dst_sel:DWORD dst_unused:UNUSED_PAD src0_sel:WORD_1 src1_sel:DWORD
	v_and_b32_sdwa v178, v166, v242 dst_sel:DWORD dst_unused:UNUSED_PAD src0_sel:WORD_1 src1_sel:DWORD
	v_and_b32_sdwa v179, v167, v242 dst_sel:DWORD dst_unused:UNUSED_PAD src0_sel:WORD_1 src1_sel:DWORD
	v_and_b32_sdwa v180, v172, v242 dst_sel:DWORD dst_unused:UNUSED_PAD src0_sel:WORD_1 src1_sel:DWORD
	v_and_b32_sdwa v181, v173, v242 dst_sel:DWORD dst_unused:UNUSED_PAD src0_sel:WORD_1 src1_sel:DWORD
	v_and_b32_sdwa v182, v174, v242 dst_sel:DWORD dst_unused:UNUSED_PAD src0_sel:WORD_1 src1_sel:DWORD
	v_and_b32_sdwa v183, v175, v242 dst_sel:DWORD dst_unused:UNUSED_PAD src0_sel:WORD_1 src1_sel:DWORD
	v_add3_u32 v164, v164, v176, s3
	v_add3_u32 v165, v165, v177, s3
	v_add3_u32 v166, v166, v178, s3
	v_add3_u32 v167, v167, v179, s3
	v_add3_u32 v172, v172, v180, s3
	v_add3_u32 v173, v173, v181, s3
	v_add3_u32 v174, v174, v182, s3
	v_add3_u32 v175, v175, v183, s3
	v_and_b32_e32 v165, 0xffff0000, v165
	v_and_b32_e32 v167, 0xffff0000, v167
	v_and_b32_e32 v173, 0xffff0000, v173
	v_and_b32_e32 v175, 0xffff0000, v175
	v_or_b32_sdwa v188, v165, v164 dst_sel:DWORD dst_unused:UNUSED_PAD src0_sel:DWORD src1_sel:WORD_1
	v_or_b32_sdwa v189, v167, v166 dst_sel:DWORD dst_unused:UNUSED_PAD src0_sel:DWORD src1_sel:WORD_1
	v_or_b32_sdwa v190, v173, v172 dst_sel:DWORD dst_unused:UNUSED_PAD src0_sel:DWORD src1_sel:WORD_1
	v_or_b32_sdwa v191, v175, v174 dst_sel:DWORD dst_unused:UNUSED_PAD src0_sel:DWORD src1_sel:WORD_1
	global_store_dwordx4 v243, v[188:191], s[84:85]
	s_add_u32 s84, s84, 0x1000
	s_addc_u32 s85, s85, 0
	s_cmp_eq_u32 s83, 1
	s_cbranch_scc1 .Lp6b_epdone
	s_cmp_eq_u32 s95, 1
	s_cbranch_scc0 .Lp6b_epdone
	v_mov_b32_e32 v0, v64
	v_mov_b32_e32 v1, v65
	v_mov_b32_e32 v2, v66
	v_mov_b32_e32 v3, v67
	v_mov_b32_e32 v4, v68
	v_mov_b32_e32 v5, v69
	v_mov_b32_e32 v6, v70
	v_mov_b32_e32 v7, v71
	v_mov_b32_e32 v8, v72
	v_mov_b32_e32 v9, v73
	v_mov_b32_e32 v10, v74
	v_mov_b32_e32 v11, v75
	v_mov_b32_e32 v12, v76
	v_mov_b32_e32 v13, v77
	v_mov_b32_e32 v14, v78
	v_mov_b32_e32 v15, v79
	v_mov_b32_e32 v16, v80
	v_mov_b32_e32 v17, v81
	v_mov_b32_e32 v18, v82
	v_mov_b32_e32 v19, v83
	v_mov_b32_e32 v20, v84
	v_mov_b32_e32 v21, v85
	v_mov_b32_e32 v22, v86
	v_mov_b32_e32 v23, v87
	v_mov_b32_e32 v24, v88
	v_mov_b32_e32 v25, v89
	v_mov_b32_e32 v26, v90
	v_mov_b32_e32 v27, v91
	v_mov_b32_e32 v28, v92
	v_mov_b32_e32 v29, v93
	v_mov_b32_e32 v30, v94
	v_mov_b32_e32 v31, v95
	v_mov_b32_e32 v32, v96
	v_mov_b32_e32 v33, v97
	v_mov_b32_e32 v34, v98
	v_mov_b32_e32 v35, v99
	v_mov_b32_e32 v36, v100
	v_mov_b32_e32 v37, v101
	v_mov_b32_e32 v38, v102
	v_mov_b32_e32 v39, v103
	v_mov_b32_e32 v40, v104
	v_mov_b32_e32 v41, v105
	v_mov_b32_e32 v42, v106
	v_mov_b32_e32 v43, v107
	v_mov_b32_e32 v44, v108
	v_mov_b32_e32 v45, v109
	v_mov_b32_e32 v46, v110
	v_mov_b32_e32 v47, v111
	v_mov_b32_e32 v48, v112
	v_mov_b32_e32 v49, v113
	v_mov_b32_e32 v50, v114
	v_mov_b32_e32 v51, v115
	v_mov_b32_e32 v52, v116
	v_mov_b32_e32 v53, v117
	v_mov_b32_e32 v54, v118
	v_mov_b32_e32 v55, v119
	v_mov_b32_e32 v56, v120
	v_mov_b32_e32 v57, v121
	v_mov_b32_e32 v58, v122
	v_mov_b32_e32 v59, v123
	v_mov_b32_e32 v60, v124
	v_mov_b32_e32 v61, v125
	v_mov_b32_e32 v62, v126
	v_mov_b32_e32 v63, v127
	s_mov_b32 s83, 1
	s_branch .Lp6b_ep
.Lp6b_epdone:
	v_lshrrev_b32_e32 v236, 3, v168
	v_lshrrev_b32_e32 v237, 4, v168
	v_xor_b32_e32 v237, v237, v168
	v_and_b32_e32 v237, 7, v237
	v_lshlrev_b32_e32 v237, 4, v237
	v_lshl_or_b32 v232, v236, 11, v237
	v_add_u32_e32 v233, 0x10000, v232
	v_add_u32_e32 v234, 0x20000, v232
	v_add_u32_e32 v235, 0x30000, v232
	s_load_dwordx2 s[90:91], s[0:1], 0x100
	s_load_dwordx2 s[92:93], s[0:1], 0xb8
	v_lshrrev_b32_e32 v237, 6, v168
	s_nop 1
	v_readfirstlane_b32 s97, v237
	s_nop 3
	s_lshl_b32 s96, s97, 10
	s_add_u32 s96, s96, 16
	s_add_u32 s94, s81, s80
	s_cmp_lt_i32 s94, s82
	s_cselect_b32 s95, 1, 0
	s_cmp_lg_u64 s[20:21], 0
	s_cselect_b32 s95, 0, s95
	s_cmp_ge_u32 s94, 0x40
	s_cselect_b32 s97, 1, 0
	s_mul_i32 s100, s97, 0x40
	s_sub_u32 s100, s94, s100
	s_lshr_b32 s101, s100, 3
	s_and_b32 s100, s100, 7
	s_lshl_b32 s97, s97, 3
	s_add_u32 s100, s100, s97
	s_add_u32 s100, s100, s79
	s_cmp_lg_u32 s101, s74
	s_cselect_b32 s95, 0, s95
	s_cmp_eq_u32 s95, 1
	s_cselect_b32 s101, s100, s70
	s_mov_b32 s97, s101
	s_waitcnt lgkmcnt(0)
	s_lshl_b32 s94, s74, 18
	s_add_u32 s98, s92, s94
	s_addc_u32 s99, s93, 0
	s_lshl_b32 s101, s101, 18
	s_add_u32 s92, s90, s101
	s_addc_u32 s93, s91, 0
	s_lshl_b32 s94, s70, 18
	s_add_u32 s90, s90, s94
	s_addc_u32 s91, s91, 0
	s_waitcnt vmcnt(0)
	s_barrier
	s_add_u32 m0, s96, 0x0
	s_nop 0
	global_load_lds_dwordx4 v232, s[90:91]
	s_add_u32 m0, s96, 0x1000
	s_nop 0
	global_load_lds_dwordx4 v233, s[90:91]
	s_add_u32 m0, s96, 0x2000
	s_nop 0
	global_load_lds_dwordx4 v234, s[90:91]
	s_add_u32 m0, s96, 0x3000
	s_nop 0
	global_load_lds_dwordx4 v235, s[90:91]
	s_add_u32 m0, s96, 0x4000
	s_nop 0
	global_load_lds_dwordx4 v232, s[92:93]
	s_add_u32 m0, s96, 0x5000
	s_nop 0
	global_load_lds_dwordx4 v233, s[92:93]
	s_add_u32 m0, s96, 0x6000
	s_nop 0
	global_load_lds_dwordx4 v234, s[92:93]
	s_add_u32 m0, s96, 0x7000
	s_nop 0
	global_load_lds_dwordx4 v235, s[92:93]
	s_add_u32 m0, s96, 0x8000
	s_nop 0
	global_load_lds_dwordx4 v232, s[98:99]
	s_add_u32 m0, s96, 0x9000
	s_nop 0
	global_load_lds_dwordx4 v233, s[98:99]
	s_add_u32 m0, s96, 0xa000
	s_nop 0
	global_load_lds_dwordx4 v234, s[98:99]
	s_add_u32 m0, s96, 0xb000
	s_nop 0
	global_load_lds_dwordx4 v235, s[98:99]
	s_add_u32 s90, s90, 0x80
	s_addc_u32 s91, s91, 0
	s_add_u32 s92, s92, 0x80
	s_addc_u32 s93, s93, 0
	s_add_u32 s98, s98, 0x80
	s_addc_u32 s99, s99, 0
	v_mov_b32_e32 v0, 0
	v_mov_b32_e32 v1, v0
	v_mov_b32_e32 v2, v0
	v_mov_b32_e32 v3, v0
	v_mov_b32_e32 v4, v0
	v_mov_b32_e32 v5, v0
	v_mov_b32_e32 v6, v0
	v_mov_b32_e32 v7, v0
	v_mov_b32_e32 v8, v0
	v_mov_b32_e32 v9, v0
	v_mov_b32_e32 v10, v0
	v_mov_b32_e32 v11, v0
	v_mov_b32_e32 v12, v0
	v_mov_b32_e32 v13, v0
	v_mov_b32_e32 v14, v0
	v_mov_b32_e32 v15, v0
	v_mov_b32_e32 v16, v0
	v_mov_b32_e32 v17, v0
	v_mov_b32_e32 v18, v0
	v_mov_b32_e32 v19, v0
	v_mov_b32_e32 v20, v0
	v_mov_b32_e32 v21, v0
	v_mov_b32_e32 v22, v0
	v_mov_b32_e32 v23, v0
	v_mov_b32_e32 v24, v0
	v_mov_b32_e32 v25, v0
	v_mov_b32_e32 v26, v0
	v_mov_b32_e32 v27, v0
	v_mov_b32_e32 v28, v0
	v_mov_b32_e32 v29, v0
	v_mov_b32_e32 v30, v0
	v_mov_b32_e32 v31, v0
	v_mov_b32_e32 v32, v0
	v_mov_b32_e32 v33, v0
	v_mov_b32_e32 v34, v0
	v_mov_b32_e32 v35, v0
	v_mov_b32_e32 v36, v0
	v_mov_b32_e32 v37, v0
	v_mov_b32_e32 v38, v0
	v_mov_b32_e32 v39, v0
	v_mov_b32_e32 v40, v0
	v_mov_b32_e32 v41, v0
	v_mov_b32_e32 v42, v0
	v_mov_b32_e32 v43, v0
	v_mov_b32_e32 v44, v0
	v_mov_b32_e32 v45, v0
	v_mov_b32_e32 v46, v0
	v_mov_b32_e32 v47, v0
	v_mov_b32_e32 v48, v0
	v_mov_b32_e32 v49, v0
	v_mov_b32_e32 v50, v0
	v_mov_b32_e32 v51, v0
	v_mov_b32_e32 v52, v0
	v_mov_b32_e32 v53, v0
	v_mov_b32_e32 v54, v0
	v_mov_b32_e32 v55, v0
	v_mov_b32_e32 v56, v0
	v_mov_b32_e32 v57, v0
	v_mov_b32_e32 v58, v0
	v_mov_b32_e32 v59, v0
	v_mov_b32_e32 v60, v0
	v_mov_b32_e32 v61, v0
	v_mov_b32_e32 v62, v0
	v_mov_b32_e32 v63, v0
	v_mov_b32_e32 v64, v0
	v_mov_b32_e32 v65, v0
	v_mov_b32_e32 v66, v0
	v_mov_b32_e32 v67, v0
	v_mov_b32_e32 v68, v0
	v_mov_b32_e32 v69, v0
	v_mov_b32_e32 v70, v0
	v_mov_b32_e32 v71, v0
	v_mov_b32_e32 v72, v0
	v_mov_b32_e32 v73, v0
	v_mov_b32_e32 v74, v0
	v_mov_b32_e32 v75, v0
	v_mov_b32_e32 v76, v0
	v_mov_b32_e32 v77, v0
	v_mov_b32_e32 v78, v0
	v_mov_b32_e32 v79, v0
	v_mov_b32_e32 v80, v0
	v_mov_b32_e32 v81, v0
	v_mov_b32_e32 v82, v0
	v_mov_b32_e32 v83, v0
	v_mov_b32_e32 v84, v0
	v_mov_b32_e32 v85, v0
	v_mov_b32_e32 v86, v0
	v_mov_b32_e32 v87, v0
	v_mov_b32_e32 v88, v0
	v_mov_b32_e32 v89, v0
	v_mov_b32_e32 v90, v0
	v_mov_b32_e32 v91, v0
	v_mov_b32_e32 v92, v0
	v_mov_b32_e32 v93, v0
	v_mov_b32_e32 v94, v0
	v_mov_b32_e32 v95, v0
	v_mov_b32_e32 v96, v0
	v_mov_b32_e32 v97, v0
	v_mov_b32_e32 v98, v0
	v_mov_b32_e32 v99, v0
	v_mov_b32_e32 v100, v0
	v_mov_b32_e32 v101, v0
	v_mov_b32_e32 v102, v0
	v_mov_b32_e32 v103, v0
	v_mov_b32_e32 v104, v0
	v_mov_b32_e32 v105, v0
	v_mov_b32_e32 v106, v0
	v_mov_b32_e32 v107, v0
	v_mov_b32_e32 v108, v0
	v_mov_b32_e32 v109, v0
	v_mov_b32_e32 v110, v0
	v_mov_b32_e32 v111, v0
	v_mov_b32_e32 v112, v0
	v_mov_b32_e32 v113, v0
	v_mov_b32_e32 v114, v0
	v_mov_b32_e32 v115, v0
	v_mov_b32_e32 v116, v0
	v_mov_b32_e32 v117, v0
	v_mov_b32_e32 v118, v0
	v_mov_b32_e32 v119, v0
	v_mov_b32_e32 v120, v0
	v_mov_b32_e32 v121, v0
	v_mov_b32_e32 v122, v0
	v_mov_b32_e32 v123, v0
	v_mov_b32_e32 v124, v0
	v_mov_b32_e32 v125, v0
	v_mov_b32_e32 v126, v0
	v_mov_b32_e32 v127, v0
	s_mov_b32 s94, 0

.Lp6c_ep:
	s_lshl_b32 s71, s83, 25
	s_add_u32 s71, s71, 0x8000
	s_add_u32 s84, s24, s71
	s_addc_u32 s85, s25, 0
	v_and_b32_sdwa v128, v0, v242 dst_sel:DWORD dst_unused:UNUSED_PAD src0_sel:WORD_1 src1_sel:DWORD
	v_and_b32_sdwa v129, v1, v242 dst_sel:DWORD dst_unused:UNUSED_PAD src0_sel:WORD_1 src1_sel:DWORD
	v_and_b32_sdwa v130, v2, v242 dst_sel:DWORD dst_unused:UNUSED_PAD src0_sel:WORD_1 src1_sel:DWORD
	v_and_b32_sdwa v131, v3, v242 dst_sel:DWORD dst_unused:UNUSED_PAD src0_sel:WORD_1 src1_sel:DWORD
	v_and_b32_sdwa v132, v4, v242 dst_sel:DWORD dst_unused:UNUSED_PAD src0_sel:WORD_1 src1_sel:DWORD
	v_and_b32_sdwa v133, v5, v242 dst_sel:DWORD dst_unused:UNUSED_PAD src0_sel:WORD_1 src1_sel:DWORD
	v_and_b32_sdwa v134, v6, v242 dst_sel:DWORD dst_unused:UNUSED_PAD src0_sel:WORD_1 src1_sel:DWORD
	v_and_b32_sdwa v135, v7, v242 dst_sel:DWORD dst_unused:UNUSED_PAD src0_sel:WORD_1 src1_sel:DWORD
	v_add3_u32 v0, v0, v128, s3
	v_add3_u32 v1, v1, v129, s3
	v_add3_u32 v2, v2, v130, s3
	v_add3_u32 v3, v3, v131, s3
	v_add3_u32 v4, v4, v132, s3
	v_add3_u32 v5, v5, v133, s3
	v_add3_u32 v6, v6, v134, s3
	v_add3_u32 v7, v7, v135, s3
	v_and_b32_e32 v1, 0xffff0000, v1
	v_and_b32_e32 v3, 0xffff0000, v3
	v_and_b32_e32 v5, 0xffff0000, v5
	v_and_b32_e32 v7, 0xffff0000, v7
	v_or_b32_sdwa v136, v1, v0 dst_sel:DWORD dst_unused:UNUSED_PAD src0_sel:DWORD src1_sel:WORD_1
	v_or_b32_sdwa v137, v3, v2 dst_sel:DWORD dst_unused:UNUSED_PAD src0_sel:DWORD src1_sel:WORD_1
	v_or_b32_sdwa v138, v5, v4 dst_sel:DWORD dst_unused:UNUSED_PAD src0_sel:DWORD src1_sel:WORD_1
	v_or_b32_sdwa v139, v7, v6 dst_sel:DWORD dst_unused:UNUSED_PAD src0_sel:DWORD src1_sel:WORD_1
	global_store_dwordx4 v243, v[136:139], s[84:85]
	s_add_u32 s84, s84, 0x1000
	s_addc_u32 s85, s85, 0
	v_and_b32_sdwa v128, v8, v242 dst_sel:DWORD dst_unused:UNUSED_PAD src0_sel:WORD_1 src1_sel:DWORD
	v_and_b32_sdwa v129, v9, v242 dst_sel:DWORD dst_unused:UNUSED_PAD src0_sel:WORD_1 src1_sel:DWORD
	v_and_b32_sdwa v130, v10, v242 dst_sel:DWORD dst_unused:UNUSED_PAD src0_sel:WORD_1 src1_sel:DWORD
	v_and_b32_sdwa v131, v11, v242 dst_sel:DWORD dst_unused:UNUSED_PAD src0_sel:WORD_1 src1_sel:DWORD
	v_and_b32_sdwa v132, v12, v242 dst_sel:DWORD dst_unused:UNUSED_PAD src0_sel:WORD_1 src1_sel:DWORD
	v_and_b32_sdwa v133, v13, v242 dst_sel:DWORD dst_unused:UNUSED_PAD src0_sel:WORD_1 src1_sel:DWORD
	v_and_b32_sdwa v134, v14, v242 dst_sel:DWORD dst_unused:UNUSED_PAD src0_sel:WORD_1 src1_sel:DWORD
	v_and_b32_sdwa v135, v15, v242 dst_sel:DWORD dst_unused:UNUSED_PAD src0_sel:WORD_1 src1_sel:DWORD
	v_add3_u32 v8, v8, v128, s3
	v_add3_u32 v9, v9, v129, s3
	v_add3_u32 v10, v10, v130, s3
	v_add3_u32 v11, v11, v131, s3
	v_add3_u32 v12, v12, v132, s3
	v_add3_u32 v13, v13, v133, s3
	v_add3_u32 v14, v14, v134, s3
	v_add3_u32 v15, v15, v135, s3
	v_and_b32_e32 v9, 0xffff0000, v9
	v_and_b32_e32 v11, 0xffff0000, v11
	v_and_b32_e32 v13, 0xffff0000, v13
	v_and_b32_e32 v15, 0xffff0000, v15
	v_or_b32_sdwa v140, v9, v8 dst_sel:DWORD dst_unused:UNUSED_PAD src0_sel:DWORD src1_sel:WORD_1
	v_or_b32_sdwa v141, v11, v10 dst_sel:DWORD dst_unused:UNUSED_PAD src0_sel:DWORD src1_sel:WORD_1
	v_or_b32_sdwa v142, v13, v12 dst_sel:DWORD dst_unused:UNUSED_PAD src0_sel:DWORD src1_sel:WORD_1
	v_or_b32_sdwa v143, v15, v14 dst_sel:DWORD dst_unused:UNUSED_PAD src0_sel:DWORD src1_sel:WORD_1
	global_store_dwordx4 v243, v[140:143], s[84:85]
	s_add_u32 s84, s84, 0x1000
	s_addc_u32 s85, s85, 0
	v_and_b32_sdwa v128, v16, v242 dst_sel:DWORD dst_unused:UNUSED_PAD src0_sel:WORD_1 src1_sel:DWORD
	v_and_b32_sdwa v129, v17, v242 dst_sel:DWORD dst_unused:UNUSED_PAD src0_sel:WORD_1 src1_sel:DWORD
	v_and_b32_sdwa v130, v18, v242 dst_sel:DWORD dst_unused:UNUSED_PAD src0_sel:WORD_1 src1_sel:DWORD
	v_and_b32_sdwa v131, v19, v242 dst_sel:DWORD dst_unused:UNUSED_PAD src0_sel:WORD_1 src1_sel:DWORD
	v_and_b32_sdwa v132, v20, v242 dst_sel:DWORD dst_unused:UNUSED_PAD src0_sel:WORD_1 src1_sel:DWORD
	v_and_b32_sdwa v133, v21, v242 dst_sel:DWORD dst_unused:UNUSED_PAD src0_sel:WORD_1 src1_sel:DWORD
	v_and_b32_sdwa v134, v22, v242 dst_sel:DWORD dst_unused:UNUSED_PAD src0_sel:WORD_1 src1_sel:DWORD
	v_and_b32_sdwa v135, v23, v242 dst_sel:DWORD dst_unused:UNUSED_PAD src0_sel:WORD_1 src1_sel:DWORD
	v_add3_u32 v16, v16, v128, s3
	v_add3_u32 v17, v17, v129, s3
	v_add3_u32 v18, v18, v130, s3
	v_add3_u32 v19, v19, v131, s3
	v_add3_u32 v20, v20, v132, s3
	v_add3_u32 v21, v21, v133, s3
	v_add3_u32 v22, v22, v134, s3
	v_add3_u32 v23, v23, v135, s3
	v_and_b32_e32 v17, 0xffff0000, v17
	v_and_b32_e32 v19, 0xffff0000, v19
	v_and_b32_e32 v21, 0xffff0000, v21
	v_and_b32_e32 v23, 0xffff0000, v23
	v_or_b32_sdwa v136, v17, v16 dst_sel:DWORD dst_unused:UNUSED_PAD src0_sel:DWORD src1_sel:WORD_1
	v_or_b32_sdwa v137, v19, v18 dst_sel:DWORD dst_unused:UNUSED_PAD src0_sel:DWORD src1_sel:WORD_1
	v_or_b32_sdwa v138, v21, v20 dst_sel:DWORD dst_unused:UNUSED_PAD src0_sel:DWORD src1_sel:WORD_1
	v_or_b32_sdwa v139, v23, v22 dst_sel:DWORD dst_unused:UNUSED_PAD src0_sel:DWORD src1_sel:WORD_1
	global_store_dwordx4 v243, v[136:139], s[84:85]
	s_add_u32 s84, s84, 0x1000
	s_addc_u32 s85, s85, 0
	v_and_b32_sdwa v128, v24, v242 dst_sel:DWORD dst_unused:UNUSED_PAD src0_sel:WORD_1 src1_sel:DWORD
	v_and_b32_sdwa v129, v25, v242 dst_sel:DWORD dst_unused:UNUSED_PAD src0_sel:WORD_1 src1_sel:DWORD
	v_and_b32_sdwa v130, v26, v242 dst_sel:DWORD dst_unused:UNUSED_PAD src0_sel:WORD_1 src1_sel:DWORD
	v_and_b32_sdwa v131, v27, v242 dst_sel:DWORD dst_unused:UNUSED_PAD src0_sel:WORD_1 src1_sel:DWORD
	v_and_b32_sdwa v132, v28, v242 dst_sel:DWORD dst_unused:UNUSED_PAD src0_sel:WORD_1 src1_sel:DWORD
	v_and_b32_sdwa v133, v29, v242 dst_sel:DWORD dst_unused:UNUSED_PAD src0_sel:WORD_1 src1_sel:DWORD
	v_and_b32_sdwa v134, v30, v242 dst_sel:DWORD dst_unused:UNUSED_PAD src0_sel:WORD_1 src1_sel:DWORD
	v_and_b32_sdwa v135, v31, v242 dst_sel:DWORD dst_unused:UNUSED_PAD src0_sel:WORD_1 src1_sel:DWORD
	v_add3_u32 v24, v24, v128, s3
	v_add3_u32 v25, v25, v129, s3
	v_add3_u32 v26, v26, v130, s3
	v_add3_u32 v27, v27, v131, s3
	v_add3_u32 v28, v28, v132, s3
	v_add3_u32 v29, v29, v133, s3
	v_add3_u32 v30, v30, v134, s3
	v_add3_u32 v31, v31, v135, s3
	v_and_b32_e32 v25, 0xffff0000, v25
	v_and_b32_e32 v27, 0xffff0000, v27
	v_and_b32_e32 v29, 0xffff0000, v29
	v_and_b32_e32 v31, 0xffff0000, v31
	v_or_b32_sdwa v140, v25, v24 dst_sel:DWORD dst_unused:UNUSED_PAD src0_sel:DWORD src1_sel:WORD_1
	v_or_b32_sdwa v141, v27, v26 dst_sel:DWORD dst_unused:UNUSED_PAD src0_sel:DWORD src1_sel:WORD_1
	v_or_b32_sdwa v142, v29, v28 dst_sel:DWORD dst_unused:UNUSED_PAD src0_sel:DWORD src1_sel:WORD_1
	v_or_b32_sdwa v143, v31, v30 dst_sel:DWORD dst_unused:UNUSED_PAD src0_sel:DWORD src1_sel:WORD_1
	global_store_dwordx4 v243, v[140:143], s[84:85]
	s_add_u32 s84, s84, 0x1000
	s_addc_u32 s85, s85, 0
	v_and_b32_sdwa v128, v32, v242 dst_sel:DWORD dst_unused:UNUSED_PAD src0_sel:WORD_1 src1_sel:DWORD
	v_and_b32_sdwa v129, v33, v242 dst_sel:DWORD dst_unused:UNUSED_PAD src0_sel:WORD_1 src1_sel:DWORD
	v_and_b32_sdwa v130, v34, v242 dst_sel:DWORD dst_unused:UNUSED_PAD src0_sel:WORD_1 src1_sel:DWORD
	v_and_b32_sdwa v131, v35, v242 dst_sel:DWORD dst_unused:UNUSED_PAD src0_sel:WORD_1 src1_sel:DWORD
	v_and_b32_sdwa v132, v36, v242 dst_sel:DWORD dst_unused:UNUSED_PAD src0_sel:WORD_1 src1_sel:DWORD
	v_and_b32_sdwa v133, v37, v242 dst_sel:DWORD dst_unused:UNUSED_PAD src0_sel:WORD_1 src1_sel:DWORD
	v_and_b32_sdwa v134, v38, v242 dst_sel:DWORD dst_unused:UNUSED_PAD src0_sel:WORD_1 src1_sel:DWORD
	v_and_b32_sdwa v135, v39, v242 dst_sel:DWORD dst_unused:UNUSED_PAD src0_sel:WORD_1 src1_sel:DWORD
	v_add3_u32 v32, v32, v128, s3
	v_add3_u32 v33, v33, v129, s3
	v_add3_u32 v34, v34, v130, s3
	v_add3_u32 v35, v35, v131, s3
	v_add3_u32 v36, v36, v132, s3
	v_add3_u32 v37, v37, v133, s3
	v_add3_u32 v38, v38, v134, s3
	v_add3_u32 v39, v39, v135, s3
	v_and_b32_e32 v33, 0xffff0000, v33
	v_and_b32_e32 v35, 0xffff0000, v35
	v_and_b32_e32 v37, 0xffff0000, v37
	v_and_b32_e32 v39, 0xffff0000, v39
	v_or_b32_sdwa v136, v33, v32 dst_sel:DWORD dst_unused:UNUSED_PAD src0_sel:DWORD src1_sel:WORD_1
	v_or_b32_sdwa v137, v35, v34 dst_sel:DWORD dst_unused:UNUSED_PAD src0_sel:DWORD src1_sel:WORD_1
	v_or_b32_sdwa v138, v37, v36 dst_sel:DWORD dst_unused:UNUSED_PAD src0_sel:DWORD src1_sel:WORD_1
	v_or_b32_sdwa v139, v39, v38 dst_sel:DWORD dst_unused:UNUSED_PAD src0_sel:DWORD src1_sel:WORD_1
	global_store_dwordx4 v243, v[136:139], s[84:85]
	s_add_u32 s84, s84, 0x1000
	s_addc_u32 s85, s85, 0
	v_and_b32_sdwa v128, v40, v242 dst_sel:DWORD dst_unused:UNUSED_PAD src0_sel:WORD_1 src1_sel:DWORD
	v_and_b32_sdwa v129, v41, v242 dst_sel:DWORD dst_unused:UNUSED_PAD src0_sel:WORD_1 src1_sel:DWORD
	v_and_b32_sdwa v130, v42, v242 dst_sel:DWORD dst_unused:UNUSED_PAD src0_sel:WORD_1 src1_sel:DWORD
	v_and_b32_sdwa v131, v43, v242 dst_sel:DWORD dst_unused:UNUSED_PAD src0_sel:WORD_1 src1_sel:DWORD
	v_and_b32_sdwa v132, v44, v242 dst_sel:DWORD dst_unused:UNUSED_PAD src0_sel:WORD_1 src1_sel:DWORD
	v_and_b32_sdwa v133, v45, v242 dst_sel:DWORD dst_unused:UNUSED_PAD src0_sel:WORD_1 src1_sel:DWORD
	v_and_b32_sdwa v134, v46, v242 dst_sel:DWORD dst_unused:UNUSED_PAD src0_sel:WORD_1 src1_sel:DWORD
	v_and_b32_sdwa v135, v47, v242 dst_sel:DWORD dst_unused:UNUSED_PAD src0_sel:WORD_1 src1_sel:DWORD
	v_add3_u32 v40, v40, v128, s3
	v_add3_u32 v41, v41, v129, s3
	v_add3_u32 v42, v42, v130, s3
	v_add3_u32 v43, v43, v131, s3
	v_add3_u32 v44, v44, v132, s3
	v_add3_u32 v45, v45, v133, s3
	v_add3_u32 v46, v46, v134, s3
	v_add3_u32 v47, v47, v135, s3
	v_and_b32_e32 v41, 0xffff0000, v41
	v_and_b32_e32 v43, 0xffff0000, v43
	v_and_b32_e32 v45, 0xffff0000, v45
	v_and_b32_e32 v47, 0xffff0000, v47
	v_or_b32_sdwa v140, v41, v40 dst_sel:DWORD dst_unused:UNUSED_PAD src0_sel:DWORD src1_sel:WORD_1
	v_or_b32_sdwa v141, v43, v42 dst_sel:DWORD dst_unused:UNUSED_PAD src0_sel:DWORD src1_sel:WORD_1
	v_or_b32_sdwa v142, v45, v44 dst_sel:DWORD dst_unused:UNUSED_PAD src0_sel:DWORD src1_sel:WORD_1
	v_or_b32_sdwa v143, v47, v46 dst_sel:DWORD dst_unused:UNUSED_PAD src0_sel:DWORD src1_sel:WORD_1
	global_store_dwordx4 v243, v[140:143], s[84:85]
	s_add_u32 s84, s84, 0x1000
	s_addc_u32 s85, s85, 0
	v_and_b32_sdwa v128, v48, v242 dst_sel:DWORD dst_unused:UNUSED_PAD src0_sel:WORD_1 src1_sel:DWORD
	v_and_b32_sdwa v129, v49, v242 dst_sel:DWORD dst_unused:UNUSED_PAD src0_sel:WORD_1 src1_sel:DWORD
	v_and_b32_sdwa v130, v50, v242 dst_sel:DWORD dst_unused:UNUSED_PAD src0_sel:WORD_1 src1_sel:DWORD
	v_and_b32_sdwa v131, v51, v242 dst_sel:DWORD dst_unused:UNUSED_PAD src0_sel:WORD_1 src1_sel:DWORD
	v_and_b32_sdwa v132, v52, v242 dst_sel:DWORD dst_unused:UNUSED_PAD src0_sel:WORD_1 src1_sel:DWORD
	v_and_b32_sdwa v133, v53, v242 dst_sel:DWORD dst_unused:UNUSED_PAD src0_sel:WORD_1 src1_sel:DWORD
	v_and_b32_sdwa v134, v54, v242 dst_sel:DWORD dst_unused:UNUSED_PAD src0_sel:WORD_1 src1_sel:DWORD
	v_and_b32_sdwa v135, v55, v242 dst_sel:DWORD dst_unused:UNUSED_PAD src0_sel:WORD_1 src1_sel:DWORD
	v_add3_u32 v48, v48, v128, s3
	v_add3_u32 v49, v49, v129, s3
	v_add3_u32 v50, v50, v130, s3
	v_add3_u32 v51, v51, v131, s3
	v_add3_u32 v52, v52, v132, s3
	v_add3_u32 v53, v53, v133, s3
	v_add3_u32 v54, v54, v134, s3
	v_add3_u32 v55, v55, v135, s3
	v_and_b32_e32 v49, 0xffff0000, v49
	v_and_b32_e32 v51, 0xffff0000, v51
	v_and_b32_e32 v53, 0xffff0000, v53
	v_and_b32_e32 v55, 0xffff0000, v55
	v_or_b32_sdwa v136, v49, v48 dst_sel:DWORD dst_unused:UNUSED_PAD src0_sel:DWORD src1_sel:WORD_1
	v_or_b32_sdwa v137, v51, v50 dst_sel:DWORD dst_unused:UNUSED_PAD src0_sel:DWORD src1_sel:WORD_1
	v_or_b32_sdwa v138, v53, v52 dst_sel:DWORD dst_unused:UNUSED_PAD src0_sel:DWORD src1_sel:WORD_1
	v_or_b32_sdwa v139, v55, v54 dst_sel:DWORD dst_unused:UNUSED_PAD src0_sel:DWORD src1_sel:WORD_1
	global_store_dwordx4 v243, v[136:139], s[84:85]
	s_add_u32 s84, s84, 0x1000
	s_addc_u32 s85, s85, 0
	v_and_b32_sdwa v128, v56, v242 dst_sel:DWORD dst_unused:UNUSED_PAD src0_sel:WORD_1 src1_sel:DWORD
	v_and_b32_sdwa v129, v57, v242 dst_sel:DWORD dst_unused:UNUSED_PAD src0_sel:WORD_1 src1_sel:DWORD
	v_and_b32_sdwa v130, v58, v242 dst_sel:DWORD dst_unused:UNUSED_PAD src0_sel:WORD_1 src1_sel:DWORD
	v_and_b32_sdwa v131, v59, v242 dst_sel:DWORD dst_unused:UNUSED_PAD src0_sel:WORD_1 src1_sel:DWORD
	v_and_b32_sdwa v132, v60, v242 dst_sel:DWORD dst_unused:UNUSED_PAD src0_sel:WORD_1 src1_sel:DWORD
	v_and_b32_sdwa v133, v61, v242 dst_sel:DWORD dst_unused:UNUSED_PAD src0_sel:WORD_1 src1_sel:DWORD
	v_and_b32_sdwa v134, v62, v242 dst_sel:DWORD dst_unused:UNUSED_PAD src0_sel:WORD_1 src1_sel:DWORD
	v_and_b32_sdwa v135, v63, v242 dst_sel:DWORD dst_unused:UNUSED_PAD src0_sel:WORD_1 src1_sel:DWORD
	v_add3_u32 v56, v56, v128, s3
	v_add3_u32 v57, v57, v129, s3
	v_add3_u32 v58, v58, v130, s3
	v_add3_u32 v59, v59, v131, s3
	v_add3_u32 v60, v60, v132, s3
	v_add3_u32 v61, v61, v133, s3
	v_add3_u32 v62, v62, v134, s3
	v_add3_u32 v63, v63, v135, s3
	v_and_b32_e32 v57, 0xffff0000, v57
	v_and_b32_e32 v59, 0xffff0000, v59
	v_and_b32_e32 v61, 0xffff0000, v61
	v_and_b32_e32 v63, 0xffff0000, v63
	v_or_b32_sdwa v140, v57, v56 dst_sel:DWORD dst_unused:UNUSED_PAD src0_sel:DWORD src1_sel:WORD_1
	v_or_b32_sdwa v141, v59, v58 dst_sel:DWORD dst_unused:UNUSED_PAD src0_sel:DWORD src1_sel:WORD_1
	v_or_b32_sdwa v142, v61, v60 dst_sel:DWORD dst_unused:UNUSED_PAD src0_sel:DWORD src1_sel:WORD_1
	v_or_b32_sdwa v143, v63, v62 dst_sel:DWORD dst_unused:UNUSED_PAD src0_sel:DWORD src1_sel:WORD_1
	global_store_dwordx4 v243, v[140:143], s[84:85]
	s_add_u32 s84, s84, 0x1000
	s_addc_u32 s85, s85, 0
	s_cmp_eq_u32 s83, 1
	s_cbranch_scc1 .Lp6c_epdone
	s_cmp_eq_u32 s95, 1
	s_cbranch_scc0 .Lp6c_epdone
	v_mov_b32_e32 v0, v64
	v_mov_b32_e32 v1, v65
	v_mov_b32_e32 v2, v66
	v_mov_b32_e32 v3, v67
	v_mov_b32_e32 v4, v68
	v_mov_b32_e32 v5, v69
	v_mov_b32_e32 v6, v70
	v_mov_b32_e32 v7, v71
	v_mov_b32_e32 v8, v72
	v_mov_b32_e32 v9, v73
	v_mov_b32_e32 v10, v74
	v_mov_b32_e32 v11, v75
	v_mov_b32_e32 v12, v76
	v_mov_b32_e32 v13, v77
	v_mov_b32_e32 v14, v78
	v_mov_b32_e32 v15, v79
	v_mov_b32_e32 v16, v80
	v_mov_b32_e32 v17, v81
	v_mov_b32_e32 v18, v82
	v_mov_b32_e32 v19, v83
	v_mov_b32_e32 v20, v84
	v_mov_b32_e32 v21, v85
	v_mov_b32_e32 v22, v86
	v_mov_b32_e32 v23, v87
	v_mov_b32_e32 v24, v88
	v_mov_b32_e32 v25, v89
	v_mov_b32_e32 v26, v90
	v_mov_b32_e32 v27, v91
	v_mov_b32_e32 v28, v92
	v_mov_b32_e32 v29, v93
	v_mov_b32_e32 v30, v94
	v_mov_b32_e32 v31, v95
	v_mov_b32_e32 v32, v96
	v_mov_b32_e32 v33, v97
	v_mov_b32_e32 v34, v98
	v_mov_b32_e32 v35, v99
	v_mov_b32_e32 v36, v100
	v_mov_b32_e32 v37, v101
	v_mov_b32_e32 v38, v102
	v_mov_b32_e32 v39, v103
	v_mov_b32_e32 v40, v104
	v_mov_b32_e32 v41, v105
	v_mov_b32_e32 v42, v106
	v_mov_b32_e32 v43, v107
	v_mov_b32_e32 v44, v108
	v_mov_b32_e32 v45, v109
	v_mov_b32_e32 v46, v110
	v_mov_b32_e32 v47, v111
	v_mov_b32_e32 v48, v112
	v_mov_b32_e32 v49, v113
	v_mov_b32_e32 v50, v114
	v_mov_b32_e32 v51, v115
	v_mov_b32_e32 v52, v116
	v_mov_b32_e32 v53, v117
	v_mov_b32_e32 v54, v118
	v_mov_b32_e32 v55, v119
	v_mov_b32_e32 v56, v120
	v_mov_b32_e32 v57, v121
	v_mov_b32_e32 v58, v122
	v_mov_b32_e32 v59, v123
	v_mov_b32_e32 v60, v124
	v_mov_b32_e32 v61, v125
	v_mov_b32_e32 v62, v126
	v_mov_b32_e32 v63, v127
	s_mov_b32 s83, 1
	s_branch .Lp6c_ep
.Lp6c_epdone:
	v_lshrrev_b32_e32 v236, 3, v168
	v_lshrrev_b32_e32 v237, 4, v168
	v_xor_b32_e32 v237, v237, v168
	v_and_b32_e32 v237, 7, v237
	v_lshlrev_b32_e32 v237, 4, v237
	v_lshl_or_b32 v232, v236, 11, v237
	v_add_u32_e32 v233, 0x10000, v232
	v_add_u32_e32 v234, 0x20000, v232
	v_add_u32_e32 v235, 0x30000, v232
	s_load_dwordx2 s[90:91], s[0:1], 0xa0
	s_load_dwordx2 s[92:93], s[0:1], 0xa8
	v_lshrrev_b32_e32 v237, 6, v168
	s_nop 1
	v_readfirstlane_b32 s97, v237
	s_nop 3
	s_lshl_b32 s96, s97, 10
	s_add_u32 s96, s96, 16
	s_add_u32 s94, s81, s80
	s_cmp_lt_i32 s94, s82
	s_cselect_b32 s95, 1, 0
	s_cmp_lg_u64 s[20:21], 0
	s_cselect_b32 s95, 0, s95
	s_cmp_ge_u32 s94, 0x40
	s_cselect_b32 s97, 1, 0
	s_mul_i32 s100, s97, 0x40
	s_sub_u32 s100, s94, s100
	s_lshr_b32 s101, s100, 3
	s_and_b32 s100, s100, 7
	s_lshl_b32 s97, s97, 3
	s_add_u32 s100, s100, s97
	s_add_u32 s100, s100, s79
	s_cmp_lg_u32 s101, s74
	s_cselect_b32 s95, 0, s95
	s_cmp_eq_u32 s95, 1
	s_cselect_b32 s101, s100, s70
	s_mov_b32 s97, s101
	s_waitcnt lgkmcnt(0)
	s_lshl_b32 s94, s74, 18
	s_add_u32 s94, s94, 0xe40000
	s_add_u32 s98, s92, s94
	s_addc_u32 s99, s93, 0
	s_lshl_b32 s101, s101, 18
	s_add_u32 s92, s90, s101
	s_addc_u32 s93, s91, 0
	s_lshl_b32 s94, s70, 18
	s_add_u32 s90, s90, s94
	s_addc_u32 s91, s91, 0
	s_waitcnt vmcnt(0)
	s_barrier
	s_add_u32 m0, s96, 0x0
	s_nop 0
	global_load_lds_dwordx4 v232, s[90:91]
	s_add_u32 m0, s96, 0x1000
	s_nop 0
	global_load_lds_dwordx4 v233, s[90:91]
	s_add_u32 m0, s96, 0x2000
	s_nop 0
	global_load_lds_dwordx4 v234, s[90:91]
	s_add_u32 m0, s96, 0x3000
	s_nop 0
	global_load_lds_dwordx4 v235, s[90:91]
	s_add_u32 m0, s96, 0x4000
	s_nop 0
	global_load_lds_dwordx4 v232, s[92:93]
	s_add_u32 m0, s96, 0x5000
	s_nop 0
	global_load_lds_dwordx4 v233, s[92:93]
	s_add_u32 m0, s96, 0x6000
	s_nop 0
	global_load_lds_dwordx4 v234, s[92:93]
	s_add_u32 m0, s96, 0x7000
	s_nop 0
	global_load_lds_dwordx4 v235, s[92:93]
	s_add_u32 m0, s96, 0x8000
	s_nop 0
	global_load_lds_dwordx4 v232, s[98:99]
	s_add_u32 m0, s96, 0x9000
	s_nop 0
	global_load_lds_dwordx4 v233, s[98:99]
	s_add_u32 m0, s96, 0xa000
	s_nop 0
	global_load_lds_dwordx4 v234, s[98:99]
	s_add_u32 m0, s96, 0xb000
	s_nop 0
	global_load_lds_dwordx4 v235, s[98:99]
	s_add_u32 s90, s90, 0x80
	s_addc_u32 s91, s91, 0
	s_add_u32 s92, s92, 0x80
	s_addc_u32 s93, s93, 0
	s_add_u32 s98, s98, 0x80
	s_addc_u32 s99, s99, 0
	v_mov_b32_e32 v0, 0
	v_mov_b32_e32 v1, v0
	v_mov_b32_e32 v2, v0
	v_mov_b32_e32 v3, v0
	v_mov_b32_e32 v4, v0
	v_mov_b32_e32 v5, v0
	v_mov_b32_e32 v6, v0
	v_mov_b32_e32 v7, v0
	v_mov_b32_e32 v8, v0
	v_mov_b32_e32 v9, v0
	v_mov_b32_e32 v10, v0
	v_mov_b32_e32 v11, v0
	v_mov_b32_e32 v12, v0
	v_mov_b32_e32 v13, v0
	v_mov_b32_e32 v14, v0
	v_mov_b32_e32 v15, v0
	v_mov_b32_e32 v16, v0
	v_mov_b32_e32 v17, v0
	v_mov_b32_e32 v18, v0
	v_mov_b32_e32 v19, v0
	v_mov_b32_e32 v20, v0
	v_mov_b32_e32 v21, v0
	v_mov_b32_e32 v22, v0
	v_mov_b32_e32 v23, v0
	v_mov_b32_e32 v24, v0
	v_mov_b32_e32 v25, v0
	v_mov_b32_e32 v26, v0
	v_mov_b32_e32 v27, v0
	v_mov_b32_e32 v28, v0
	v_mov_b32_e32 v29, v0
	v_mov_b32_e32 v30, v0
	v_mov_b32_e32 v31, v0
	v_mov_b32_e32 v32, v0
	v_mov_b32_e32 v33, v0
	v_mov_b32_e32 v34, v0
	v_mov_b32_e32 v35, v0
	v_mov_b32_e32 v36, v0
	v_mov_b32_e32 v37, v0
	v_mov_b32_e32 v38, v0
	v_mov_b32_e32 v39, v0
	v_mov_b32_e32 v40, v0
	v_mov_b32_e32 v41, v0
	v_mov_b32_e32 v42, v0
	v_mov_b32_e32 v43, v0
	v_mov_b32_e32 v44, v0
	v_mov_b32_e32 v45, v0
	v_mov_b32_e32 v46, v0
	v_mov_b32_e32 v47, v0
	v_mov_b32_e32 v48, v0
	v_mov_b32_e32 v49, v0
	v_mov_b32_e32 v50, v0
	v_mov_b32_e32 v51, v0
	v_mov_b32_e32 v52, v0
	v_mov_b32_e32 v53, v0
	v_mov_b32_e32 v54, v0
	v_mov_b32_e32 v55, v0
	v_mov_b32_e32 v56, v0
	v_mov_b32_e32 v57, v0
	v_mov_b32_e32 v58, v0
	v_mov_b32_e32 v59, v0
	v_mov_b32_e32 v60, v0
	v_mov_b32_e32 v61, v0
	v_mov_b32_e32 v62, v0
	v_mov_b32_e32 v63, v0
	v_mov_b32_e32 v64, v0
	v_mov_b32_e32 v65, v0
	v_mov_b32_e32 v66, v0
	v_mov_b32_e32 v67, v0
	v_mov_b32_e32 v68, v0
	v_mov_b32_e32 v69, v0
	v_mov_b32_e32 v70, v0
	v_mov_b32_e32 v71, v0
	v_mov_b32_e32 v72, v0
	v_mov_b32_e32 v73, v0
	v_mov_b32_e32 v74, v0
	v_mov_b32_e32 v75, v0
	v_mov_b32_e32 v76, v0
	v_mov_b32_e32 v77, v0
	v_mov_b32_e32 v78, v0
	v_mov_b32_e32 v79, v0
	v_mov_b32_e32 v80, v0
	v_mov_b32_e32 v81, v0
	v_mov_b32_e32 v82, v0
	v_mov_b32_e32 v83, v0
	v_mov_b32_e32 v84, v0
	v_mov_b32_e32 v85, v0
	v_mov_b32_e32 v86, v0
	v_mov_b32_e32 v87, v0
	v_mov_b32_e32 v88, v0
	v_mov_b32_e32 v89, v0
	v_mov_b32_e32 v90, v0
	v_mov_b32_e32 v91, v0
	v_mov_b32_e32 v92, v0
	v_mov_b32_e32 v93, v0
	v_mov_b32_e32 v94, v0
	v_mov_b32_e32 v95, v0
	v_mov_b32_e32 v96, v0
	v_mov_b32_e32 v97, v0
	v_mov_b32_e32 v98, v0
	v_mov_b32_e32 v99, v0
	v_mov_b32_e32 v100, v0
	v_mov_b32_e32 v101, v0
	v_mov_b32_e32 v102, v0
	v_mov_b32_e32 v103, v0
	v_mov_b32_e32 v104, v0
	v_mov_b32_e32 v105, v0
	v_mov_b32_e32 v106, v0
	v_mov_b32_e32 v107, v0
	v_mov_b32_e32 v108, v0
	v_mov_b32_e32 v109, v0
	v_mov_b32_e32 v110, v0
	v_mov_b32_e32 v111, v0
	v_mov_b32_e32 v112, v0
	v_mov_b32_e32 v113, v0
	v_mov_b32_e32 v114, v0
	v_mov_b32_e32 v115, v0
	v_mov_b32_e32 v116, v0
	v_mov_b32_e32 v117, v0
	v_mov_b32_e32 v118, v0
	v_mov_b32_e32 v119, v0
	v_mov_b32_e32 v120, v0
	v_mov_b32_e32 v121, v0
	v_mov_b32_e32 v122, v0
	v_mov_b32_e32 v123, v0
	v_mov_b32_e32 v124, v0
	v_mov_b32_e32 v125, v0
	v_mov_b32_e32 v126, v0
	v_mov_b32_e32 v127, v0
	s_mov_b32 s94, 0

.Lp6d_ep:
	s_add_u32 s28, s22, 0x1000
	s_addc_u32 s29, s23, 0
	global_load_dwordx4 v[128:131], v244, s[28:29]
	global_load_dwordx4 v[132:135], v244, s[28:29] offset:64
	global_load_dwordx4 v[136:139], v244, s[28:29] offset:128
	global_load_dwordx4 v[140:143], v244, s[28:29] offset:192
	s_cmp_eq_u32 s83, 1
	s_cselect_b32 s75, s97, s70
	v_lshrrev_b32_e32 v249, 1, v168
	v_and_b32_e32 v249, 0x1c0, v249
	v_and_b32_e32 v250, 15, v168
	v_or_b32_e32 v249, v249, v250
	v_lshl_add_u32 v249, s75, 7, v249
	v_lshlrev_b32_e32 v249, 11, v249
	v_bfe_u32 v250, v168, 4, 2
	v_lshlrev_b32_e32 v246, 3, v250
	v_and_b32_e32 v250, 1, v250
	v_mul_u32_u24_e32 v250, 24, v250
	v_add3_u32 v249, v249, v250, v246
	v_bfe_u32 v250, v168, 6, 1
	s_lshl_b32 s71, s74, 8
	v_lshl_add_u32 v245, v250, 7, v249
	v_add_u32_e32 v245, s71, v245
	v_add_u32_e32 v246, 0x8000, v245
	v_add_u32_e32 v247, 0x10000, v245
	v_add_u32_e32 v248, 0x18000, v245
	s_lshl_b32 s71, s83, 25
	s_add_u32 s86, s24, s71
	s_addc_u32 s87, s25, 0
	s_lshl_b32 s71, s83, 25
	s_add_u32 s71, s71, 0x8000
	s_add_u32 s88, s24, s71
	s_addc_u32 s89, s25, 0
	global_load_dwordx4 v[148:151], v243, s[86:87]
	s_add_u32 s86, s86, 0x1000
	s_addc_u32 s87, s87, 0
	global_load_dwordx4 v[164:167], v243, s[88:89]
	s_add_u32 s88, s88, 0x1000
	s_addc_u32 s89, s89, 0
	global_load_dwordx4 v[152:155], v243, s[86:87]
	s_add_u32 s86, s86, 0x1000
	s_addc_u32 s87, s87, 0
	global_load_dwordx4 v[172:175], v243, s[88:89]
	s_add_u32 s88, s88, 0x1000
	s_addc_u32 s89, s89, 0
	global_load_dwordx4 v[156:159], v243, s[86:87]
	s_add_u32 s86, s86, 0x1000
	s_addc_u32 s87, s87, 0
	global_load_dwordx4 v[176:179], v243, s[88:89]
	s_add_u32 s88, s88, 0x1000
	s_addc_u32 s89, s89, 0
	global_load_dwordx4 v[160:163], v243, s[86:87]
	s_add_u32 s86, s86, 0x1000
	s_addc_u32 s87, s87, 0
	global_load_dwordx4 v[180:183], v243, s[88:89]
	s_add_u32 s88, s88, 0x1000
	s_addc_u32 s89, s89, 0
	s_waitcnt vmcnt(6)
	v_add_f32_e32 v184, v0, v128
	v_add_f32_e32 v185, v1, v129
	v_add_f32_e32 v186, v2, v130
	v_add_f32_e32 v187, v3, v131
	v_add_f32_e32 v188, v4, v132
	v_add_f32_e32 v189, v5, v133
	v_add_f32_e32 v190, v6, v134
	v_add_f32_e32 v191, v7, v135
	v_mul_f32_e32 v184, 0xbfb8aa3b, v184
	v_mul_f32_e32 v185, 0xbfb8aa3b, v185
	v_mul_f32_e32 v186, 0xbfb8aa3b, v186
	v_mul_f32_e32 v187, 0xbfb8aa3b, v187
	v_mul_f32_e32 v188, 0xbfb8aa3b, v188
	v_mul_f32_e32 v189, 0xbfb8aa3b, v189
	v_mul_f32_e32 v190, 0xbfb8aa3b, v190
	v_mul_f32_e32 v191, 0xbfb8aa3b, v191
	v_exp_f32_e32 v192, v184
	v_exp_f32_e32 v193, v185
	v_exp_f32_e32 v194, v186
	v_exp_f32_e32 v195, v187
	v_exp_f32_e32 v196, v188
	v_exp_f32_e32 v197, v189
	v_exp_f32_e32 v198, v190
	v_exp_f32_e32 v199, v191
	v_add_f32_e32 v192, 1.0, v192
	v_add_f32_e32 v193, 1.0, v193
	v_add_f32_e32 v194, 1.0, v194
	v_add_f32_e32 v195, 1.0, v195
	v_add_f32_e32 v196, 1.0, v196
	v_add_f32_e32 v197, 1.0, v197
	v_add_f32_e32 v198, 1.0, v198
	v_add_f32_e32 v199, 1.0, v199
	v_div_scale_f32 v200, s[76:77], v192, v192, 1.0
	v_div_scale_f32 v201, s[76:77], v193, v193, 1.0
	v_div_scale_f32 v202, s[76:77], v194, v194, 1.0
	v_div_scale_f32 v203, s[76:77], v195, v195, 1.0
	v_div_scale_f32 v204, s[76:77], v196, v196, 1.0
	v_div_scale_f32 v205, s[76:77], v197, v197, 1.0
	v_div_scale_f32 v206, s[76:77], v198, v198, 1.0
	v_div_scale_f32 v207, s[76:77], v199, v199, 1.0
	v_rcp_f32_e32 v208, v200
	v_rcp_f32_e32 v209, v201
	v_rcp_f32_e32 v210, v202
	v_rcp_f32_e32 v211, v203
	v_rcp_f32_e32 v212, v204
	v_rcp_f32_e32 v213, v205
	v_rcp_f32_e32 v214, v206
	v_rcp_f32_e32 v215, v207
	v_fma_f32 v184, -v200, v208, 1.0
	v_fma_f32 v185, -v201, v209, 1.0
	v_fma_f32 v186, -v202, v210, 1.0
	v_fma_f32 v187, -v203, v211, 1.0
	v_fma_f32 v188, -v204, v212, 1.0
	v_fma_f32 v189, -v205, v213, 1.0
	v_fma_f32 v190, -v206, v214, 1.0
	v_fma_f32 v191, -v207, v215, 1.0
	v_fmac_f32_e32 v208, v184, v208
	v_fmac_f32_e32 v209, v185, v209
	v_fmac_f32_e32 v210, v186, v210
	v_fmac_f32_e32 v211, v187, v211
	v_fmac_f32_e32 v212, v188, v212
	v_fmac_f32_e32 v213, v189, v213
	v_fmac_f32_e32 v214, v190, v214
	v_fmac_f32_e32 v215, v191, v215
	v_div_scale_f32 v216, vcc, 1.0, v192, 1.0
	v_mul_f32_e32 v224, v216, v208
	v_fma_f32 v184, -v200, v224, v216
	v_fmac_f32_e32 v224, v184, v208
	v_fma_f32 v216, -v200, v224, v216
	v_div_fmas_f32 v216, v216, v208, v224
	v_div_fixup_f32 v184, v216, v192, 1.0
	v_div_scale_f32 v217, vcc, 1.0, v193, 1.0
	v_mul_f32_e32 v225, v217, v209
	v_fma_f32 v185, -v201, v225, v217
	v_fmac_f32_e32 v225, v185, v209
	v_fma_f32 v217, -v201, v225, v217
	v_div_fmas_f32 v217, v217, v209, v225
	v_div_fixup_f32 v185, v217, v193, 1.0
	v_div_scale_f32 v218, vcc, 1.0, v194, 1.0
	v_mul_f32_e32 v226, v218, v210
	v_fma_f32 v186, -v202, v226, v218
	v_fmac_f32_e32 v226, v186, v210
	v_fma_f32 v218, -v202, v226, v218
	v_div_fmas_f32 v218, v218, v210, v226
	v_div_fixup_f32 v186, v218, v194, 1.0
	v_div_scale_f32 v219, vcc, 1.0, v195, 1.0
	v_mul_f32_e32 v227, v219, v211
	v_fma_f32 v187, -v203, v227, v219
	v_fmac_f32_e32 v227, v187, v211
	v_fma_f32 v219, -v203, v227, v219
	v_div_fmas_f32 v219, v219, v211, v227
	v_div_fixup_f32 v187, v219, v195, 1.0
	v_div_scale_f32 v220, vcc, 1.0, v196, 1.0
	v_mul_f32_e32 v228, v220, v212
	v_fma_f32 v188, -v204, v228, v220
	v_fmac_f32_e32 v228, v188, v212
	v_fma_f32 v220, -v204, v228, v220
	v_div_fmas_f32 v220, v220, v212, v228
	v_div_fixup_f32 v188, v220, v196, 1.0
	v_div_scale_f32 v221, vcc, 1.0, v197, 1.0
	v_mul_f32_e32 v229, v221, v213
	v_fma_f32 v189, -v205, v229, v221
	v_fmac_f32_e32 v229, v189, v213
	v_fma_f32 v221, -v205, v229, v221
	v_div_fmas_f32 v221, v221, v213, v229
	v_div_fixup_f32 v189, v221, v197, 1.0
	v_div_scale_f32 v222, vcc, 1.0, v198, 1.0
	v_mul_f32_e32 v230, v222, v214
	v_fma_f32 v190, -v206, v230, v222
	v_fmac_f32_e32 v230, v190, v214
	v_fma_f32 v222, -v206, v230, v222
	v_div_fmas_f32 v222, v222, v214, v230
	v_div_fixup_f32 v190, v222, v198, 1.0
	v_div_scale_f32 v223, vcc, 1.0, v199, 1.0
	v_mul_f32_e32 v231, v223, v215
	v_fma_f32 v191, -v207, v231, v223
	v_fmac_f32_e32 v231, v191, v215
	v_fma_f32 v223, -v207, v231, v223
	v_div_fmas_f32 v223, v223, v215, v231
	v_div_fixup_f32 v191, v223, v199, 1.0
	v_lshlrev_b32_e32 v192, 16, v148
	v_and_b32_e32 v193, 0xffff0000, v148
	v_lshlrev_b32_e32 v200, 16, v164
	v_and_b32_e32 v201, 0xffff0000, v164
	v_lshlrev_b32_e32 v194, 16, v149
	v_and_b32_e32 v195, 0xffff0000, v149
	v_lshlrev_b32_e32 v202, 16, v165
	v_and_b32_e32 v203, 0xffff0000, v165
	v_lshlrev_b32_e32 v196, 16, v150
	v_and_b32_e32 v197, 0xffff0000, v150
	v_lshlrev_b32_e32 v204, 16, v166
	v_and_b32_e32 v205, 0xffff0000, v166
	v_lshlrev_b32_e32 v198, 16, v151
	v_and_b32_e32 v199, 0xffff0000, v151
	v_lshlrev_b32_e32 v206, 16, v167
	v_and_b32_e32 v207, 0xffff0000, v167
	v_fma_f32 v184, v184, v200, v192
	v_fma_f32 v185, v185, v201, v193
	v_fma_f32 v186, v186, v202, v194
	v_fma_f32 v187, v187, v203, v195
	v_fma_f32 v188, v188, v204, v196
	v_fma_f32 v189, v189, v205, v197
	v_fma_f32 v190, v190, v206, v198
	v_fma_f32 v191, v191, v207, v199
	v_and_b32_sdwa v208, v184, v242 dst_sel:DWORD dst_unused:UNUSED_PAD src0_sel:WORD_1 src1_sel:DWORD
	v_and_b32_sdwa v209, v185, v242 dst_sel:DWORD dst_unused:UNUSED_PAD src0_sel:WORD_1 src1_sel:DWORD
	v_and_b32_sdwa v210, v186, v242 dst_sel:DWORD dst_unused:UNUSED_PAD src0_sel:WORD_1 src1_sel:DWORD
	v_and_b32_sdwa v211, v187, v242 dst_sel:DWORD dst_unused:UNUSED_PAD src0_sel:WORD_1 src1_sel:DWORD
	v_and_b32_sdwa v212, v188, v242 dst_sel:DWORD dst_unused:UNUSED_PAD src0_sel:WORD_1 src1_sel:DWORD
	v_and_b32_sdwa v213, v189, v242 dst_sel:DWORD dst_unused:UNUSED_PAD src0_sel:WORD_1 src1_sel:DWORD
	v_and_b32_sdwa v214, v190, v242 dst_sel:DWORD dst_unused:UNUSED_PAD src0_sel:WORD_1 src1_sel:DWORD
	v_and_b32_sdwa v215, v191, v242 dst_sel:DWORD dst_unused:UNUSED_PAD src0_sel:WORD_1 src1_sel:DWORD
	v_add3_u32 v184, v184, v208, s3
	v_add3_u32 v185, v185, v209, s3
	v_add3_u32 v186, v186, v210, s3
	v_add3_u32 v187, v187, v211, s3
	v_add3_u32 v188, v188, v212, s3
	v_add3_u32 v189, v189, v213, s3
	v_add3_u32 v190, v190, v214, s3
	v_add3_u32 v191, v191, v215, s3
	v_and_b32_e32 v185, 0xffff0000, v185
	v_and_b32_e32 v187, 0xffff0000, v187
	v_and_b32_e32 v189, 0xffff0000, v189
	v_and_b32_e32 v191, 0xffff0000, v191
	v_or_b32_sdwa v216, v185, v184 dst_sel:DWORD dst_unused:UNUSED_PAD src0_sel:DWORD src1_sel:WORD_1
	v_or_b32_sdwa v217, v187, v186 dst_sel:DWORD dst_unused:UNUSED_PAD src0_sel:DWORD src1_sel:WORD_1
	v_or_b32_sdwa v218, v189, v188 dst_sel:DWORD dst_unused:UNUSED_PAD src0_sel:DWORD src1_sel:WORD_1
	v_or_b32_sdwa v219, v191, v190 dst_sel:DWORD dst_unused:UNUSED_PAD src0_sel:DWORD src1_sel:WORD_1
	s_nop 1
	v_permlane16_swap_b32_e32 v216, v218
	v_permlane16_swap_b32_e32 v217, v219
	global_store_dwordx4 v245, v[216:219], s[26:27]
	s_waitcnt vmcnt(5)
	v_add_f32_e32 v184, v8, v136
	v_add_f32_e32 v185, v9, v137
	v_add_f32_e32 v186, v10, v138
	v_add_f32_e32 v187, v11, v139
	v_add_f32_e32 v188, v12, v140
	v_add_f32_e32 v189, v13, v141
	v_add_f32_e32 v190, v14, v142
	v_add_f32_e32 v191, v15, v143
	v_mul_f32_e32 v184, 0xbfb8aa3b, v184
	v_mul_f32_e32 v185, 0xbfb8aa3b, v185
	v_mul_f32_e32 v186, 0xbfb8aa3b, v186
	v_mul_f32_e32 v187, 0xbfb8aa3b, v187
	v_mul_f32_e32 v188, 0xbfb8aa3b, v188
	v_mul_f32_e32 v189, 0xbfb8aa3b, v189
	v_mul_f32_e32 v190, 0xbfb8aa3b, v190
	v_mul_f32_e32 v191, 0xbfb8aa3b, v191
	v_exp_f32_e32 v192, v184
	v_exp_f32_e32 v193, v185
	v_exp_f32_e32 v194, v186
	v_exp_f32_e32 v195, v187
	v_exp_f32_e32 v196, v188
	v_exp_f32_e32 v197, v189
	v_exp_f32_e32 v198, v190
	v_exp_f32_e32 v199, v191
	v_add_f32_e32 v192, 1.0, v192
	v_add_f32_e32 v193, 1.0, v193
	v_add_f32_e32 v194, 1.0, v194
	v_add_f32_e32 v195, 1.0, v195
	v_add_f32_e32 v196, 1.0, v196
	v_add_f32_e32 v197, 1.0, v197
	v_add_f32_e32 v198, 1.0, v198
	v_add_f32_e32 v199, 1.0, v199
	v_div_scale_f32 v200, s[76:77], v192, v192, 1.0
	v_div_scale_f32 v201, s[76:77], v193, v193, 1.0
	v_div_scale_f32 v202, s[76:77], v194, v194, 1.0
	v_div_scale_f32 v203, s[76:77], v195, v195, 1.0
	v_div_scale_f32 v204, s[76:77], v196, v196, 1.0
	v_div_scale_f32 v205, s[76:77], v197, v197, 1.0
	v_div_scale_f32 v206, s[76:77], v198, v198, 1.0
	v_div_scale_f32 v207, s[76:77], v199, v199, 1.0
	v_rcp_f32_e32 v208, v200
	v_rcp_f32_e32 v209, v201
	v_rcp_f32_e32 v210, v202
	v_rcp_f32_e32 v211, v203
	v_rcp_f32_e32 v212, v204
	v_rcp_f32_e32 v213, v205
	v_rcp_f32_e32 v214, v206
	v_rcp_f32_e32 v215, v207
	v_fma_f32 v184, -v200, v208, 1.0
	v_fma_f32 v185, -v201, v209, 1.0
	v_fma_f32 v186, -v202, v210, 1.0
	v_fma_f32 v187, -v203, v211, 1.0
	v_fma_f32 v188, -v204, v212, 1.0
	v_fma_f32 v189, -v205, v213, 1.0
	v_fma_f32 v190, -v206, v214, 1.0
	v_fma_f32 v191, -v207, v215, 1.0
	v_fmac_f32_e32 v208, v184, v208
	v_fmac_f32_e32 v209, v185, v209
	v_fmac_f32_e32 v210, v186, v210
	v_fmac_f32_e32 v211, v187, v211
	v_fmac_f32_e32 v212, v188, v212
	v_fmac_f32_e32 v213, v189, v213
	v_fmac_f32_e32 v214, v190, v214
	v_fmac_f32_e32 v215, v191, v215
	v_div_scale_f32 v216, vcc, 1.0, v192, 1.0
	v_mul_f32_e32 v224, v216, v208
	v_fma_f32 v184, -v200, v224, v216
	v_fmac_f32_e32 v224, v184, v208
	v_fma_f32 v216, -v200, v224, v216
	v_div_fmas_f32 v216, v216, v208, v224
	v_div_fixup_f32 v184, v216, v192, 1.0
	v_div_scale_f32 v217, vcc, 1.0, v193, 1.0
	v_mul_f32_e32 v225, v217, v209
	v_fma_f32 v185, -v201, v225, v217
	v_fmac_f32_e32 v225, v185, v209
	v_fma_f32 v217, -v201, v225, v217
	v_div_fmas_f32 v217, v217, v209, v225
	v_div_fixup_f32 v185, v217, v193, 1.0
	v_div_scale_f32 v218, vcc, 1.0, v194, 1.0
	v_mul_f32_e32 v226, v218, v210
	v_fma_f32 v186, -v202, v226, v218
	v_fmac_f32_e32 v226, v186, v210
	v_fma_f32 v218, -v202, v226, v218
	v_div_fmas_f32 v218, v218, v210, v226
	v_div_fixup_f32 v186, v218, v194, 1.0
	v_div_scale_f32 v219, vcc, 1.0, v195, 1.0
	v_mul_f32_e32 v227, v219, v211
	v_fma_f32 v187, -v203, v227, v219
	v_fmac_f32_e32 v227, v187, v211
	v_fma_f32 v219, -v203, v227, v219
	v_div_fmas_f32 v219, v219, v211, v227
	v_div_fixup_f32 v187, v219, v195, 1.0
	v_div_scale_f32 v220, vcc, 1.0, v196, 1.0
	v_mul_f32_e32 v228, v220, v212
	v_fma_f32 v188, -v204, v228, v220
	v_fmac_f32_e32 v228, v188, v212
	v_fma_f32 v220, -v204, v228, v220
	v_div_fmas_f32 v220, v220, v212, v228
	v_div_fixup_f32 v188, v220, v196, 1.0
	v_div_scale_f32 v221, vcc, 1.0, v197, 1.0
	v_mul_f32_e32 v229, v221, v213
	v_fma_f32 v189, -v205, v229, v221
	v_fmac_f32_e32 v229, v189, v213
	v_fma_f32 v221, -v205, v229, v221
	v_div_fmas_f32 v221, v221, v213, v229
	v_div_fixup_f32 v189, v221, v197, 1.0
	v_div_scale_f32 v222, vcc, 1.0, v198, 1.0
	v_mul_f32_e32 v230, v222, v214
	v_fma_f32 v190, -v206, v230, v222
	v_fmac_f32_e32 v230, v190, v214
	v_fma_f32 v222, -v206, v230, v222
	v_div_fmas_f32 v222, v222, v214, v230
	v_div_fixup_f32 v190, v222, v198, 1.0
	v_div_scale_f32 v223, vcc, 1.0, v199, 1.0
	v_mul_f32_e32 v231, v223, v215
	v_fma_f32 v191, -v207, v231, v223
	v_fmac_f32_e32 v231, v191, v215
	v_fma_f32 v223, -v207, v231, v223
	v_div_fmas_f32 v223, v223, v215, v231
	v_div_fixup_f32 v191, v223, v199, 1.0
	v_lshlrev_b32_e32 v192, 16, v152
	v_and_b32_e32 v193, 0xffff0000, v152
	v_lshlrev_b32_e32 v200, 16, v172
	v_and_b32_e32 v201, 0xffff0000, v172
	v_lshlrev_b32_e32 v194, 16, v153
	v_and_b32_e32 v195, 0xffff0000, v153
	v_lshlrev_b32_e32 v202, 16, v173
	v_and_b32_e32 v203, 0xffff0000, v173
	v_lshlrev_b32_e32 v196, 16, v154
	v_and_b32_e32 v197, 0xffff0000, v154
	v_lshlrev_b32_e32 v204, 16, v174
	v_and_b32_e32 v205, 0xffff0000, v174
	v_lshlrev_b32_e32 v198, 16, v155
	v_and_b32_e32 v199, 0xffff0000, v155
	v_lshlrev_b32_e32 v206, 16, v175
	v_and_b32_e32 v207, 0xffff0000, v175
	v_fma_f32 v184, v184, v200, v192
	v_fma_f32 v185, v185, v201, v193
	v_fma_f32 v186, v186, v202, v194
	v_fma_f32 v187, v187, v203, v195
	v_fma_f32 v188, v188, v204, v196
	v_fma_f32 v189, v189, v205, v197
	v_fma_f32 v190, v190, v206, v198
	v_fma_f32 v191, v191, v207, v199
	v_and_b32_sdwa v208, v184, v242 dst_sel:DWORD dst_unused:UNUSED_PAD src0_sel:WORD_1 src1_sel:DWORD
	v_and_b32_sdwa v209, v185, v242 dst_sel:DWORD dst_unused:UNUSED_PAD src0_sel:WORD_1 src1_sel:DWORD
	v_and_b32_sdwa v210, v186, v242 dst_sel:DWORD dst_unused:UNUSED_PAD src0_sel:WORD_1 src1_sel:DWORD
	v_and_b32_sdwa v211, v187, v242 dst_sel:DWORD dst_unused:UNUSED_PAD src0_sel:WORD_1 src1_sel:DWORD
	v_and_b32_sdwa v212, v188, v242 dst_sel:DWORD dst_unused:UNUSED_PAD src0_sel:WORD_1 src1_sel:DWORD
	v_and_b32_sdwa v213, v189, v242 dst_sel:DWORD dst_unused:UNUSED_PAD src0_sel:WORD_1 src1_sel:DWORD
	v_and_b32_sdwa v214, v190, v242 dst_sel:DWORD dst_unused:UNUSED_PAD src0_sel:WORD_1 src1_sel:DWORD
	v_and_b32_sdwa v215, v191, v242 dst_sel:DWORD dst_unused:UNUSED_PAD src0_sel:WORD_1 src1_sel:DWORD
	v_add3_u32 v184, v184, v208, s3
	v_add3_u32 v185, v185, v209, s3
	v_add3_u32 v186, v186, v210, s3
	v_add3_u32 v187, v187, v211, s3
	v_add3_u32 v188, v188, v212, s3
	v_add3_u32 v189, v189, v213, s3
	v_add3_u32 v190, v190, v214, s3
	v_add3_u32 v191, v191, v215, s3
	v_and_b32_e32 v185, 0xffff0000, v185
	v_and_b32_e32 v187, 0xffff0000, v187
	v_and_b32_e32 v189, 0xffff0000, v189
	v_and_b32_e32 v191, 0xffff0000, v191
	v_or_b32_sdwa v220, v185, v184 dst_sel:DWORD dst_unused:UNUSED_PAD src0_sel:DWORD src1_sel:WORD_1
	v_or_b32_sdwa v221, v187, v186 dst_sel:DWORD dst_unused:UNUSED_PAD src0_sel:DWORD src1_sel:WORD_1
	v_or_b32_sdwa v222, v189, v188 dst_sel:DWORD dst_unused:UNUSED_PAD src0_sel:DWORD src1_sel:WORD_1
	v_or_b32_sdwa v223, v191, v190 dst_sel:DWORD dst_unused:UNUSED_PAD src0_sel:DWORD src1_sel:WORD_1
	s_nop 1
	v_permlane16_swap_b32_e32 v220, v222
	v_permlane16_swap_b32_e32 v221, v223
	global_store_dwordx4 v245, v[220:223], s[26:27] offset:64
	s_waitcnt vmcnt(4)
	v_add_f32_e32 v184, v16, v128
	v_add_f32_e32 v185, v17, v129
	v_add_f32_e32 v186, v18, v130
	v_add_f32_e32 v187, v19, v131
	v_add_f32_e32 v188, v20, v132
	v_add_f32_e32 v189, v21, v133
	v_add_f32_e32 v190, v22, v134
	v_add_f32_e32 v191, v23, v135
	v_mul_f32_e32 v184, 0xbfb8aa3b, v184
	v_mul_f32_e32 v185, 0xbfb8aa3b, v185
	v_mul_f32_e32 v186, 0xbfb8aa3b, v186
	v_mul_f32_e32 v187, 0xbfb8aa3b, v187
	v_mul_f32_e32 v188, 0xbfb8aa3b, v188
	v_mul_f32_e32 v189, 0xbfb8aa3b, v189
	v_mul_f32_e32 v190, 0xbfb8aa3b, v190
	v_mul_f32_e32 v191, 0xbfb8aa3b, v191
	v_exp_f32_e32 v192, v184
	v_exp_f32_e32 v193, v185
	v_exp_f32_e32 v194, v186
	v_exp_f32_e32 v195, v187
	v_exp_f32_e32 v196, v188
	v_exp_f32_e32 v197, v189
	v_exp_f32_e32 v198, v190
	v_exp_f32_e32 v199, v191
	v_add_f32_e32 v192, 1.0, v192
	v_add_f32_e32 v193, 1.0, v193
	v_add_f32_e32 v194, 1.0, v194
	v_add_f32_e32 v195, 1.0, v195
	v_add_f32_e32 v196, 1.0, v196
	v_add_f32_e32 v197, 1.0, v197
	v_add_f32_e32 v198, 1.0, v198
	v_add_f32_e32 v199, 1.0, v199
	v_div_scale_f32 v200, s[76:77], v192, v192, 1.0
	v_div_scale_f32 v201, s[76:77], v193, v193, 1.0
	v_div_scale_f32 v202, s[76:77], v194, v194, 1.0
	v_div_scale_f32 v203, s[76:77], v195, v195, 1.0
	v_div_scale_f32 v204, s[76:77], v196, v196, 1.0
	v_div_scale_f32 v205, s[76:77], v197, v197, 1.0
	v_div_scale_f32 v206, s[76:77], v198, v198, 1.0
	v_div_scale_f32 v207, s[76:77], v199, v199, 1.0
	v_rcp_f32_e32 v208, v200
	v_rcp_f32_e32 v209, v201
	v_rcp_f32_e32 v210, v202
	v_rcp_f32_e32 v211, v203
	v_rcp_f32_e32 v212, v204
	v_rcp_f32_e32 v213, v205
	v_rcp_f32_e32 v214, v206
	v_rcp_f32_e32 v215, v207
	v_fma_f32 v184, -v200, v208, 1.0
	v_fma_f32 v185, -v201, v209, 1.0
	v_fma_f32 v186, -v202, v210, 1.0
	v_fma_f32 v187, -v203, v211, 1.0
	v_fma_f32 v188, -v204, v212, 1.0
	v_fma_f32 v189, -v205, v213, 1.0
	v_fma_f32 v190, -v206, v214, 1.0
	v_fma_f32 v191, -v207, v215, 1.0
	v_fmac_f32_e32 v208, v184, v208
	v_fmac_f32_e32 v209, v185, v209
	v_fmac_f32_e32 v210, v186, v210
	v_fmac_f32_e32 v211, v187, v211
	v_fmac_f32_e32 v212, v188, v212
	v_fmac_f32_e32 v213, v189, v213
	v_fmac_f32_e32 v214, v190, v214
	v_fmac_f32_e32 v215, v191, v215
	v_div_scale_f32 v216, vcc, 1.0, v192, 1.0
	v_mul_f32_e32 v224, v216, v208
	v_fma_f32 v184, -v200, v224, v216
	v_fmac_f32_e32 v224, v184, v208
	v_fma_f32 v216, -v200, v224, v216
	v_div_fmas_f32 v216, v216, v208, v224
	v_div_fixup_f32 v184, v216, v192, 1.0
	v_div_scale_f32 v217, vcc, 1.0, v193, 1.0
	v_mul_f32_e32 v225, v217, v209
	v_fma_f32 v185, -v201, v225, v217
	v_fmac_f32_e32 v225, v185, v209
	v_fma_f32 v217, -v201, v225, v217
	v_div_fmas_f32 v217, v217, v209, v225
	v_div_fixup_f32 v185, v217, v193, 1.0
	v_div_scale_f32 v218, vcc, 1.0, v194, 1.0
	v_mul_f32_e32 v226, v218, v210
	v_fma_f32 v186, -v202, v226, v218
	v_fmac_f32_e32 v226, v186, v210
	v_fma_f32 v218, -v202, v226, v218
	v_div_fmas_f32 v218, v218, v210, v226
	v_div_fixup_f32 v186, v218, v194, 1.0
	v_div_scale_f32 v219, vcc, 1.0, v195, 1.0
	v_mul_f32_e32 v227, v219, v211
	v_fma_f32 v187, -v203, v227, v219
	v_fmac_f32_e32 v227, v187, v211
	v_fma_f32 v219, -v203, v227, v219
	v_div_fmas_f32 v219, v219, v211, v227
	v_div_fixup_f32 v187, v219, v195, 1.0
	v_div_scale_f32 v220, vcc, 1.0, v196, 1.0
	v_mul_f32_e32 v228, v220, v212
	v_fma_f32 v188, -v204, v228, v220
	v_fmac_f32_e32 v228, v188, v212
	v_fma_f32 v220, -v204, v228, v220
	v_div_fmas_f32 v220, v220, v212, v228
	v_div_fixup_f32 v188, v220, v196, 1.0
	v_div_scale_f32 v221, vcc, 1.0, v197, 1.0
	v_mul_f32_e32 v229, v221, v213
	v_fma_f32 v189, -v205, v229, v221
	v_fmac_f32_e32 v229, v189, v213
	v_fma_f32 v221, -v205, v229, v221
	v_div_fmas_f32 v221, v221, v213, v229
	v_div_fixup_f32 v189, v221, v197, 1.0
	v_div_scale_f32 v222, vcc, 1.0, v198, 1.0
	v_mul_f32_e32 v230, v222, v214
	v_fma_f32 v190, -v206, v230, v222
	v_fmac_f32_e32 v230, v190, v214
	v_fma_f32 v222, -v206, v230, v222
	v_div_fmas_f32 v222, v222, v214, v230
	v_div_fixup_f32 v190, v222, v198, 1.0
	v_div_scale_f32 v223, vcc, 1.0, v199, 1.0
	v_mul_f32_e32 v231, v223, v215
	v_fma_f32 v191, -v207, v231, v223
	v_fmac_f32_e32 v231, v191, v215
	v_fma_f32 v223, -v207, v231, v223
	v_div_fmas_f32 v223, v223, v215, v231
	v_div_fixup_f32 v191, v223, v199, 1.0
	v_lshlrev_b32_e32 v192, 16, v156
	v_and_b32_e32 v193, 0xffff0000, v156
	v_lshlrev_b32_e32 v200, 16, v176
	v_and_b32_e32 v201, 0xffff0000, v176
	v_lshlrev_b32_e32 v194, 16, v157
	v_and_b32_e32 v195, 0xffff0000, v157
	v_lshlrev_b32_e32 v202, 16, v177
	v_and_b32_e32 v203, 0xffff0000, v177
	v_lshlrev_b32_e32 v196, 16, v158
	v_and_b32_e32 v197, 0xffff0000, v158
	v_lshlrev_b32_e32 v204, 16, v178
	v_and_b32_e32 v205, 0xffff0000, v178
	v_lshlrev_b32_e32 v198, 16, v159
	v_and_b32_e32 v199, 0xffff0000, v159
	v_lshlrev_b32_e32 v206, 16, v179
	v_and_b32_e32 v207, 0xffff0000, v179
	v_fma_f32 v184, v184, v200, v192
	v_fma_f32 v185, v185, v201, v193
	v_fma_f32 v186, v186, v202, v194
	v_fma_f32 v187, v187, v203, v195
	v_fma_f32 v188, v188, v204, v196
	v_fma_f32 v189, v189, v205, v197
	v_fma_f32 v190, v190, v206, v198
	v_fma_f32 v191, v191, v207, v199
	v_and_b32_sdwa v208, v184, v242 dst_sel:DWORD dst_unused:UNUSED_PAD src0_sel:WORD_1 src1_sel:DWORD
	v_and_b32_sdwa v209, v185, v242 dst_sel:DWORD dst_unused:UNUSED_PAD src0_sel:WORD_1 src1_sel:DWORD
	v_and_b32_sdwa v210, v186, v242 dst_sel:DWORD dst_unused:UNUSED_PAD src0_sel:WORD_1 src1_sel:DWORD
	v_and_b32_sdwa v211, v187, v242 dst_sel:DWORD dst_unused:UNUSED_PAD src0_sel:WORD_1 src1_sel:DWORD
	v_and_b32_sdwa v212, v188, v242 dst_sel:DWORD dst_unused:UNUSED_PAD src0_sel:WORD_1 src1_sel:DWORD
	v_and_b32_sdwa v213, v189, v242 dst_sel:DWORD dst_unused:UNUSED_PAD src0_sel:WORD_1 src1_sel:DWORD
	v_and_b32_sdwa v214, v190, v242 dst_sel:DWORD dst_unused:UNUSED_PAD src0_sel:WORD_1 src1_sel:DWORD
	v_and_b32_sdwa v215, v191, v242 dst_sel:DWORD dst_unused:UNUSED_PAD src0_sel:WORD_1 src1_sel:DWORD
	v_add3_u32 v184, v184, v208, s3
	v_add3_u32 v185, v185, v209, s3
	v_add3_u32 v186, v186, v210, s3
	v_add3_u32 v187, v187, v211, s3
	v_add3_u32 v188, v188, v212, s3
	v_add3_u32 v189, v189, v213, s3
	v_add3_u32 v190, v190, v214, s3
	v_add3_u32 v191, v191, v215, s3
	v_and_b32_e32 v185, 0xffff0000, v185
	v_and_b32_e32 v187, 0xffff0000, v187
	v_and_b32_e32 v189, 0xffff0000, v189
	v_and_b32_e32 v191, 0xffff0000, v191
	v_or_b32_sdwa v216, v185, v184 dst_sel:DWORD dst_unused:UNUSED_PAD src0_sel:DWORD src1_sel:WORD_1
	v_or_b32_sdwa v217, v187, v186 dst_sel:DWORD dst_unused:UNUSED_PAD src0_sel:DWORD src1_sel:WORD_1
	v_or_b32_sdwa v218, v189, v188 dst_sel:DWORD dst_unused:UNUSED_PAD src0_sel:DWORD src1_sel:WORD_1
	v_or_b32_sdwa v219, v191, v190 dst_sel:DWORD dst_unused:UNUSED_PAD src0_sel:DWORD src1_sel:WORD_1
	s_nop 1
	v_permlane16_swap_b32_e32 v216, v218
	v_permlane16_swap_b32_e32 v217, v219
	global_store_dwordx4 v246, v[216:219], s[26:27]
	s_waitcnt vmcnt(3)
	v_add_f32_e32 v184, v24, v136
	v_add_f32_e32 v185, v25, v137
	v_add_f32_e32 v186, v26, v138
	v_add_f32_e32 v187, v27, v139
	v_add_f32_e32 v188, v28, v140
	v_add_f32_e32 v189, v29, v141
	v_add_f32_e32 v190, v30, v142
	v_add_f32_e32 v191, v31, v143
	v_mul_f32_e32 v184, 0xbfb8aa3b, v184
	v_mul_f32_e32 v185, 0xbfb8aa3b, v185
	v_mul_f32_e32 v186, 0xbfb8aa3b, v186
	v_mul_f32_e32 v187, 0xbfb8aa3b, v187
	v_mul_f32_e32 v188, 0xbfb8aa3b, v188
	v_mul_f32_e32 v189, 0xbfb8aa3b, v189
	v_mul_f32_e32 v190, 0xbfb8aa3b, v190
	v_mul_f32_e32 v191, 0xbfb8aa3b, v191
	v_exp_f32_e32 v192, v184
	v_exp_f32_e32 v193, v185
	v_exp_f32_e32 v194, v186
	v_exp_f32_e32 v195, v187
	v_exp_f32_e32 v196, v188
	v_exp_f32_e32 v197, v189
	v_exp_f32_e32 v198, v190
	v_exp_f32_e32 v199, v191
	v_add_f32_e32 v192, 1.0, v192
	v_add_f32_e32 v193, 1.0, v193
	v_add_f32_e32 v194, 1.0, v194
	v_add_f32_e32 v195, 1.0, v195
	v_add_f32_e32 v196, 1.0, v196
	v_add_f32_e32 v197, 1.0, v197
	v_add_f32_e32 v198, 1.0, v198
	v_add_f32_e32 v199, 1.0, v199
	v_div_scale_f32 v200, s[76:77], v192, v192, 1.0
	v_div_scale_f32 v201, s[76:77], v193, v193, 1.0
	v_div_scale_f32 v202, s[76:77], v194, v194, 1.0
	v_div_scale_f32 v203, s[76:77], v195, v195, 1.0
	v_div_scale_f32 v204, s[76:77], v196, v196, 1.0
	v_div_scale_f32 v205, s[76:77], v197, v197, 1.0
	v_div_scale_f32 v206, s[76:77], v198, v198, 1.0
	v_div_scale_f32 v207, s[76:77], v199, v199, 1.0
	v_rcp_f32_e32 v208, v200
	v_rcp_f32_e32 v209, v201
	v_rcp_f32_e32 v210, v202
	v_rcp_f32_e32 v211, v203
	v_rcp_f32_e32 v212, v204
	v_rcp_f32_e32 v213, v205
	v_rcp_f32_e32 v214, v206
	v_rcp_f32_e32 v215, v207
	v_fma_f32 v184, -v200, v208, 1.0
	v_fma_f32 v185, -v201, v209, 1.0
	v_fma_f32 v186, -v202, v210, 1.0
	v_fma_f32 v187, -v203, v211, 1.0
	v_fma_f32 v188, -v204, v212, 1.0
	v_fma_f32 v189, -v205, v213, 1.0
	v_fma_f32 v190, -v206, v214, 1.0
	v_fma_f32 v191, -v207, v215, 1.0
	v_fmac_f32_e32 v208, v184, v208
	v_fmac_f32_e32 v209, v185, v209
	v_fmac_f32_e32 v210, v186, v210
	v_fmac_f32_e32 v211, v187, v211
	v_fmac_f32_e32 v212, v188, v212
	v_fmac_f32_e32 v213, v189, v213
	v_fmac_f32_e32 v214, v190, v214
	v_fmac_f32_e32 v215, v191, v215
	v_div_scale_f32 v216, vcc, 1.0, v192, 1.0
	v_mul_f32_e32 v224, v216, v208
	v_fma_f32 v184, -v200, v224, v216
	v_fmac_f32_e32 v224, v184, v208
	v_fma_f32 v216, -v200, v224, v216
	v_div_fmas_f32 v216, v216, v208, v224
	v_div_fixup_f32 v184, v216, v192, 1.0
	v_div_scale_f32 v217, vcc, 1.0, v193, 1.0
	v_mul_f32_e32 v225, v217, v209
	v_fma_f32 v185, -v201, v225, v217
	v_fmac_f32_e32 v225, v185, v209
	v_fma_f32 v217, -v201, v225, v217
	v_div_fmas_f32 v217, v217, v209, v225
	v_div_fixup_f32 v185, v217, v193, 1.0
	v_div_scale_f32 v218, vcc, 1.0, v194, 1.0
	v_mul_f32_e32 v226, v218, v210
	v_fma_f32 v186, -v202, v226, v218
	v_fmac_f32_e32 v226, v186, v210
	v_fma_f32 v218, -v202, v226, v218
	v_div_fmas_f32 v218, v218, v210, v226
	v_div_fixup_f32 v186, v218, v194, 1.0
	v_div_scale_f32 v219, vcc, 1.0, v195, 1.0
	v_mul_f32_e32 v227, v219, v211
	v_fma_f32 v187, -v203, v227, v219
	v_fmac_f32_e32 v227, v187, v211
	v_fma_f32 v219, -v203, v227, v219
	v_div_fmas_f32 v219, v219, v211, v227
	v_div_fixup_f32 v187, v219, v195, 1.0
	v_div_scale_f32 v220, vcc, 1.0, v196, 1.0
	v_mul_f32_e32 v228, v220, v212
	v_fma_f32 v188, -v204, v228, v220
	v_fmac_f32_e32 v228, v188, v212
	v_fma_f32 v220, -v204, v228, v220
	v_div_fmas_f32 v220, v220, v212, v228
	v_div_fixup_f32 v188, v220, v196, 1.0
	v_div_scale_f32 v221, vcc, 1.0, v197, 1.0
	v_mul_f32_e32 v229, v221, v213
	v_fma_f32 v189, -v205, v229, v221
	v_fmac_f32_e32 v229, v189, v213
	v_fma_f32 v221, -v205, v229, v221
	v_div_fmas_f32 v221, v221, v213, v229
	v_div_fixup_f32 v189, v221, v197, 1.0
	v_div_scale_f32 v222, vcc, 1.0, v198, 1.0
	v_mul_f32_e32 v230, v222, v214
	v_fma_f32 v190, -v206, v230, v222
	v_fmac_f32_e32 v230, v190, v214
	v_fma_f32 v222, -v206, v230, v222
	v_div_fmas_f32 v222, v222, v214, v230
	v_div_fixup_f32 v190, v222, v198, 1.0
	v_div_scale_f32 v223, vcc, 1.0, v199, 1.0
	v_mul_f32_e32 v231, v223, v215
	v_fma_f32 v191, -v207, v231, v223
	v_fmac_f32_e32 v231, v191, v215
	v_fma_f32 v223, -v207, v231, v223
	v_div_fmas_f32 v223, v223, v215, v231
	v_div_fixup_f32 v191, v223, v199, 1.0
	v_lshlrev_b32_e32 v192, 16, v160
	v_and_b32_e32 v193, 0xffff0000, v160
	v_lshlrev_b32_e32 v200, 16, v180
	v_and_b32_e32 v201, 0xffff0000, v180
	v_lshlrev_b32_e32 v194, 16, v161
	v_and_b32_e32 v195, 0xffff0000, v161
	v_lshlrev_b32_e32 v202, 16, v181
	v_and_b32_e32 v203, 0xffff0000, v181
	v_lshlrev_b32_e32 v196, 16, v162
	v_and_b32_e32 v197, 0xffff0000, v162
	v_lshlrev_b32_e32 v204, 16, v182
	v_and_b32_e32 v205, 0xffff0000, v182
	v_lshlrev_b32_e32 v198, 16, v163
	v_and_b32_e32 v199, 0xffff0000, v163
	v_lshlrev_b32_e32 v206, 16, v183
	v_and_b32_e32 v207, 0xffff0000, v183
	v_fma_f32 v184, v184, v200, v192
	v_fma_f32 v185, v185, v201, v193
	v_fma_f32 v186, v186, v202, v194
	v_fma_f32 v187, v187, v203, v195
	v_fma_f32 v188, v188, v204, v196
	v_fma_f32 v189, v189, v205, v197
	v_fma_f32 v190, v190, v206, v198
	v_fma_f32 v191, v191, v207, v199
	v_and_b32_sdwa v208, v184, v242 dst_sel:DWORD dst_unused:UNUSED_PAD src0_sel:WORD_1 src1_sel:DWORD
	v_and_b32_sdwa v209, v185, v242 dst_sel:DWORD dst_unused:UNUSED_PAD src0_sel:WORD_1 src1_sel:DWORD
	v_and_b32_sdwa v210, v186, v242 dst_sel:DWORD dst_unused:UNUSED_PAD src0_sel:WORD_1 src1_sel:DWORD
	v_and_b32_sdwa v211, v187, v242 dst_sel:DWORD dst_unused:UNUSED_PAD src0_sel:WORD_1 src1_sel:DWORD
	v_and_b32_sdwa v212, v188, v242 dst_sel:DWORD dst_unused:UNUSED_PAD src0_sel:WORD_1 src1_sel:DWORD
	v_and_b32_sdwa v213, v189, v242 dst_sel:DWORD dst_unused:UNUSED_PAD src0_sel:WORD_1 src1_sel:DWORD
	v_and_b32_sdwa v214, v190, v242 dst_sel:DWORD dst_unused:UNUSED_PAD src0_sel:WORD_1 src1_sel:DWORD
	v_and_b32_sdwa v215, v191, v242 dst_sel:DWORD dst_unused:UNUSED_PAD src0_sel:WORD_1 src1_sel:DWORD
	v_add3_u32 v184, v184, v208, s3
	v_add3_u32 v185, v185, v209, s3
	v_add3_u32 v186, v186, v210, s3
	v_add3_u32 v187, v187, v211, s3
	v_add3_u32 v188, v188, v212, s3
	v_add3_u32 v189, v189, v213, s3
	v_add3_u32 v190, v190, v214, s3
	v_add3_u32 v191, v191, v215, s3
	v_and_b32_e32 v185, 0xffff0000, v185
	v_and_b32_e32 v187, 0xffff0000, v187
	v_and_b32_e32 v189, 0xffff0000, v189
	v_and_b32_e32 v191, 0xffff0000, v191
	v_or_b32_sdwa v220, v185, v184 dst_sel:DWORD dst_unused:UNUSED_PAD src0_sel:DWORD src1_sel:WORD_1
	v_or_b32_sdwa v221, v187, v186 dst_sel:DWORD dst_unused:UNUSED_PAD src0_sel:DWORD src1_sel:WORD_1
	v_or_b32_sdwa v222, v189, v188 dst_sel:DWORD dst_unused:UNUSED_PAD src0_sel:DWORD src1_sel:WORD_1
	v_or_b32_sdwa v223, v191, v190 dst_sel:DWORD dst_unused:UNUSED_PAD src0_sel:DWORD src1_sel:WORD_1
	s_nop 1
	v_permlane16_swap_b32_e32 v220, v222
	v_permlane16_swap_b32_e32 v221, v223
	global_store_dwordx4 v246, v[220:223], s[26:27] offset:64
	global_load_dwordx4 v[148:151], v243, s[86:87]
	s_add_u32 s86, s86, 0x1000
	s_addc_u32 s87, s87, 0
	global_load_dwordx4 v[164:167], v243, s[88:89]
	s_add_u32 s88, s88, 0x1000
	s_addc_u32 s89, s89, 0
	global_load_dwordx4 v[152:155], v243, s[86:87]
	s_add_u32 s86, s86, 0x1000
	s_addc_u32 s87, s87, 0
	global_load_dwordx4 v[172:175], v243, s[88:89]
	s_add_u32 s88, s88, 0x1000
	s_addc_u32 s89, s89, 0
	global_load_dwordx4 v[156:159], v243, s[86:87]
	s_add_u32 s86, s86, 0x1000
	s_addc_u32 s87, s87, 0
	global_load_dwordx4 v[176:179], v243, s[88:89]
	s_add_u32 s88, s88, 0x1000
	s_addc_u32 s89, s89, 0
	global_load_dwordx4 v[160:163], v243, s[86:87]
	s_add_u32 s86, s86, 0x1000
	s_addc_u32 s87, s87, 0
	global_load_dwordx4 v[180:183], v243, s[88:89]
	s_add_u32 s88, s88, 0x1000
	s_addc_u32 s89, s89, 0
	s_waitcnt vmcnt(6)
	v_add_f32_e32 v184, v32, v128
	v_add_f32_e32 v185, v33, v129
	v_add_f32_e32 v186, v34, v130
	v_add_f32_e32 v187, v35, v131
	v_add_f32_e32 v188, v36, v132
	v_add_f32_e32 v189, v37, v133
	v_add_f32_e32 v190, v38, v134
	v_add_f32_e32 v191, v39, v135
	v_mul_f32_e32 v184, 0xbfb8aa3b, v184
	v_mul_f32_e32 v185, 0xbfb8aa3b, v185
	v_mul_f32_e32 v186, 0xbfb8aa3b, v186
	v_mul_f32_e32 v187, 0xbfb8aa3b, v187
	v_mul_f32_e32 v188, 0xbfb8aa3b, v188
	v_mul_f32_e32 v189, 0xbfb8aa3b, v189
	v_mul_f32_e32 v190, 0xbfb8aa3b, v190
	v_mul_f32_e32 v191, 0xbfb8aa3b, v191
	v_exp_f32_e32 v192, v184
	v_exp_f32_e32 v193, v185
	v_exp_f32_e32 v194, v186
	v_exp_f32_e32 v195, v187
	v_exp_f32_e32 v196, v188
	v_exp_f32_e32 v197, v189
	v_exp_f32_e32 v198, v190
	v_exp_f32_e32 v199, v191
	v_add_f32_e32 v192, 1.0, v192
	v_add_f32_e32 v193, 1.0, v193
	v_add_f32_e32 v194, 1.0, v194
	v_add_f32_e32 v195, 1.0, v195
	v_add_f32_e32 v196, 1.0, v196
	v_add_f32_e32 v197, 1.0, v197
	v_add_f32_e32 v198, 1.0, v198
	v_add_f32_e32 v199, 1.0, v199
	v_div_scale_f32 v200, s[76:77], v192, v192, 1.0
	v_div_scale_f32 v201, s[76:77], v193, v193, 1.0
	v_div_scale_f32 v202, s[76:77], v194, v194, 1.0
	v_div_scale_f32 v203, s[76:77], v195, v195, 1.0
	v_div_scale_f32 v204, s[76:77], v196, v196, 1.0
	v_div_scale_f32 v205, s[76:77], v197, v197, 1.0
	v_div_scale_f32 v206, s[76:77], v198, v198, 1.0
	v_div_scale_f32 v207, s[76:77], v199, v199, 1.0
	v_rcp_f32_e32 v208, v200
	v_rcp_f32_e32 v209, v201
	v_rcp_f32_e32 v210, v202
	v_rcp_f32_e32 v211, v203
	v_rcp_f32_e32 v212, v204
	v_rcp_f32_e32 v213, v205
	v_rcp_f32_e32 v214, v206
	v_rcp_f32_e32 v215, v207
	v_fma_f32 v184, -v200, v208, 1.0
	v_fma_f32 v185, -v201, v209, 1.0
	v_fma_f32 v186, -v202, v210, 1.0
	v_fma_f32 v187, -v203, v211, 1.0
	v_fma_f32 v188, -v204, v212, 1.0
	v_fma_f32 v189, -v205, v213, 1.0
	v_fma_f32 v190, -v206, v214, 1.0
	v_fma_f32 v191, -v207, v215, 1.0
	v_fmac_f32_e32 v208, v184, v208
	v_fmac_f32_e32 v209, v185, v209
	v_fmac_f32_e32 v210, v186, v210
	v_fmac_f32_e32 v211, v187, v211
	v_fmac_f32_e32 v212, v188, v212
	v_fmac_f32_e32 v213, v189, v213
	v_fmac_f32_e32 v214, v190, v214
	v_fmac_f32_e32 v215, v191, v215
	v_div_scale_f32 v216, vcc, 1.0, v192, 1.0
	v_mul_f32_e32 v224, v216, v208
	v_fma_f32 v184, -v200, v224, v216
	v_fmac_f32_e32 v224, v184, v208
	v_fma_f32 v216, -v200, v224, v216
	v_div_fmas_f32 v216, v216, v208, v224
	v_div_fixup_f32 v184, v216, v192, 1.0
	v_div_scale_f32 v217, vcc, 1.0, v193, 1.0
	v_mul_f32_e32 v225, v217, v209
	v_fma_f32 v185, -v201, v225, v217
	v_fmac_f32_e32 v225, v185, v209
	v_fma_f32 v217, -v201, v225, v217
	v_div_fmas_f32 v217, v217, v209, v225
	v_div_fixup_f32 v185, v217, v193, 1.0
	v_div_scale_f32 v218, vcc, 1.0, v194, 1.0
	v_mul_f32_e32 v226, v218, v210
	v_fma_f32 v186, -v202, v226, v218
	v_fmac_f32_e32 v226, v186, v210
	v_fma_f32 v218, -v202, v226, v218
	v_div_fmas_f32 v218, v218, v210, v226
	v_div_fixup_f32 v186, v218, v194, 1.0
	v_div_scale_f32 v219, vcc, 1.0, v195, 1.0
	v_mul_f32_e32 v227, v219, v211
	v_fma_f32 v187, -v203, v227, v219
	v_fmac_f32_e32 v227, v187, v211
	v_fma_f32 v219, -v203, v227, v219
	v_div_fmas_f32 v219, v219, v211, v227
	v_div_fixup_f32 v187, v219, v195, 1.0
	v_div_scale_f32 v220, vcc, 1.0, v196, 1.0
	v_mul_f32_e32 v228, v220, v212
	v_fma_f32 v188, -v204, v228, v220
	v_fmac_f32_e32 v228, v188, v212
	v_fma_f32 v220, -v204, v228, v220
	v_div_fmas_f32 v220, v220, v212, v228
	v_div_fixup_f32 v188, v220, v196, 1.0
	v_div_scale_f32 v221, vcc, 1.0, v197, 1.0
	v_mul_f32_e32 v229, v221, v213
	v_fma_f32 v189, -v205, v229, v221
	v_fmac_f32_e32 v229, v189, v213
	v_fma_f32 v221, -v205, v229, v221
	v_div_fmas_f32 v221, v221, v213, v229
	v_div_fixup_f32 v189, v221, v197, 1.0
	v_div_scale_f32 v222, vcc, 1.0, v198, 1.0
	v_mul_f32_e32 v230, v222, v214
	v_fma_f32 v190, -v206, v230, v222
	v_fmac_f32_e32 v230, v190, v214
	v_fma_f32 v222, -v206, v230, v222
	v_div_fmas_f32 v222, v222, v214, v230
	v_div_fixup_f32 v190, v222, v198, 1.0
	v_div_scale_f32 v223, vcc, 1.0, v199, 1.0
	v_mul_f32_e32 v231, v223, v215
	v_fma_f32 v191, -v207, v231, v223
	v_fmac_f32_e32 v231, v191, v215
	v_fma_f32 v223, -v207, v231, v223
	v_div_fmas_f32 v223, v223, v215, v231
	v_div_fixup_f32 v191, v223, v199, 1.0
	v_lshlrev_b32_e32 v192, 16, v148
	v_and_b32_e32 v193, 0xffff0000, v148
	v_lshlrev_b32_e32 v200, 16, v164
	v_and_b32_e32 v201, 0xffff0000, v164
	v_lshlrev_b32_e32 v194, 16, v149
	v_and_b32_e32 v195, 0xffff0000, v149
	v_lshlrev_b32_e32 v202, 16, v165
	v_and_b32_e32 v203, 0xffff0000, v165
	v_lshlrev_b32_e32 v196, 16, v150
	v_and_b32_e32 v197, 0xffff0000, v150
	v_lshlrev_b32_e32 v204, 16, v166
	v_and_b32_e32 v205, 0xffff0000, v166
	v_lshlrev_b32_e32 v198, 16, v151
	v_and_b32_e32 v199, 0xffff0000, v151
	v_lshlrev_b32_e32 v206, 16, v167
	v_and_b32_e32 v207, 0xffff0000, v167
	v_fma_f32 v184, v184, v200, v192
	v_fma_f32 v185, v185, v201, v193
	v_fma_f32 v186, v186, v202, v194
	v_fma_f32 v187, v187, v203, v195
	v_fma_f32 v188, v188, v204, v196
	v_fma_f32 v189, v189, v205, v197
	v_fma_f32 v190, v190, v206, v198
	v_fma_f32 v191, v191, v207, v199
	v_and_b32_sdwa v208, v184, v242 dst_sel:DWORD dst_unused:UNUSED_PAD src0_sel:WORD_1 src1_sel:DWORD
	v_and_b32_sdwa v209, v185, v242 dst_sel:DWORD dst_unused:UNUSED_PAD src0_sel:WORD_1 src1_sel:DWORD
	v_and_b32_sdwa v210, v186, v242 dst_sel:DWORD dst_unused:UNUSED_PAD src0_sel:WORD_1 src1_sel:DWORD
	v_and_b32_sdwa v211, v187, v242 dst_sel:DWORD dst_unused:UNUSED_PAD src0_sel:WORD_1 src1_sel:DWORD
	v_and_b32_sdwa v212, v188, v242 dst_sel:DWORD dst_unused:UNUSED_PAD src0_sel:WORD_1 src1_sel:DWORD
	v_and_b32_sdwa v213, v189, v242 dst_sel:DWORD dst_unused:UNUSED_PAD src0_sel:WORD_1 src1_sel:DWORD
	v_and_b32_sdwa v214, v190, v242 dst_sel:DWORD dst_unused:UNUSED_PAD src0_sel:WORD_1 src1_sel:DWORD
	v_and_b32_sdwa v215, v191, v242 dst_sel:DWORD dst_unused:UNUSED_PAD src0_sel:WORD_1 src1_sel:DWORD
	v_add3_u32 v184, v184, v208, s3
	v_add3_u32 v185, v185, v209, s3
	v_add3_u32 v186, v186, v210, s3
	v_add3_u32 v187, v187, v211, s3
	v_add3_u32 v188, v188, v212, s3
	v_add3_u32 v189, v189, v213, s3
	v_add3_u32 v190, v190, v214, s3
	v_add3_u32 v191, v191, v215, s3
	v_and_b32_e32 v185, 0xffff0000, v185
	v_and_b32_e32 v187, 0xffff0000, v187
	v_and_b32_e32 v189, 0xffff0000, v189
	v_and_b32_e32 v191, 0xffff0000, v191
	v_or_b32_sdwa v216, v185, v184 dst_sel:DWORD dst_unused:UNUSED_PAD src0_sel:DWORD src1_sel:WORD_1
	v_or_b32_sdwa v217, v187, v186 dst_sel:DWORD dst_unused:UNUSED_PAD src0_sel:DWORD src1_sel:WORD_1
	v_or_b32_sdwa v218, v189, v188 dst_sel:DWORD dst_unused:UNUSED_PAD src0_sel:DWORD src1_sel:WORD_1
	v_or_b32_sdwa v219, v191, v190 dst_sel:DWORD dst_unused:UNUSED_PAD src0_sel:DWORD src1_sel:WORD_1
	s_nop 1
	v_permlane16_swap_b32_e32 v216, v218
	v_permlane16_swap_b32_e32 v217, v219
	global_store_dwordx4 v247, v[216:219], s[26:27]
	s_waitcnt vmcnt(5)
	v_add_f32_e32 v184, v40, v136
	v_add_f32_e32 v185, v41, v137
	v_add_f32_e32 v186, v42, v138
	v_add_f32_e32 v187, v43, v139
	v_add_f32_e32 v188, v44, v140
	v_add_f32_e32 v189, v45, v141
	v_add_f32_e32 v190, v46, v142
	v_add_f32_e32 v191, v47, v143
	v_mul_f32_e32 v184, 0xbfb8aa3b, v184
	v_mul_f32_e32 v185, 0xbfb8aa3b, v185
	v_mul_f32_e32 v186, 0xbfb8aa3b, v186
	v_mul_f32_e32 v187, 0xbfb8aa3b, v187
	v_mul_f32_e32 v188, 0xbfb8aa3b, v188
	v_mul_f32_e32 v189, 0xbfb8aa3b, v189
	v_mul_f32_e32 v190, 0xbfb8aa3b, v190
	v_mul_f32_e32 v191, 0xbfb8aa3b, v191
	v_exp_f32_e32 v192, v184
	v_exp_f32_e32 v193, v185
	v_exp_f32_e32 v194, v186
	v_exp_f32_e32 v195, v187
	v_exp_f32_e32 v196, v188
	v_exp_f32_e32 v197, v189
	v_exp_f32_e32 v198, v190
	v_exp_f32_e32 v199, v191
	v_add_f32_e32 v192, 1.0, v192
	v_add_f32_e32 v193, 1.0, v193
	v_add_f32_e32 v194, 1.0, v194
	v_add_f32_e32 v195, 1.0, v195
	v_add_f32_e32 v196, 1.0, v196
	v_add_f32_e32 v197, 1.0, v197
	v_add_f32_e32 v198, 1.0, v198
	v_add_f32_e32 v199, 1.0, v199
	v_div_scale_f32 v200, s[76:77], v192, v192, 1.0
	v_div_scale_f32 v201, s[76:77], v193, v193, 1.0
	v_div_scale_f32 v202, s[76:77], v194, v194, 1.0
	v_div_scale_f32 v203, s[76:77], v195, v195, 1.0
	v_div_scale_f32 v204, s[76:77], v196, v196, 1.0
	v_div_scale_f32 v205, s[76:77], v197, v197, 1.0
	v_div_scale_f32 v206, s[76:77], v198, v198, 1.0
	v_div_scale_f32 v207, s[76:77], v199, v199, 1.0
	v_rcp_f32_e32 v208, v200
	v_rcp_f32_e32 v209, v201
	v_rcp_f32_e32 v210, v202
	v_rcp_f32_e32 v211, v203
	v_rcp_f32_e32 v212, v204
	v_rcp_f32_e32 v213, v205
	v_rcp_f32_e32 v214, v206
	v_rcp_f32_e32 v215, v207
	v_fma_f32 v184, -v200, v208, 1.0
	v_fma_f32 v185, -v201, v209, 1.0
	v_fma_f32 v186, -v202, v210, 1.0
	v_fma_f32 v187, -v203, v211, 1.0
	v_fma_f32 v188, -v204, v212, 1.0
	v_fma_f32 v189, -v205, v213, 1.0
	v_fma_f32 v190, -v206, v214, 1.0
	v_fma_f32 v191, -v207, v215, 1.0
	v_fmac_f32_e32 v208, v184, v208
	v_fmac_f32_e32 v209, v185, v209
	v_fmac_f32_e32 v210, v186, v210
	v_fmac_f32_e32 v211, v187, v211
	v_fmac_f32_e32 v212, v188, v212
	v_fmac_f32_e32 v213, v189, v213
	v_fmac_f32_e32 v214, v190, v214
	v_fmac_f32_e32 v215, v191, v215
	v_div_scale_f32 v216, vcc, 1.0, v192, 1.0
	v_mul_f32_e32 v224, v216, v208
	v_fma_f32 v184, -v200, v224, v216
	v_fmac_f32_e32 v224, v184, v208
	v_fma_f32 v216, -v200, v224, v216
	v_div_fmas_f32 v216, v216, v208, v224
	v_div_fixup_f32 v184, v216, v192, 1.0
	v_div_scale_f32 v217, vcc, 1.0, v193, 1.0
	v_mul_f32_e32 v225, v217, v209
	v_fma_f32 v185, -v201, v225, v217
	v_fmac_f32_e32 v225, v185, v209
	v_fma_f32 v217, -v201, v225, v217
	v_div_fmas_f32 v217, v217, v209, v225
	v_div_fixup_f32 v185, v217, v193, 1.0
	v_div_scale_f32 v218, vcc, 1.0, v194, 1.0
	v_mul_f32_e32 v226, v218, v210
	v_fma_f32 v186, -v202, v226, v218
	v_fmac_f32_e32 v226, v186, v210
	v_fma_f32 v218, -v202, v226, v218
	v_div_fmas_f32 v218, v218, v210, v226
	v_div_fixup_f32 v186, v218, v194, 1.0
	v_div_scale_f32 v219, vcc, 1.0, v195, 1.0
	v_mul_f32_e32 v227, v219, v211
	v_fma_f32 v187, -v203, v227, v219
	v_fmac_f32_e32 v227, v187, v211
	v_fma_f32 v219, -v203, v227, v219
	v_div_fmas_f32 v219, v219, v211, v227
	v_div_fixup_f32 v187, v219, v195, 1.0
	v_div_scale_f32 v220, vcc, 1.0, v196, 1.0
	v_mul_f32_e32 v228, v220, v212
	v_fma_f32 v188, -v204, v228, v220
	v_fmac_f32_e32 v228, v188, v212
	v_fma_f32 v220, -v204, v228, v220
	v_div_fmas_f32 v220, v220, v212, v228
	v_div_fixup_f32 v188, v220, v196, 1.0
	v_div_scale_f32 v221, vcc, 1.0, v197, 1.0
	v_mul_f32_e32 v229, v221, v213
	v_fma_f32 v189, -v205, v229, v221
	v_fmac_f32_e32 v229, v189, v213
	v_fma_f32 v221, -v205, v229, v221
	v_div_fmas_f32 v221, v221, v213, v229
	v_div_fixup_f32 v189, v221, v197, 1.0
	v_div_scale_f32 v222, vcc, 1.0, v198, 1.0
	v_mul_f32_e32 v230, v222, v214
	v_fma_f32 v190, -v206, v230, v222
	v_fmac_f32_e32 v230, v190, v214
	v_fma_f32 v222, -v206, v230, v222
	v_div_fmas_f32 v222, v222, v214, v230
	v_div_fixup_f32 v190, v222, v198, 1.0
	v_div_scale_f32 v223, vcc, 1.0, v199, 1.0
	v_mul_f32_e32 v231, v223, v215
	v_fma_f32 v191, -v207, v231, v223
	v_fmac_f32_e32 v231, v191, v215
	v_fma_f32 v223, -v207, v231, v223
	v_div_fmas_f32 v223, v223, v215, v231
	v_div_fixup_f32 v191, v223, v199, 1.0
	v_lshlrev_b32_e32 v192, 16, v152
	v_and_b32_e32 v193, 0xffff0000, v152
	v_lshlrev_b32_e32 v200, 16, v172
	v_and_b32_e32 v201, 0xffff0000, v172
	v_lshlrev_b32_e32 v194, 16, v153
	v_and_b32_e32 v195, 0xffff0000, v153
	v_lshlrev_b32_e32 v202, 16, v173
	v_and_b32_e32 v203, 0xffff0000, v173
	v_lshlrev_b32_e32 v196, 16, v154
	v_and_b32_e32 v197, 0xffff0000, v154
	v_lshlrev_b32_e32 v204, 16, v174
	v_and_b32_e32 v205, 0xffff0000, v174
	v_lshlrev_b32_e32 v198, 16, v155
	v_and_b32_e32 v199, 0xffff0000, v155
	v_lshlrev_b32_e32 v206, 16, v175
	v_and_b32_e32 v207, 0xffff0000, v175
	v_fma_f32 v184, v184, v200, v192
	v_fma_f32 v185, v185, v201, v193
	v_fma_f32 v186, v186, v202, v194
	v_fma_f32 v187, v187, v203, v195
	v_fma_f32 v188, v188, v204, v196
	v_fma_f32 v189, v189, v205, v197
	v_fma_f32 v190, v190, v206, v198
	v_fma_f32 v191, v191, v207, v199
	v_and_b32_sdwa v208, v184, v242 dst_sel:DWORD dst_unused:UNUSED_PAD src0_sel:WORD_1 src1_sel:DWORD
	v_and_b32_sdwa v209, v185, v242 dst_sel:DWORD dst_unused:UNUSED_PAD src0_sel:WORD_1 src1_sel:DWORD
	v_and_b32_sdwa v210, v186, v242 dst_sel:DWORD dst_unused:UNUSED_PAD src0_sel:WORD_1 src1_sel:DWORD
	v_and_b32_sdwa v211, v187, v242 dst_sel:DWORD dst_unused:UNUSED_PAD src0_sel:WORD_1 src1_sel:DWORD
	v_and_b32_sdwa v212, v188, v242 dst_sel:DWORD dst_unused:UNUSED_PAD src0_sel:WORD_1 src1_sel:DWORD
	v_and_b32_sdwa v213, v189, v242 dst_sel:DWORD dst_unused:UNUSED_PAD src0_sel:WORD_1 src1_sel:DWORD
	v_and_b32_sdwa v214, v190, v242 dst_sel:DWORD dst_unused:UNUSED_PAD src0_sel:WORD_1 src1_sel:DWORD
	v_and_b32_sdwa v215, v191, v242 dst_sel:DWORD dst_unused:UNUSED_PAD src0_sel:WORD_1 src1_sel:DWORD
	v_add3_u32 v184, v184, v208, s3
	v_add3_u32 v185, v185, v209, s3
	v_add3_u32 v186, v186, v210, s3
	v_add3_u32 v187, v187, v211, s3
	v_add3_u32 v188, v188, v212, s3
	v_add3_u32 v189, v189, v213, s3
	v_add3_u32 v190, v190, v214, s3
	v_add3_u32 v191, v191, v215, s3
	v_and_b32_e32 v185, 0xffff0000, v185
	v_and_b32_e32 v187, 0xffff0000, v187
	v_and_b32_e32 v189, 0xffff0000, v189
	v_and_b32_e32 v191, 0xffff0000, v191
	v_or_b32_sdwa v220, v185, v184 dst_sel:DWORD dst_unused:UNUSED_PAD src0_sel:DWORD src1_sel:WORD_1
	v_or_b32_sdwa v221, v187, v186 dst_sel:DWORD dst_unused:UNUSED_PAD src0_sel:DWORD src1_sel:WORD_1
	v_or_b32_sdwa v222, v189, v188 dst_sel:DWORD dst_unused:UNUSED_PAD src0_sel:DWORD src1_sel:WORD_1
	v_or_b32_sdwa v223, v191, v190 dst_sel:DWORD dst_unused:UNUSED_PAD src0_sel:DWORD src1_sel:WORD_1
	s_nop 1
	v_permlane16_swap_b32_e32 v220, v222
	v_permlane16_swap_b32_e32 v221, v223
	global_store_dwordx4 v247, v[220:223], s[26:27] offset:64
	s_waitcnt vmcnt(4)
	v_add_f32_e32 v184, v48, v128
	v_add_f32_e32 v185, v49, v129
	v_add_f32_e32 v186, v50, v130
	v_add_f32_e32 v187, v51, v131
	v_add_f32_e32 v188, v52, v132
	v_add_f32_e32 v189, v53, v133
	v_add_f32_e32 v190, v54, v134
	v_add_f32_e32 v191, v55, v135
	v_mul_f32_e32 v184, 0xbfb8aa3b, v184
	v_mul_f32_e32 v185, 0xbfb8aa3b, v185
	v_mul_f32_e32 v186, 0xbfb8aa3b, v186
	v_mul_f32_e32 v187, 0xbfb8aa3b, v187
	v_mul_f32_e32 v188, 0xbfb8aa3b, v188
	v_mul_f32_e32 v189, 0xbfb8aa3b, v189
	v_mul_f32_e32 v190, 0xbfb8aa3b, v190
	v_mul_f32_e32 v191, 0xbfb8aa3b, v191
	v_exp_f32_e32 v192, v184
	v_exp_f32_e32 v193, v185
	v_exp_f32_e32 v194, v186
	v_exp_f32_e32 v195, v187
	v_exp_f32_e32 v196, v188
	v_exp_f32_e32 v197, v189
	v_exp_f32_e32 v198, v190
	v_exp_f32_e32 v199, v191
	v_add_f32_e32 v192, 1.0, v192
	v_add_f32_e32 v193, 1.0, v193
	v_add_f32_e32 v194, 1.0, v194
	v_add_f32_e32 v195, 1.0, v195
	v_add_f32_e32 v196, 1.0, v196
	v_add_f32_e32 v197, 1.0, v197
	v_add_f32_e32 v198, 1.0, v198
	v_add_f32_e32 v199, 1.0, v199
	v_div_scale_f32 v200, s[76:77], v192, v192, 1.0
	v_div_scale_f32 v201, s[76:77], v193, v193, 1.0
	v_div_scale_f32 v202, s[76:77], v194, v194, 1.0
	v_div_scale_f32 v203, s[76:77], v195, v195, 1.0
	v_div_scale_f32 v204, s[76:77], v196, v196, 1.0
	v_div_scale_f32 v205, s[76:77], v197, v197, 1.0
	v_div_scale_f32 v206, s[76:77], v198, v198, 1.0
	v_div_scale_f32 v207, s[76:77], v199, v199, 1.0
	v_rcp_f32_e32 v208, v200
	v_rcp_f32_e32 v209, v201
	v_rcp_f32_e32 v210, v202
	v_rcp_f32_e32 v211, v203
	v_rcp_f32_e32 v212, v204
	v_rcp_f32_e32 v213, v205
	v_rcp_f32_e32 v214, v206
	v_rcp_f32_e32 v215, v207
	v_fma_f32 v184, -v200, v208, 1.0
	v_fma_f32 v185, -v201, v209, 1.0
	v_fma_f32 v186, -v202, v210, 1.0
	v_fma_f32 v187, -v203, v211, 1.0
	v_fma_f32 v188, -v204, v212, 1.0
	v_fma_f32 v189, -v205, v213, 1.0
	v_fma_f32 v190, -v206, v214, 1.0
	v_fma_f32 v191, -v207, v215, 1.0
	v_fmac_f32_e32 v208, v184, v208
	v_fmac_f32_e32 v209, v185, v209
	v_fmac_f32_e32 v210, v186, v210
	v_fmac_f32_e32 v211, v187, v211
	v_fmac_f32_e32 v212, v188, v212
	v_fmac_f32_e32 v213, v189, v213
	v_fmac_f32_e32 v214, v190, v214
	v_fmac_f32_e32 v215, v191, v215
	v_div_scale_f32 v216, vcc, 1.0, v192, 1.0
	v_mul_f32_e32 v224, v216, v208
	v_fma_f32 v184, -v200, v224, v216
	v_fmac_f32_e32 v224, v184, v208
	v_fma_f32 v216, -v200, v224, v216
	v_div_fmas_f32 v216, v216, v208, v224
	v_div_fixup_f32 v184, v216, v192, 1.0
	v_div_scale_f32 v217, vcc, 1.0, v193, 1.0
	v_mul_f32_e32 v225, v217, v209
	v_fma_f32 v185, -v201, v225, v217
	v_fmac_f32_e32 v225, v185, v209
	v_fma_f32 v217, -v201, v225, v217
	v_div_fmas_f32 v217, v217, v209, v225
	v_div_fixup_f32 v185, v217, v193, 1.0
	v_div_scale_f32 v218, vcc, 1.0, v194, 1.0
	v_mul_f32_e32 v226, v218, v210
	v_fma_f32 v186, -v202, v226, v218
	v_fmac_f32_e32 v226, v186, v210
	v_fma_f32 v218, -v202, v226, v218
	v_div_fmas_f32 v218, v218, v210, v226
	v_div_fixup_f32 v186, v218, v194, 1.0
	v_div_scale_f32 v219, vcc, 1.0, v195, 1.0
	v_mul_f32_e32 v227, v219, v211
	v_fma_f32 v187, -v203, v227, v219
	v_fmac_f32_e32 v227, v187, v211
	v_fma_f32 v219, -v203, v227, v219
	v_div_fmas_f32 v219, v219, v211, v227
	v_div_fixup_f32 v187, v219, v195, 1.0
	v_div_scale_f32 v220, vcc, 1.0, v196, 1.0
	v_mul_f32_e32 v228, v220, v212
	v_fma_f32 v188, -v204, v228, v220
	v_fmac_f32_e32 v228, v188, v212
	v_fma_f32 v220, -v204, v228, v220
	v_div_fmas_f32 v220, v220, v212, v228
	v_div_fixup_f32 v188, v220, v196, 1.0
	v_div_scale_f32 v221, vcc, 1.0, v197, 1.0
	v_mul_f32_e32 v229, v221, v213
	v_fma_f32 v189, -v205, v229, v221
	v_fmac_f32_e32 v229, v189, v213
	v_fma_f32 v221, -v205, v229, v221
	v_div_fmas_f32 v221, v221, v213, v229
	v_div_fixup_f32 v189, v221, v197, 1.0
	v_div_scale_f32 v222, vcc, 1.0, v198, 1.0
	v_mul_f32_e32 v230, v222, v214
	v_fma_f32 v190, -v206, v230, v222
	v_fmac_f32_e32 v230, v190, v214
	v_fma_f32 v222, -v206, v230, v222
	v_div_fmas_f32 v222, v222, v214, v230
	v_div_fixup_f32 v190, v222, v198, 1.0
	v_div_scale_f32 v223, vcc, 1.0, v199, 1.0
	v_mul_f32_e32 v231, v223, v215
	v_fma_f32 v191, -v207, v231, v223
	v_fmac_f32_e32 v231, v191, v215
	v_fma_f32 v223, -v207, v231, v223
	v_div_fmas_f32 v223, v223, v215, v231
	v_div_fixup_f32 v191, v223, v199, 1.0
	v_lshlrev_b32_e32 v192, 16, v156
	v_and_b32_e32 v193, 0xffff0000, v156
	v_lshlrev_b32_e32 v200, 16, v176
	v_and_b32_e32 v201, 0xffff0000, v176
	v_lshlrev_b32_e32 v194, 16, v157
	v_and_b32_e32 v195, 0xffff0000, v157
	v_lshlrev_b32_e32 v202, 16, v177
	v_and_b32_e32 v203, 0xffff0000, v177
	v_lshlrev_b32_e32 v196, 16, v158
	v_and_b32_e32 v197, 0xffff0000, v158
	v_lshlrev_b32_e32 v204, 16, v178
	v_and_b32_e32 v205, 0xffff0000, v178
	v_lshlrev_b32_e32 v198, 16, v159
	v_and_b32_e32 v199, 0xffff0000, v159
	v_lshlrev_b32_e32 v206, 16, v179
	v_and_b32_e32 v207, 0xffff0000, v179
	v_fma_f32 v184, v184, v200, v192
	v_fma_f32 v185, v185, v201, v193
	v_fma_f32 v186, v186, v202, v194
	v_fma_f32 v187, v187, v203, v195
	v_fma_f32 v188, v188, v204, v196
	v_fma_f32 v189, v189, v205, v197
	v_fma_f32 v190, v190, v206, v198
	v_fma_f32 v191, v191, v207, v199
	v_and_b32_sdwa v208, v184, v242 dst_sel:DWORD dst_unused:UNUSED_PAD src0_sel:WORD_1 src1_sel:DWORD
	v_and_b32_sdwa v209, v185, v242 dst_sel:DWORD dst_unused:UNUSED_PAD src0_sel:WORD_1 src1_sel:DWORD
	v_and_b32_sdwa v210, v186, v242 dst_sel:DWORD dst_unused:UNUSED_PAD src0_sel:WORD_1 src1_sel:DWORD
	v_and_b32_sdwa v211, v187, v242 dst_sel:DWORD dst_unused:UNUSED_PAD src0_sel:WORD_1 src1_sel:DWORD
	v_and_b32_sdwa v212, v188, v242 dst_sel:DWORD dst_unused:UNUSED_PAD src0_sel:WORD_1 src1_sel:DWORD
	v_and_b32_sdwa v213, v189, v242 dst_sel:DWORD dst_unused:UNUSED_PAD src0_sel:WORD_1 src1_sel:DWORD
	v_and_b32_sdwa v214, v190, v242 dst_sel:DWORD dst_unused:UNUSED_PAD src0_sel:WORD_1 src1_sel:DWORD
	v_and_b32_sdwa v215, v191, v242 dst_sel:DWORD dst_unused:UNUSED_PAD src0_sel:WORD_1 src1_sel:DWORD
	v_add3_u32 v184, v184, v208, s3
	v_add3_u32 v185, v185, v209, s3
	v_add3_u32 v186, v186, v210, s3
	v_add3_u32 v187, v187, v211, s3
	v_add3_u32 v188, v188, v212, s3
	v_add3_u32 v189, v189, v213, s3
	v_add3_u32 v190, v190, v214, s3
	v_add3_u32 v191, v191, v215, s3
	v_and_b32_e32 v185, 0xffff0000, v185
	v_and_b32_e32 v187, 0xffff0000, v187
	v_and_b32_e32 v189, 0xffff0000, v189
	v_and_b32_e32 v191, 0xffff0000, v191
	v_or_b32_sdwa v216, v185, v184 dst_sel:DWORD dst_unused:UNUSED_PAD src0_sel:DWORD src1_sel:WORD_1
	v_or_b32_sdwa v217, v187, v186 dst_sel:DWORD dst_unused:UNUSED_PAD src0_sel:DWORD src1_sel:WORD_1
	v_or_b32_sdwa v218, v189, v188 dst_sel:DWORD dst_unused:UNUSED_PAD src0_sel:DWORD src1_sel:WORD_1
	v_or_b32_sdwa v219, v191, v190 dst_sel:DWORD dst_unused:UNUSED_PAD src0_sel:DWORD src1_sel:WORD_1
	s_nop 1
	v_permlane16_swap_b32_e32 v216, v218
	v_permlane16_swap_b32_e32 v217, v219
	global_store_dwordx4 v248, v[216:219], s[26:27]
	s_waitcnt vmcnt(3)
	v_add_f32_e32 v184, v56, v136
	v_add_f32_e32 v185, v57, v137
	v_add_f32_e32 v186, v58, v138
	v_add_f32_e32 v187, v59, v139
	v_add_f32_e32 v188, v60, v140
	v_add_f32_e32 v189, v61, v141
	v_add_f32_e32 v190, v62, v142
	v_add_f32_e32 v191, v63, v143
	v_mul_f32_e32 v184, 0xbfb8aa3b, v184
	v_mul_f32_e32 v185, 0xbfb8aa3b, v185
	v_mul_f32_e32 v186, 0xbfb8aa3b, v186
	v_mul_f32_e32 v187, 0xbfb8aa3b, v187
	v_mul_f32_e32 v188, 0xbfb8aa3b, v188
	v_mul_f32_e32 v189, 0xbfb8aa3b, v189
	v_mul_f32_e32 v190, 0xbfb8aa3b, v190
	v_mul_f32_e32 v191, 0xbfb8aa3b, v191
	v_exp_f32_e32 v192, v184
	v_exp_f32_e32 v193, v185
	v_exp_f32_e32 v194, v186
	v_exp_f32_e32 v195, v187
	v_exp_f32_e32 v196, v188
	v_exp_f32_e32 v197, v189
	v_exp_f32_e32 v198, v190
	v_exp_f32_e32 v199, v191
	v_add_f32_e32 v192, 1.0, v192
	v_add_f32_e32 v193, 1.0, v193
	v_add_f32_e32 v194, 1.0, v194
	v_add_f32_e32 v195, 1.0, v195
	v_add_f32_e32 v196, 1.0, v196
	v_add_f32_e32 v197, 1.0, v197
	v_add_f32_e32 v198, 1.0, v198
	v_add_f32_e32 v199, 1.0, v199
	v_div_scale_f32 v200, s[76:77], v192, v192, 1.0
	v_div_scale_f32 v201, s[76:77], v193, v193, 1.0
	v_div_scale_f32 v202, s[76:77], v194, v194, 1.0
	v_div_scale_f32 v203, s[76:77], v195, v195, 1.0
	v_div_scale_f32 v204, s[76:77], v196, v196, 1.0
	v_div_scale_f32 v205, s[76:77], v197, v197, 1.0
	v_div_scale_f32 v206, s[76:77], v198, v198, 1.0
	v_div_scale_f32 v207, s[76:77], v199, v199, 1.0
	v_rcp_f32_e32 v208, v200
	v_rcp_f32_e32 v209, v201
	v_rcp_f32_e32 v210, v202
	v_rcp_f32_e32 v211, v203
	v_rcp_f32_e32 v212, v204
	v_rcp_f32_e32 v213, v205
	v_rcp_f32_e32 v214, v206
	v_rcp_f32_e32 v215, v207
	v_fma_f32 v184, -v200, v208, 1.0
	v_fma_f32 v185, -v201, v209, 1.0
	v_fma_f32 v186, -v202, v210, 1.0
	v_fma_f32 v187, -v203, v211, 1.0
	v_fma_f32 v188, -v204, v212, 1.0
	v_fma_f32 v189, -v205, v213, 1.0
	v_fma_f32 v190, -v206, v214, 1.0
	v_fma_f32 v191, -v207, v215, 1.0
	v_fmac_f32_e32 v208, v184, v208
	v_fmac_f32_e32 v209, v185, v209
	v_fmac_f32_e32 v210, v186, v210
	v_fmac_f32_e32 v211, v187, v211
	v_fmac_f32_e32 v212, v188, v212
	v_fmac_f32_e32 v213, v189, v213
	v_fmac_f32_e32 v214, v190, v214
	v_fmac_f32_e32 v215, v191, v215
	v_div_scale_f32 v216, vcc, 1.0, v192, 1.0
	v_mul_f32_e32 v224, v216, v208
	v_fma_f32 v184, -v200, v224, v216
	v_fmac_f32_e32 v224, v184, v208
	v_fma_f32 v216, -v200, v224, v216
	v_div_fmas_f32 v216, v216, v208, v224
	v_div_fixup_f32 v184, v216, v192, 1.0
	v_div_scale_f32 v217, vcc, 1.0, v193, 1.0
	v_mul_f32_e32 v225, v217, v209
	v_fma_f32 v185, -v201, v225, v217
	v_fmac_f32_e32 v225, v185, v209
	v_fma_f32 v217, -v201, v225, v217
	v_div_fmas_f32 v217, v217, v209, v225
	v_div_fixup_f32 v185, v217, v193, 1.0
	v_div_scale_f32 v218, vcc, 1.0, v194, 1.0
	v_mul_f32_e32 v226, v218, v210
	v_fma_f32 v186, -v202, v226, v218
	v_fmac_f32_e32 v226, v186, v210
	v_fma_f32 v218, -v202, v226, v218
	v_div_fmas_f32 v218, v218, v210, v226
	v_div_fixup_f32 v186, v218, v194, 1.0
	v_div_scale_f32 v219, vcc, 1.0, v195, 1.0
	v_mul_f32_e32 v227, v219, v211
	v_fma_f32 v187, -v203, v227, v219
	v_fmac_f32_e32 v227, v187, v211
	v_fma_f32 v219, -v203, v227, v219
	v_div_fmas_f32 v219, v219, v211, v227
	v_div_fixup_f32 v187, v219, v195, 1.0
	v_div_scale_f32 v220, vcc, 1.0, v196, 1.0
	v_mul_f32_e32 v228, v220, v212
	v_fma_f32 v188, -v204, v228, v220
	v_fmac_f32_e32 v228, v188, v212
	v_fma_f32 v220, -v204, v228, v220
	v_div_fmas_f32 v220, v220, v212, v228
	v_div_fixup_f32 v188, v220, v196, 1.0
	v_div_scale_f32 v221, vcc, 1.0, v197, 1.0
	v_mul_f32_e32 v229, v221, v213
	v_fma_f32 v189, -v205, v229, v221
	v_fmac_f32_e32 v229, v189, v213
	v_fma_f32 v221, -v205, v229, v221
	v_div_fmas_f32 v221, v221, v213, v229
	v_div_fixup_f32 v189, v221, v197, 1.0
	v_div_scale_f32 v222, vcc, 1.0, v198, 1.0
	v_mul_f32_e32 v230, v222, v214
	v_fma_f32 v190, -v206, v230, v222
	v_fmac_f32_e32 v230, v190, v214
	v_fma_f32 v222, -v206, v230, v222
	v_div_fmas_f32 v222, v222, v214, v230
	v_div_fixup_f32 v190, v222, v198, 1.0
	v_div_scale_f32 v223, vcc, 1.0, v199, 1.0
	v_mul_f32_e32 v231, v223, v215
	v_fma_f32 v191, -v207, v231, v223
	v_fmac_f32_e32 v231, v191, v215
	v_fma_f32 v223, -v207, v231, v223
	v_div_fmas_f32 v223, v223, v215, v231
	v_div_fixup_f32 v191, v223, v199, 1.0
	v_lshlrev_b32_e32 v192, 16, v160
	v_and_b32_e32 v193, 0xffff0000, v160
	v_lshlrev_b32_e32 v200, 16, v180
	v_and_b32_e32 v201, 0xffff0000, v180
	v_lshlrev_b32_e32 v194, 16, v161
	v_and_b32_e32 v195, 0xffff0000, v161
	v_lshlrev_b32_e32 v202, 16, v181
	v_and_b32_e32 v203, 0xffff0000, v181
	v_lshlrev_b32_e32 v196, 16, v162
	v_and_b32_e32 v197, 0xffff0000, v162
	v_lshlrev_b32_e32 v204, 16, v182
	v_and_b32_e32 v205, 0xffff0000, v182
	v_lshlrev_b32_e32 v198, 16, v163
	v_and_b32_e32 v199, 0xffff0000, v163
	v_lshlrev_b32_e32 v206, 16, v183
	v_and_b32_e32 v207, 0xffff0000, v183
	v_fma_f32 v184, v184, v200, v192
	v_fma_f32 v185, v185, v201, v193
	v_fma_f32 v186, v186, v202, v194
	v_fma_f32 v187, v187, v203, v195
	v_fma_f32 v188, v188, v204, v196
	v_fma_f32 v189, v189, v205, v197
	v_fma_f32 v190, v190, v206, v198
	v_fma_f32 v191, v191, v207, v199
	v_and_b32_sdwa v208, v184, v242 dst_sel:DWORD dst_unused:UNUSED_PAD src0_sel:WORD_1 src1_sel:DWORD
	v_and_b32_sdwa v209, v185, v242 dst_sel:DWORD dst_unused:UNUSED_PAD src0_sel:WORD_1 src1_sel:DWORD
	v_and_b32_sdwa v210, v186, v242 dst_sel:DWORD dst_unused:UNUSED_PAD src0_sel:WORD_1 src1_sel:DWORD
	v_and_b32_sdwa v211, v187, v242 dst_sel:DWORD dst_unused:UNUSED_PAD src0_sel:WORD_1 src1_sel:DWORD
	v_and_b32_sdwa v212, v188, v242 dst_sel:DWORD dst_unused:UNUSED_PAD src0_sel:WORD_1 src1_sel:DWORD
	v_and_b32_sdwa v213, v189, v242 dst_sel:DWORD dst_unused:UNUSED_PAD src0_sel:WORD_1 src1_sel:DWORD
	v_and_b32_sdwa v214, v190, v242 dst_sel:DWORD dst_unused:UNUSED_PAD src0_sel:WORD_1 src1_sel:DWORD
	v_and_b32_sdwa v215, v191, v242 dst_sel:DWORD dst_unused:UNUSED_PAD src0_sel:WORD_1 src1_sel:DWORD
	v_add3_u32 v184, v184, v208, s3
	v_add3_u32 v185, v185, v209, s3
	v_add3_u32 v186, v186, v210, s3
	v_add3_u32 v187, v187, v211, s3
	v_add3_u32 v188, v188, v212, s3
	v_add3_u32 v189, v189, v213, s3
	v_add3_u32 v190, v190, v214, s3
	v_add3_u32 v191, v191, v215, s3
	v_and_b32_e32 v185, 0xffff0000, v185
	v_and_b32_e32 v187, 0xffff0000, v187
	v_and_b32_e32 v189, 0xffff0000, v189
	v_and_b32_e32 v191, 0xffff0000, v191
	v_or_b32_sdwa v220, v185, v184 dst_sel:DWORD dst_unused:UNUSED_PAD src0_sel:DWORD src1_sel:WORD_1
	v_or_b32_sdwa v221, v187, v186 dst_sel:DWORD dst_unused:UNUSED_PAD src0_sel:DWORD src1_sel:WORD_1
	v_or_b32_sdwa v222, v189, v188 dst_sel:DWORD dst_unused:UNUSED_PAD src0_sel:DWORD src1_sel:WORD_1
	v_or_b32_sdwa v223, v191, v190 dst_sel:DWORD dst_unused:UNUSED_PAD src0_sel:DWORD src1_sel:WORD_1
	s_nop 1
	v_permlane16_swap_b32_e32 v220, v222
	v_permlane16_swap_b32_e32 v221, v223
	global_store_dwordx4 v248, v[220:223], s[26:27] offset:64
	s_cmp_eq_u32 s83, 1
	s_cbranch_scc1 .Lp6d_epdone
	s_cmp_eq_u32 s95, 1
	s_cbranch_scc0 .Lp6d_epdone
	v_mov_b32_e32 v0, v64
	v_mov_b32_e32 v1, v65
	v_mov_b32_e32 v2, v66
	v_mov_b32_e32 v3, v67
	v_mov_b32_e32 v4, v68
	v_mov_b32_e32 v5, v69
	v_mov_b32_e32 v6, v70
	v_mov_b32_e32 v7, v71
	v_mov_b32_e32 v8, v72
	v_mov_b32_e32 v9, v73
	v_mov_b32_e32 v10, v74
	v_mov_b32_e32 v11, v75
	v_mov_b32_e32 v12, v76
	v_mov_b32_e32 v13, v77
	v_mov_b32_e32 v14, v78
	v_mov_b32_e32 v15, v79
	v_mov_b32_e32 v16, v80
	v_mov_b32_e32 v17, v81
	v_mov_b32_e32 v18, v82
	v_mov_b32_e32 v19, v83
	v_mov_b32_e32 v20, v84
	v_mov_b32_e32 v21, v85
	v_mov_b32_e32 v22, v86
	v_mov_b32_e32 v23, v87
	v_mov_b32_e32 v24, v88
	v_mov_b32_e32 v25, v89
	v_mov_b32_e32 v26, v90
	v_mov_b32_e32 v27, v91
	v_mov_b32_e32 v28, v92
	v_mov_b32_e32 v29, v93
	v_mov_b32_e32 v30, v94
	v_mov_b32_e32 v31, v95
	v_mov_b32_e32 v32, v96
	v_mov_b32_e32 v33, v97
	v_mov_b32_e32 v34, v98
	v_mov_b32_e32 v35, v99
	v_mov_b32_e32 v36, v100
	v_mov_b32_e32 v37, v101
	v_mov_b32_e32 v38, v102
	v_mov_b32_e32 v39, v103
	v_mov_b32_e32 v40, v104
	v_mov_b32_e32 v41, v105
	v_mov_b32_e32 v42, v106
	v_mov_b32_e32 v43, v107
	v_mov_b32_e32 v44, v108
	v_mov_b32_e32 v45, v109
	v_mov_b32_e32 v46, v110
	v_mov_b32_e32 v47, v111
	v_mov_b32_e32 v48, v112
	v_mov_b32_e32 v49, v113
	v_mov_b32_e32 v50, v114
	v_mov_b32_e32 v51, v115
	v_mov_b32_e32 v52, v116
	v_mov_b32_e32 v53, v117
	v_mov_b32_e32 v54, v118
	v_mov_b32_e32 v55, v119
	v_mov_b32_e32 v56, v120
	v_mov_b32_e32 v57, v121
	v_mov_b32_e32 v58, v122
	v_mov_b32_e32 v59, v123
	v_mov_b32_e32 v60, v124
	v_mov_b32_e32 v61, v125
	v_mov_b32_e32 v62, v126
	v_mov_b32_e32 v63, v127
	s_mov_b32 s83, 1
	s_branch .Lp6d_ep
.Lp6d_epdone:
	s_add_i32 s81, s81, s80
	s_cmp_eq_u32 s95, 1
	s_cbranch_scc0 .Lp6_nodual
	s_add_i32 s81, s81, s80
.Lp6_nodual:
	s_mov_b32 s95, 0
	s_cmp_ge_i32 s81, s82
	s_cbranch_scc0 .Lp6_visit
